# phase 0 filter: lane broadcasts of the hidden activations via v_readlane (SGPR operand) instead of ds_bpermute
# speedup vs baseline: 1.0097x; 1.0097x over previous
.LBB0_72:
	s_or_b64 exec, exec, s[52:53]
	v_lshlrev_b32_e32 v0, 2, v26
	global_load_dword v11, v0, s[50:51]
	s_mov_b32 s1, 0
	v_lshl_add_u64 v[8:9], v[2:3], 0, s[48:49]
	s_waitcnt vmcnt(0)
	v_readlane_b32 s88, v10, 0
	v_readlane_b32 s89, v10, 1
	v_readlane_b32 s90, v10, 2
	v_readlane_b32 s91, v10, 3
	v_readlane_b32 s92, v10, 4
	v_readlane_b32 s93, v10, 5
	v_readlane_b32 s94, v10, 6
	v_readlane_b32 s95, v10, 7
	v_readlane_b32 s96, v10, 8
	v_readlane_b32 s97, v10, 9
	v_readlane_b32 s98, v10, 10
	v_fmac_f32_e32 v11, s88, v104
	v_fmac_f32_e32 v11, s89, v105
	v_fmac_f32_e32 v11, s90, v106
	v_fmac_f32_e32 v11, s91, v107
	v_fmac_f32_e32 v11, s92, v108
	v_fmac_f32_e32 v11, s93, v109
	v_fmac_f32_e32 v11, s94, v110
	v_fmac_f32_e32 v11, s95, v111
	v_fmac_f32_e32 v11, s96, v112
	v_fmac_f32_e32 v11, s97, v113
	v_fmac_f32_e32 v11, s98, v114
	v_readlane_b32 s88, v10, 11
	v_readlane_b32 s89, v10, 12
	v_readlane_b32 s90, v10, 13
	v_readlane_b32 s91, v10, 14
	v_readlane_b32 s92, v10, 15
	v_readlane_b32 s93, v10, 16
	v_readlane_b32 s94, v10, 17
	v_readlane_b32 s95, v10, 18
	v_readlane_b32 s96, v10, 19
	v_readlane_b32 s97, v10, 20
	v_readlane_b32 s98, v10, 21
	v_fmac_f32_e32 v11, s88, v115
	v_fmac_f32_e32 v11, s89, v116
	v_fmac_f32_e32 v11, s90, v117
	v_fmac_f32_e32 v11, s91, v118
	v_fmac_f32_e32 v11, s92, v119
	v_fmac_f32_e32 v11, s93, v120
	v_fmac_f32_e32 v11, s94, v121
	v_fmac_f32_e32 v11, s95, v122
	v_fmac_f32_e32 v11, s96, v123
	v_fmac_f32_e32 v11, s97, v124
	v_fmac_f32_e32 v11, s98, v125
	v_readlane_b32 s88, v10, 22
	v_readlane_b32 s89, v10, 23
	v_readlane_b32 s90, v10, 24
	v_readlane_b32 s91, v10, 25
	v_readlane_b32 s92, v10, 26
	v_readlane_b32 s93, v10, 27
	v_readlane_b32 s94, v10, 28
	v_readlane_b32 s95, v10, 29
	v_readlane_b32 s96, v10, 30
	v_readlane_b32 s97, v10, 31
	v_readlane_b32 s98, v10, 32
	v_fmac_f32_e32 v11, s88, v126
	v_fmac_f32_e32 v11, s89, v127
	v_fmac_f32_e32 v11, s90, v128
	v_fmac_f32_e32 v11, s91, v129
	v_fmac_f32_e32 v11, s92, v130
	v_fmac_f32_e32 v11, s93, v131
	v_fmac_f32_e32 v11, s94, v132
	v_fmac_f32_e32 v11, s95, v133
	v_fmac_f32_e32 v11, s96, v134
	v_fmac_f32_e32 v11, s97, v135
	v_fmac_f32_e32 v11, s98, v136
	v_mov_b32_e32 v8, v137
	v_mul_f32_e32 v10, v11, v8
	v_and_b32_e32 v11, 0x7fffffff, v10
	v_cmp_nlt_f32_e64 s[10:11], |v10|, s62
	s_and_saveexec_b64 s[12:13], s[10:11]
	s_xor_b64 s[16:17], exec, s[12:13]
	s_cbranch_execz .LBB0_76
	v_lshrrev_b32_e32 v8, 23, v11
	v_add_u32_e32 v8, 0xffffff88, v8
	v_cmp_lt_u32_e32 vcc, 63, v8
	v_mov_b32_e32 v13, v1
	v_mov_b32_e32 v15, v1
	v_cndmask_b32_e32 v9, 0, v28, vcc
	v_add_u32_e32 v8, v9, v8
	v_cmp_lt_u32_e64 s[10:11], 31, v8
	v_mov_b32_e32 v17, v1
	v_mov_b32_e32 v37, v1
	v_cndmask_b32_e64 v9, 0, v29, s[10:11]
	v_add_u32_e32 v8, v9, v8
	v_cmp_lt_u32_e64 s[12:13], 31, v8
	v_mov_b32_e32 v39, v1
	v_mov_b32_e32 v41, v1
	v_cndmask_b32_e64 v9, 0, v29, s[12:13]
	v_add_u32_e32 v42, v9, v8
	v_and_b32_e32 v8, 0x7fffff, v11
	v_or_b32_e32 v43, 0x800000, v8
	v_mad_u64_u32 v[8:9], s[14:15], v43, s63, 0
	v_mov_b32_e32 v12, v9
	v_mad_u64_u32 v[12:13], s[14:15], v43, s64, v[12:13]
	v_mov_b32_e32 v14, v13
	v_mad_u64_u32 v[14:15], s[14:15], v43, s65, v[14:15]
	v_mov_b32_e32 v16, v15
	v_mad_u64_u32 v[16:17], s[14:15], v43, s66, v[16:17]
	v_mov_b32_e32 v36, v17
	v_mad_u64_u32 v[36:37], s[14:15], v43, s67, v[36:37]
	v_mov_b32_e32 v38, v37
	v_mad_u64_u32 v[38:39], s[14:15], v43, s73, v[38:39]
	v_mov_b32_e32 v40, v39
	v_mad_u64_u32 v[40:41], s[14:15], v43, s69, v[40:41]
	v_cndmask_b32_e32 v9, v38, v16, vcc
	v_cndmask_b32_e32 v13, v40, v36, vcc
	v_cndmask_b32_e32 v17, v41, v38, vcc
	v_cndmask_b32_e64 v15, v13, v9, s[10:11]
	v_cndmask_b32_e64 v13, v17, v13, s[10:11]
	v_cndmask_b32_e32 v17, v36, v14, vcc
	v_cndmask_b32_e64 v9, v9, v17, s[10:11]
	v_cndmask_b32_e32 v12, v16, v12, vcc
	v_cndmask_b32_e64 v13, v13, v15, s[12:13]
	v_cndmask_b32_e64 v15, v15, v9, s[12:13]
	v_sub_u32_e32 v36, 32, v42
	v_cndmask_b32_e64 v16, v17, v12, s[10:11]
	v_alignbit_b32 v37, v13, v15, v36
	v_cmp_eq_u32_e64 s[14:15], 0, v42
	v_cndmask_b32_e64 v9, v9, v16, s[12:13]
	v_alignbit_b32 v17, v15, v9, v36
	v_cndmask_b32_e64 v13, v37, v13, s[14:15]
	v_cndmask_b32_e32 v8, v14, v8, vcc
	v_cndmask_b32_e64 v15, v17, v15, s[14:15]
	v_bfe_u32 v38, v13, 29, 1
	v_cndmask_b32_e64 v8, v12, v8, s[10:11]
	v_alignbit_b32 v17, v13, v15, 30
	v_sub_u32_e32 v39, 0, v38
	v_cndmask_b32_e64 v8, v16, v8, s[12:13]
	v_xor_b32_e32 v17, v17, v39
	v_alignbit_b32 v12, v9, v8, v36
	v_cndmask_b32_e64 v9, v12, v9, s[14:15]
	v_ffbh_u32_e32 v14, v17
	v_alignbit_b32 v12, v15, v9, 30
	v_min_u32_e32 v14, 32, v14
	v_alignbit_b32 v8, v9, v8, 30
	v_xor_b32_e32 v12, v12, v39
	v_sub_u32_e32 v15, 31, v14
	v_xor_b32_e32 v8, v8, v39
	v_alignbit_b32 v16, v17, v12, v15
	v_alignbit_b32 v8, v12, v8, v15
	v_alignbit_b32 v9, v16, v8, 9
	v_ffbh_u32_e32 v12, v9
	v_min_u32_e32 v12, 32, v12
	v_lshrrev_b32_e32 v37, 29, v13
	v_not_b32_e32 v15, v12
	v_alignbit_b32 v8, v9, v8, v15
	v_lshlrev_b32_e32 v9, 31, v37
	v_or_b32_e32 v15, 0x33000000, v9
	v_add_lshl_u32 v12, v12, v14, 23
	v_lshrrev_b32_e32 v8, 9, v8
	v_sub_u32_e32 v12, v15, v12
	v_or_b32_e32 v9, 0.5, v9
	v_lshlrev_b32_e32 v14, 23, v14
	v_or_b32_e32 v8, v12, v8
	v_lshrrev_b32_e32 v12, 9, v16
	v_sub_u32_e32 v9, v9, v14
	v_or_b32_e32 v9, v12, v9
	v_mul_f32_e32 v12, 0x3fc90fda, v9
	v_fma_f32 v14, v9, s70, -v12
	v_fmac_f32_e32 v14, 0x33a22168, v9
	v_fmac_f32_e32 v14, 0x3fc90fda, v8
	v_lshrrev_b32_e32 v8, 30, v13
	v_add_f32_e32 v14, v12, v14
	v_add_u32_e32 v13, v38, v8
.LBB0_76:
	s_andn2_saveexec_b64 s[10:11], s[16:17]
	v_mul_f32_e64 v8, |v10|, s71
	v_rndne_f32_e32 v8, v8
	v_cvt_i32_f32_e32 v13, v8
	v_fma_f32 v14, v8, s72, |v10|
	v_fmac_f32_e32 v14, 0xb3a22168, v8
	v_fmac_f32_e32 v14, 0xa7c234c4, v8
	s_or_b64 exec, exec, s[10:11]
	global_load_dword v12, v0, s[44:45]
	v_mul_f32_e32 v15, v14, v14
	v_fmamk_f32 v16, v15, 0xb94c1982, v23
	v_fmaak_f32 v16, v15, v16, 0xbe2aaa9d
	v_mul_f32_e32 v16, v15, v16
	v_fmac_f32_e32 v14, v14, v16
	v_fmamk_f32 v16, v15, 0x37d75334, v25
	v_fmaak_f32 v16, v15, v16, 0x3d2aabf7
	v_fmaak_f32 v16, v15, v16, 0xbf000004
	v_fma_f32 v15, v15, v16, 1.0
	v_and_b32_e32 v16, 1, v13
	v_lshlrev_b32_e32 v13, 30, v13
	v_cmp_eq_u32_e32 vcc, 0, v16
	v_and_b32_e32 v13, 0x80000000, v13
	v_xor_b32_e32 v11, v11, v10
	v_cndmask_b32_e32 v14, v15, v14, vcc
	v_xor_b32_e32 v11, v11, v13
	v_xor_b32_e32 v11, v11, v14
	v_cmp_class_f32_e64 vcc, v10, s76
	v_lshl_add_u64 v[8:9], s[46:47], 0, v[0:1]
	s_mov_b32 s1, 0
	v_cndmask_b32_e32 v13, v31, v11, vcc
	v_lshl_add_u64 v[10:11], v[4:5], 0, s[42:43]
	s_waitcnt vmcnt(0)
	v_readlane_b32 s88, v13, 0
	v_readlane_b32 s89, v13, 1
	v_readlane_b32 s90, v13, 2
	v_readlane_b32 s91, v13, 3
	v_readlane_b32 s92, v13, 4
	v_readlane_b32 s93, v13, 5
	v_readlane_b32 s94, v13, 6
	v_readlane_b32 s95, v13, 7
	v_fmac_f32_e32 v12, s88, v140
	v_fmac_f32_e32 v12, s89, v141
	v_fmac_f32_e32 v12, s90, v142
	v_fmac_f32_e32 v12, s91, v143
	v_fmac_f32_e32 v12, s92, v144
	v_fmac_f32_e32 v12, s93, v145
	v_fmac_f32_e32 v12, s94, v146
	v_fmac_f32_e32 v12, s95, v147
	v_readlane_b32 s88, v13, 8
	v_readlane_b32 s89, v13, 9
	v_readlane_b32 s90, v13, 10
	v_readlane_b32 s91, v13, 11
	v_readlane_b32 s92, v13, 12
	v_readlane_b32 s93, v13, 13
	v_readlane_b32 s94, v13, 14
	v_readlane_b32 s95, v13, 15
	v_fmac_f32_e32 v12, s88, v148
	v_fmac_f32_e32 v12, s89, v149
	v_fmac_f32_e32 v12, s90, v150
	v_fmac_f32_e32 v12, s91, v151
	v_fmac_f32_e32 v12, s92, v152
	v_fmac_f32_e32 v12, s93, v153
	v_fmac_f32_e32 v12, s94, v154
	v_fmac_f32_e32 v12, s95, v155
	v_readlane_b32 s88, v13, 16
	v_readlane_b32 s89, v13, 17
	v_readlane_b32 s90, v13, 18
	v_readlane_b32 s91, v13, 19
	v_readlane_b32 s92, v13, 20
	v_readlane_b32 s93, v13, 21
	v_readlane_b32 s94, v13, 22
	v_readlane_b32 s95, v13, 23
	v_fmac_f32_e32 v12, s88, v156
	v_fmac_f32_e32 v12, s89, v157
	v_fmac_f32_e32 v12, s90, v158
	v_fmac_f32_e32 v12, s91, v159
	v_fmac_f32_e32 v12, s92, v160
	v_fmac_f32_e32 v12, s93, v161
	v_fmac_f32_e32 v12, s94, v162
	v_fmac_f32_e32 v12, s95, v163
	v_readlane_b32 s88, v13, 24
	v_readlane_b32 s89, v13, 25
	v_readlane_b32 s90, v13, 26
	v_readlane_b32 s91, v13, 27
	v_readlane_b32 s92, v13, 28
	v_readlane_b32 s93, v13, 29
	v_readlane_b32 s94, v13, 30
	v_readlane_b32 s95, v13, 31
	v_fmac_f32_e32 v12, s88, v164
	v_fmac_f32_e32 v12, s89, v165
	v_fmac_f32_e32 v12, s90, v166
	v_fmac_f32_e32 v12, s91, v167
	v_fmac_f32_e32 v12, s92, v168
	v_fmac_f32_e32 v12, s93, v169
	v_fmac_f32_e32 v12, s94, v170
	v_fmac_f32_e32 v12, s95, v171
	v_readlane_b32 s88, v13, 32
	v_readlane_b32 s89, v13, 33
	v_readlane_b32 s90, v13, 34
	v_readlane_b32 s91, v13, 35
	v_readlane_b32 s92, v13, 36
	v_readlane_b32 s93, v13, 37
	v_readlane_b32 s94, v13, 38
	v_readlane_b32 s95, v13, 39
	v_fmac_f32_e32 v12, s88, v172
	v_fmac_f32_e32 v12, s89, v173
	v_fmac_f32_e32 v12, s90, v174
	v_fmac_f32_e32 v12, s91, v175
	v_fmac_f32_e32 v12, s92, v176
	v_fmac_f32_e32 v12, s93, v177
	v_fmac_f32_e32 v12, s94, v178
	v_fmac_f32_e32 v12, s95, v179
	v_readlane_b32 s88, v13, 40
	v_readlane_b32 s89, v13, 41
	v_readlane_b32 s90, v13, 42
	v_readlane_b32 s91, v13, 43
	v_readlane_b32 s92, v13, 44
	v_readlane_b32 s93, v13, 45
	v_readlane_b32 s94, v13, 46
	v_readlane_b32 s95, v13, 47
	v_fmac_f32_e32 v12, s88, v180
	v_fmac_f32_e32 v12, s89, v181
	v_fmac_f32_e32 v12, s90, v182
	v_fmac_f32_e32 v12, s91, v183
	v_fmac_f32_e32 v12, s92, v184
	v_fmac_f32_e32 v12, s93, v185
	v_fmac_f32_e32 v12, s94, v186
	v_fmac_f32_e32 v12, s95, v187
	v_readlane_b32 s88, v13, 48
	v_readlane_b32 s89, v13, 49
	v_readlane_b32 s90, v13, 50
	v_readlane_b32 s91, v13, 51
	v_readlane_b32 s92, v13, 52
	v_readlane_b32 s93, v13, 53
	v_readlane_b32 s94, v13, 54
	v_readlane_b32 s95, v13, 55
	v_fmac_f32_e32 v12, s88, v188
	v_fmac_f32_e32 v12, s89, v189
	v_fmac_f32_e32 v12, s90, v190
	v_fmac_f32_e32 v12, s91, v191
	v_fmac_f32_e32 v12, s92, v192
	v_fmac_f32_e32 v12, s93, v193
	v_fmac_f32_e32 v12, s94, v194
	v_fmac_f32_e32 v12, s95, v195
	v_readlane_b32 s88, v13, 56
	v_readlane_b32 s89, v13, 57
	v_readlane_b32 s90, v13, 58
	v_readlane_b32 s91, v13, 59
	v_readlane_b32 s92, v13, 60
	v_readlane_b32 s93, v13, 61
	v_readlane_b32 s94, v13, 62
	v_readlane_b32 s95, v13, 63
	v_fmac_f32_e32 v12, s88, v196
	v_fmac_f32_e32 v12, s89, v197
	v_fmac_f32_e32 v12, s90, v198
	v_fmac_f32_e32 v12, s91, v199
	v_fmac_f32_e32 v12, s92, v200
	v_fmac_f32_e32 v12, s93, v201
	v_fmac_f32_e32 v12, s94, v202
	v_fmac_f32_e32 v12, s95, v203
	v_mov_b32_e32 v8, v138
	v_mul_f32_e32 v8, v12, v8
	v_and_b32_e32 v9, 0x7fffffff, v8
	v_cmp_nlt_f32_e64 s[10:11], |v8|, s62
	s_and_saveexec_b64 s[12:13], s[10:11]
	s_xor_b64 s[16:17], exec, s[12:13]
	s_cbranch_execz .LBB0_82
	v_lshrrev_b32_e32 v10, 23, v9
	v_add_u32_e32 v10, 0xffffff88, v10
	v_cmp_lt_u32_e32 vcc, 63, v10
	v_mov_b32_e32 v13, v1
	v_mov_b32_e32 v15, v1
	v_cndmask_b32_e32 v11, 0, v28, vcc
	v_add_u32_e32 v10, v11, v10
	v_cmp_lt_u32_e64 s[10:11], 31, v10
	v_mov_b32_e32 v17, v1
	v_mov_b32_e32 v37, v1
	v_cndmask_b32_e64 v11, 0, v29, s[10:11]
	v_add_u32_e32 v10, v11, v10
	v_cmp_lt_u32_e64 s[12:13], 31, v10
	v_mov_b32_e32 v39, v1
	v_mov_b32_e32 v41, v1
	v_cndmask_b32_e64 v11, 0, v29, s[12:13]
	v_add_u32_e32 v42, v11, v10
	v_and_b32_e32 v10, 0x7fffff, v9
	v_or_b32_e32 v43, 0x800000, v10
	v_mad_u64_u32 v[10:11], s[14:15], v43, s63, 0
	v_mov_b32_e32 v12, v11
	v_mad_u64_u32 v[12:13], s[14:15], v43, s64, v[12:13]
	v_mov_b32_e32 v14, v13
	v_mad_u64_u32 v[14:15], s[14:15], v43, s65, v[14:15]
	v_mov_b32_e32 v16, v15
	v_mad_u64_u32 v[16:17], s[14:15], v43, s66, v[16:17]
	v_mov_b32_e32 v36, v17
	v_mad_u64_u32 v[36:37], s[14:15], v43, s67, v[36:37]
	v_mov_b32_e32 v38, v37
	v_mad_u64_u32 v[38:39], s[14:15], v43, s73, v[38:39]
	v_mov_b32_e32 v40, v39
	v_mad_u64_u32 v[40:41], s[14:15], v43, s69, v[40:41]
	v_cndmask_b32_e32 v11, v38, v16, vcc
	v_cndmask_b32_e32 v13, v40, v36, vcc
	v_cndmask_b32_e32 v17, v41, v38, vcc
	v_cndmask_b32_e64 v15, v13, v11, s[10:11]
	v_cndmask_b32_e64 v13, v17, v13, s[10:11]
	v_cndmask_b32_e32 v17, v36, v14, vcc
	v_cndmask_b32_e64 v11, v11, v17, s[10:11]
	v_cndmask_b32_e32 v12, v16, v12, vcc
	v_cndmask_b32_e64 v13, v13, v15, s[12:13]
	v_cndmask_b32_e64 v15, v15, v11, s[12:13]
	v_sub_u32_e32 v36, 32, v42
	v_cndmask_b32_e64 v16, v17, v12, s[10:11]
	v_alignbit_b32 v37, v13, v15, v36
	v_cmp_eq_u32_e64 s[14:15], 0, v42
	v_cndmask_b32_e64 v11, v11, v16, s[12:13]
	v_alignbit_b32 v17, v15, v11, v36
	v_cndmask_b32_e64 v13, v37, v13, s[14:15]
	v_cndmask_b32_e32 v10, v14, v10, vcc
	v_cndmask_b32_e64 v15, v17, v15, s[14:15]
	v_bfe_u32 v38, v13, 29, 1
	v_cndmask_b32_e64 v10, v12, v10, s[10:11]
	v_alignbit_b32 v17, v13, v15, 30
	v_sub_u32_e32 v39, 0, v38
	v_cndmask_b32_e64 v10, v16, v10, s[12:13]
	v_xor_b32_e32 v17, v17, v39
	v_alignbit_b32 v12, v11, v10, v36
	v_cndmask_b32_e64 v11, v12, v11, s[14:15]
	v_ffbh_u32_e32 v14, v17
	v_alignbit_b32 v12, v15, v11, 30
	v_min_u32_e32 v14, 32, v14
	v_alignbit_b32 v10, v11, v10, 30
	v_xor_b32_e32 v12, v12, v39
	v_sub_u32_e32 v15, 31, v14
	v_xor_b32_e32 v10, v10, v39
	v_alignbit_b32 v16, v17, v12, v15
	v_alignbit_b32 v10, v12, v10, v15
	v_alignbit_b32 v11, v16, v10, 9
	v_ffbh_u32_e32 v12, v11
	v_min_u32_e32 v12, 32, v12
	v_lshrrev_b32_e32 v37, 29, v13
	v_not_b32_e32 v15, v12
	v_alignbit_b32 v10, v11, v10, v15
	v_lshlrev_b32_e32 v11, 31, v37
	v_or_b32_e32 v15, 0x33000000, v11
	v_add_lshl_u32 v12, v12, v14, 23
	v_lshrrev_b32_e32 v10, 9, v10
	v_sub_u32_e32 v12, v15, v12
	v_or_b32_e32 v11, 0.5, v11
	v_lshlrev_b32_e32 v14, 23, v14
	v_or_b32_e32 v10, v12, v10
	v_lshrrev_b32_e32 v12, 9, v16
	v_sub_u32_e32 v11, v11, v14
	v_or_b32_e32 v11, v12, v11
	v_mul_f32_e32 v12, 0x3fc90fda, v11
	v_fma_f32 v14, v11, s70, -v12
	v_fmac_f32_e32 v14, 0x33a22168, v11
	v_fmac_f32_e32 v14, 0x3fc90fda, v10
	v_lshrrev_b32_e32 v10, 30, v13
	v_add_f32_e32 v11, v12, v14
	v_add_u32_e32 v10, v38, v10

.Lflt_l3a:
	v_add_u32_e32 v102, s10, v101
	ds_read_b32 v40, v102
	ds_read_b32 v41, v102 offset:256
	ds_read_b32 v42, v102 offset:512
	ds_read_b32 v43, v102 offset:768
	ds_read_b32 v44, v102 offset:1024
	ds_read_b32 v45, v102 offset:1280
	ds_read_b32 v46, v102 offset:1536
	ds_read_b32 v47, v102 offset:1792
	ds_read_b32 v48, v102 offset:2048
	ds_read_b32 v49, v102 offset:2304
	ds_read_b32 v50, v102 offset:2560
	ds_read_b32 v51, v102 offset:2816
	ds_read_b32 v52, v102 offset:3072
	ds_read_b32 v53, v102 offset:3328
	ds_read_b32 v54, v102 offset:3584
	ds_read_b32 v55, v102 offset:3840
	ds_read_b32 v56, v102 offset:4096
	ds_read_b32 v57, v102 offset:4352
	ds_read_b32 v58, v102 offset:4608
	ds_read_b32 v59, v102 offset:4864
	ds_read_b32 v60, v102 offset:5120
	ds_read_b32 v61, v102 offset:5376
	ds_read_b32 v62, v102 offset:5632
	ds_read_b32 v63, v102 offset:5888
	ds_read_b32 v64, v102 offset:6144
	ds_read_b32 v65, v102 offset:6400
	ds_read_b32 v66, v102 offset:6656
	ds_read_b32 v67, v102 offset:6912
	ds_read_b32 v68, v102 offset:7168
	ds_read_b32 v69, v102 offset:7424
	ds_read_b32 v70, v102 offset:7680
	ds_read_b32 v71, v102 offset:7936
	s_lshr_b32 s96, s10, 11
	v_readlane_b32 s88, v36, s96
	s_add_i32 s96, s96, 1
	v_readlane_b32 s90, v36, s96
	s_add_i32 s96, s96, 1
	v_readlane_b32 s92, v36, s96
	s_add_i32 s96, s96, 1
	v_readlane_b32 s94, v36, s96
	s_add_u32 s10, s10, 0x2000
	s_addc_u32 s11, s11, 0
	s_cmp_eq_u32 s10, 0x20000
	s_waitcnt lgkmcnt(15)
	v_pk_fma_f32 v[14:15], v[40:41], s[88:89], v[14:15] op_sel_hi:[1,0,1]
	v_pk_fma_f32 v[12:13], v[42:43], s[88:89], v[12:13] op_sel_hi:[1,0,1]
	v_pk_fma_f32 v[10:11], v[44:45], s[88:89], v[10:11] op_sel_hi:[1,0,1]
	v_pk_fma_f32 v[8:9], v[46:47], s[88:89], v[8:9] op_sel_hi:[1,0,1]
	v_pk_fma_f32 v[14:15], v[48:49], s[90:91], v[14:15] op_sel_hi:[1,0,1]
	v_pk_fma_f32 v[12:13], v[50:51], s[90:91], v[12:13] op_sel_hi:[1,0,1]
	v_pk_fma_f32 v[10:11], v[52:53], s[90:91], v[10:11] op_sel_hi:[1,0,1]
	v_pk_fma_f32 v[8:9], v[54:55], s[90:91], v[8:9] op_sel_hi:[1,0,1]
	s_waitcnt lgkmcnt(7)
	v_pk_fma_f32 v[14:15], v[56:57], s[92:93], v[14:15] op_sel_hi:[1,0,1]
	v_pk_fma_f32 v[12:13], v[58:59], s[92:93], v[12:13] op_sel_hi:[1,0,1]
	v_pk_fma_f32 v[10:11], v[60:61], s[92:93], v[10:11] op_sel_hi:[1,0,1]
	v_pk_fma_f32 v[8:9], v[62:63], s[92:93], v[8:9] op_sel_hi:[1,0,1]
	s_waitcnt lgkmcnt(0)
	v_pk_fma_f32 v[14:15], v[64:65], s[94:95], v[14:15] op_sel_hi:[1,0,1]
	v_pk_fma_f32 v[12:13], v[66:67], s[94:95], v[12:13] op_sel_hi:[1,0,1]
	v_pk_fma_f32 v[10:11], v[68:69], s[94:95], v[10:11] op_sel_hi:[1,0,1]
	v_pk_fma_f32 v[8:9], v[70:71], s[94:95], v[8:9] op_sel_hi:[1,0,1]
	s_cbranch_scc0 .Lflt_l3a
	s_branch .Lflt_l3a_done

.LBB0_104:
	s_or_b64 exec, exec, s[16:17]
	v_lshlrev_b32_e32 v0, 2, v26
	global_load_dword v11, v0, s[50:51]
	s_mov_b32 s0, 0
	v_and_b32_e32 v36, 0x100, v32
	v_lshl_add_u64 v[8:9], v[2:3], 0, s[48:49]
	s_waitcnt vmcnt(0)
	v_readlane_b32 s88, v10, 0
	v_readlane_b32 s89, v10, 1
	v_readlane_b32 s90, v10, 2
	v_readlane_b32 s91, v10, 3
	v_readlane_b32 s92, v10, 4
	v_readlane_b32 s93, v10, 5
	v_readlane_b32 s94, v10, 6
	v_readlane_b32 s95, v10, 7
	v_readlane_b32 s96, v10, 8
	v_readlane_b32 s97, v10, 9
	v_readlane_b32 s98, v10, 10
	v_fmac_f32_e32 v11, s88, v104
	v_fmac_f32_e32 v11, s89, v105
	v_fmac_f32_e32 v11, s90, v106
	v_fmac_f32_e32 v11, s91, v107
	v_fmac_f32_e32 v11, s92, v108
	v_fmac_f32_e32 v11, s93, v109
	v_fmac_f32_e32 v11, s94, v110
	v_fmac_f32_e32 v11, s95, v111
	v_fmac_f32_e32 v11, s96, v112
	v_fmac_f32_e32 v11, s97, v113
	v_fmac_f32_e32 v11, s98, v114
	v_readlane_b32 s88, v10, 11
	v_readlane_b32 s89, v10, 12
	v_readlane_b32 s90, v10, 13
	v_readlane_b32 s91, v10, 14
	v_readlane_b32 s92, v10, 15
	v_readlane_b32 s93, v10, 16
	v_readlane_b32 s94, v10, 17
	v_readlane_b32 s95, v10, 18
	v_readlane_b32 s96, v10, 19
	v_readlane_b32 s97, v10, 20
	v_readlane_b32 s98, v10, 21
	v_fmac_f32_e32 v11, s88, v115
	v_fmac_f32_e32 v11, s89, v116
	v_fmac_f32_e32 v11, s90, v117
	v_fmac_f32_e32 v11, s91, v118
	v_fmac_f32_e32 v11, s92, v119
	v_fmac_f32_e32 v11, s93, v120
	v_fmac_f32_e32 v11, s94, v121
	v_fmac_f32_e32 v11, s95, v122
	v_fmac_f32_e32 v11, s96, v123
	v_fmac_f32_e32 v11, s97, v124
	v_fmac_f32_e32 v11, s98, v125
	v_readlane_b32 s88, v10, 22
	v_readlane_b32 s89, v10, 23
	v_readlane_b32 s90, v10, 24
	v_readlane_b32 s91, v10, 25
	v_readlane_b32 s92, v10, 26
	v_readlane_b32 s93, v10, 27
	v_readlane_b32 s94, v10, 28
	v_readlane_b32 s95, v10, 29
	v_readlane_b32 s96, v10, 30
	v_readlane_b32 s97, v10, 31
	v_readlane_b32 s98, v10, 32
	v_fmac_f32_e32 v11, s88, v126
	v_fmac_f32_e32 v11, s89, v127
	v_fmac_f32_e32 v11, s90, v128
	v_fmac_f32_e32 v11, s91, v129
	v_fmac_f32_e32 v11, s92, v130
	v_fmac_f32_e32 v11, s93, v131
	v_fmac_f32_e32 v11, s94, v132
	v_fmac_f32_e32 v11, s95, v133
	v_fmac_f32_e32 v11, s96, v134
	v_fmac_f32_e32 v11, s97, v135
	v_fmac_f32_e32 v11, s98, v136
	v_mov_b32_e32 v8, v137
	v_mul_f32_e32 v10, v11, v8
	v_and_b32_e32 v11, 0x7fffffff, v10
	v_cmp_nlt_f32_e64 s[0:1], |v10|, s62
	s_and_saveexec_b64 s[10:11], s[0:1]
	s_xor_b64 s[16:17], exec, s[10:11]
	s_cbranch_execz .LBB0_108
	v_lshrrev_b32_e32 v8, 23, v11
	v_add_u32_e32 v8, 0xffffff88, v8
	v_cmp_lt_u32_e32 vcc, 63, v8
	v_mov_b32_e32 v13, v1
	v_mov_b32_e32 v15, v1
	v_cndmask_b32_e32 v9, 0, v28, vcc
	v_add_u32_e32 v8, v9, v8
	v_cmp_lt_u32_e64 s[10:11], 31, v8
	v_mov_b32_e32 v17, v1
	v_mov_b32_e32 v39, v1
	v_cndmask_b32_e64 v9, 0, v29, s[10:11]
	v_add_u32_e32 v8, v9, v8
	v_cmp_lt_u32_e64 s[12:13], 31, v8
	v_mov_b32_e32 v41, v1
	v_mov_b32_e32 v43, v1
	v_cndmask_b32_e64 v9, 0, v29, s[12:13]
	v_add_u32_e32 v37, v9, v8
	v_and_b32_e32 v8, 0x7fffff, v11
	v_or_b32_e32 v44, 0x800000, v8
	v_mad_u64_u32 v[8:9], s[0:1], v44, s63, 0
	v_mov_b32_e32 v12, v9
	v_mad_u64_u32 v[12:13], s[0:1], v44, s64, v[12:13]
	v_mov_b32_e32 v14, v13
	v_mad_u64_u32 v[14:15], s[0:1], v44, s65, v[14:15]
	v_mov_b32_e32 v16, v15
	v_mad_u64_u32 v[16:17], s[0:1], v44, s66, v[16:17]
	v_mov_b32_e32 v38, v17
	v_mad_u64_u32 v[38:39], s[0:1], v44, s67, v[38:39]
	v_mov_b32_e32 v40, v39
	v_mad_u64_u32 v[40:41], s[0:1], v44, s73, v[40:41]
	v_mov_b32_e32 v42, v41
	v_mad_u64_u32 v[42:43], s[0:1], v44, s69, v[42:43]
	v_cndmask_b32_e32 v9, v40, v16, vcc
	v_cndmask_b32_e32 v13, v42, v38, vcc
	v_cndmask_b32_e32 v17, v43, v40, vcc
	v_cndmask_b32_e64 v15, v13, v9, s[10:11]
	v_cndmask_b32_e64 v13, v17, v13, s[10:11]
	v_cndmask_b32_e32 v17, v38, v14, vcc
	v_cndmask_b32_e64 v9, v9, v17, s[10:11]
	v_cndmask_b32_e32 v12, v16, v12, vcc
	v_cndmask_b32_e64 v13, v13, v15, s[12:13]
	v_cndmask_b32_e64 v15, v15, v9, s[12:13]
	v_sub_u32_e32 v38, 32, v37
	v_cndmask_b32_e64 v16, v17, v12, s[10:11]
	v_alignbit_b32 v39, v13, v15, v38
	v_cmp_eq_u32_e64 s[14:15], 0, v37
	v_cndmask_b32_e64 v9, v9, v16, s[12:13]
	v_alignbit_b32 v17, v15, v9, v38
	v_cndmask_b32_e64 v13, v39, v13, s[14:15]
	v_cndmask_b32_e32 v8, v14, v8, vcc
	v_cndmask_b32_e64 v15, v17, v15, s[14:15]
	v_bfe_u32 v39, v13, 29, 1
	v_cndmask_b32_e64 v8, v12, v8, s[10:11]
	v_alignbit_b32 v17, v13, v15, 30
	v_sub_u32_e32 v40, 0, v39
	v_cndmask_b32_e64 v8, v16, v8, s[12:13]
	v_xor_b32_e32 v17, v17, v40
	v_alignbit_b32 v12, v9, v8, v38
	v_cndmask_b32_e64 v9, v12, v9, s[14:15]
	v_ffbh_u32_e32 v14, v17
	v_alignbit_b32 v12, v15, v9, 30
	v_min_u32_e32 v14, 32, v14
	v_alignbit_b32 v8, v9, v8, 30
	v_xor_b32_e32 v12, v12, v40
	v_sub_u32_e32 v15, 31, v14
	v_xor_b32_e32 v8, v8, v40
	v_alignbit_b32 v16, v17, v12, v15
	v_alignbit_b32 v8, v12, v8, v15
	v_alignbit_b32 v9, v16, v8, 9
	v_ffbh_u32_e32 v12, v9
	v_min_u32_e32 v12, 32, v12
	v_lshrrev_b32_e32 v37, 29, v13
	v_not_b32_e32 v15, v12
	v_alignbit_b32 v8, v9, v8, v15
	v_lshlrev_b32_e32 v9, 31, v37
	v_or_b32_e32 v15, 0x33000000, v9
	v_add_lshl_u32 v12, v12, v14, 23
	v_lshrrev_b32_e32 v8, 9, v8
	v_sub_u32_e32 v12, v15, v12
	v_or_b32_e32 v9, 0.5, v9
	v_lshlrev_b32_e32 v14, 23, v14
	v_or_b32_e32 v8, v12, v8
	v_lshrrev_b32_e32 v12, 9, v16
	v_sub_u32_e32 v9, v9, v14
	v_or_b32_e32 v9, v12, v9
	v_mul_f32_e32 v12, 0x3fc90fda, v9
	v_fma_f32 v14, v9, s70, -v12
	v_fmac_f32_e32 v14, 0x33a22168, v9
	v_fmac_f32_e32 v14, 0x3fc90fda, v8
	v_lshrrev_b32_e32 v8, 30, v13
	v_add_f32_e32 v14, v12, v14
	v_add_u32_e32 v13, v39, v8
.LBB0_108:
	s_andn2_saveexec_b64 s[10:11], s[16:17]
	v_mul_f32_e64 v8, |v10|, s71
	v_rndne_f32_e32 v8, v8
	v_cvt_i32_f32_e32 v13, v8
	v_fma_f32 v14, v8, s72, |v10|
	v_fmac_f32_e32 v14, 0xb3a22168, v8
	v_fmac_f32_e32 v14, 0xa7c234c4, v8
	s_or_b64 exec, exec, s[10:11]
	global_load_dword v12, v0, s[44:45]
	v_mul_f32_e32 v15, v14, v14
	v_fmamk_f32 v16, v15, 0xb94c1982, v23
	v_fmaak_f32 v16, v15, v16, 0xbe2aaa9d
	v_mul_f32_e32 v16, v15, v16
	v_fmac_f32_e32 v14, v14, v16
	v_fmamk_f32 v16, v15, 0x37d75334, v25
	v_fmaak_f32 v16, v15, v16, 0x3d2aabf7
	v_fmaak_f32 v16, v15, v16, 0xbf000004
	v_fma_f32 v15, v15, v16, 1.0
	v_and_b32_e32 v16, 1, v13
	v_lshlrev_b32_e32 v13, 30, v13
	v_cmp_eq_u32_e32 vcc, 0, v16
	v_and_b32_e32 v13, 0x80000000, v13
	v_xor_b32_e32 v11, v11, v10
	v_cndmask_b32_e32 v14, v15, v14, vcc
	v_xor_b32_e32 v11, v11, v13
	v_xor_b32_e32 v11, v11, v14
	v_cmp_class_f32_e64 vcc, v10, s76
	v_lshl_add_u64 v[8:9], s[46:47], 0, v[0:1]
	s_mov_b32 s0, 0
	v_cndmask_b32_e32 v13, v31, v11, vcc
	v_lshl_add_u64 v[10:11], v[4:5], 0, s[42:43]
	s_waitcnt vmcnt(0)
	v_readlane_b32 s88, v13, 0
	v_readlane_b32 s89, v13, 1
	v_readlane_b32 s90, v13, 2
	v_readlane_b32 s91, v13, 3
	v_readlane_b32 s92, v13, 4
	v_readlane_b32 s93, v13, 5
	v_readlane_b32 s94, v13, 6
	v_readlane_b32 s95, v13, 7
	v_fmac_f32_e32 v12, s88, v140
	v_fmac_f32_e32 v12, s89, v141
	v_fmac_f32_e32 v12, s90, v142
	v_fmac_f32_e32 v12, s91, v143
	v_fmac_f32_e32 v12, s92, v144
	v_fmac_f32_e32 v12, s93, v145
	v_fmac_f32_e32 v12, s94, v146
	v_fmac_f32_e32 v12, s95, v147
	v_readlane_b32 s88, v13, 8
	v_readlane_b32 s89, v13, 9
	v_readlane_b32 s90, v13, 10
	v_readlane_b32 s91, v13, 11
	v_readlane_b32 s92, v13, 12
	v_readlane_b32 s93, v13, 13
	v_readlane_b32 s94, v13, 14
	v_readlane_b32 s95, v13, 15
	v_fmac_f32_e32 v12, s88, v148
	v_fmac_f32_e32 v12, s89, v149
	v_fmac_f32_e32 v12, s90, v150
	v_fmac_f32_e32 v12, s91, v151
	v_fmac_f32_e32 v12, s92, v152
	v_fmac_f32_e32 v12, s93, v153
	v_fmac_f32_e32 v12, s94, v154
	v_fmac_f32_e32 v12, s95, v155
	v_readlane_b32 s88, v13, 16
	v_readlane_b32 s89, v13, 17
	v_readlane_b32 s90, v13, 18
	v_readlane_b32 s91, v13, 19
	v_readlane_b32 s92, v13, 20
	v_readlane_b32 s93, v13, 21
	v_readlane_b32 s94, v13, 22
	v_readlane_b32 s95, v13, 23
	v_fmac_f32_e32 v12, s88, v156
	v_fmac_f32_e32 v12, s89, v157
	v_fmac_f32_e32 v12, s90, v158
	v_fmac_f32_e32 v12, s91, v159
	v_fmac_f32_e32 v12, s92, v160
	v_fmac_f32_e32 v12, s93, v161
	v_fmac_f32_e32 v12, s94, v162
	v_fmac_f32_e32 v12, s95, v163
	v_readlane_b32 s88, v13, 24
	v_readlane_b32 s89, v13, 25
	v_readlane_b32 s90, v13, 26
	v_readlane_b32 s91, v13, 27
	v_readlane_b32 s92, v13, 28
	v_readlane_b32 s93, v13, 29
	v_readlane_b32 s94, v13, 30
	v_readlane_b32 s95, v13, 31
	v_fmac_f32_e32 v12, s88, v164
	v_fmac_f32_e32 v12, s89, v165
	v_fmac_f32_e32 v12, s90, v166
	v_fmac_f32_e32 v12, s91, v167
	v_fmac_f32_e32 v12, s92, v168
	v_fmac_f32_e32 v12, s93, v169
	v_fmac_f32_e32 v12, s94, v170
	v_fmac_f32_e32 v12, s95, v171
	v_readlane_b32 s88, v13, 32
	v_readlane_b32 s89, v13, 33
	v_readlane_b32 s90, v13, 34
	v_readlane_b32 s91, v13, 35
	v_readlane_b32 s92, v13, 36
	v_readlane_b32 s93, v13, 37
	v_readlane_b32 s94, v13, 38
	v_readlane_b32 s95, v13, 39
	v_fmac_f32_e32 v12, s88, v172
	v_fmac_f32_e32 v12, s89, v173
	v_fmac_f32_e32 v12, s90, v174
	v_fmac_f32_e32 v12, s91, v175
	v_fmac_f32_e32 v12, s92, v176
	v_fmac_f32_e32 v12, s93, v177
	v_fmac_f32_e32 v12, s94, v178
	v_fmac_f32_e32 v12, s95, v179
	v_readlane_b32 s88, v13, 40
	v_readlane_b32 s89, v13, 41
	v_readlane_b32 s90, v13, 42
	v_readlane_b32 s91, v13, 43
	v_readlane_b32 s92, v13, 44
	v_readlane_b32 s93, v13, 45
	v_readlane_b32 s94, v13, 46
	v_readlane_b32 s95, v13, 47
	v_fmac_f32_e32 v12, s88, v180
	v_fmac_f32_e32 v12, s89, v181
	v_fmac_f32_e32 v12, s90, v182
	v_fmac_f32_e32 v12, s91, v183
	v_fmac_f32_e32 v12, s92, v184
	v_fmac_f32_e32 v12, s93, v185
	v_fmac_f32_e32 v12, s94, v186
	v_fmac_f32_e32 v12, s95, v187
	v_readlane_b32 s88, v13, 48
	v_readlane_b32 s89, v13, 49
	v_readlane_b32 s90, v13, 50
	v_readlane_b32 s91, v13, 51
	v_readlane_b32 s92, v13, 52
	v_readlane_b32 s93, v13, 53
	v_readlane_b32 s94, v13, 54
	v_readlane_b32 s95, v13, 55
	v_fmac_f32_e32 v12, s88, v188
	v_fmac_f32_e32 v12, s89, v189
	v_fmac_f32_e32 v12, s90, v190
	v_fmac_f32_e32 v12, s91, v191
	v_fmac_f32_e32 v12, s92, v192
	v_fmac_f32_e32 v12, s93, v193
	v_fmac_f32_e32 v12, s94, v194
	v_fmac_f32_e32 v12, s95, v195
	v_readlane_b32 s88, v13, 56
	v_readlane_b32 s89, v13, 57
	v_readlane_b32 s90, v13, 58
	v_readlane_b32 s91, v13, 59
	v_readlane_b32 s92, v13, 60
	v_readlane_b32 s93, v13, 61
	v_readlane_b32 s94, v13, 62
	v_readlane_b32 s95, v13, 63
	v_fmac_f32_e32 v12, s88, v196
	v_fmac_f32_e32 v12, s89, v197
	v_fmac_f32_e32 v12, s90, v198
	v_fmac_f32_e32 v12, s91, v199
	v_fmac_f32_e32 v12, s92, v200
	v_fmac_f32_e32 v12, s93, v201
	v_fmac_f32_e32 v12, s94, v202
	v_fmac_f32_e32 v12, s95, v203
	v_mov_b32_e32 v8, v138
	v_mul_f32_e32 v8, v12, v8
	v_and_b32_e32 v9, 0x7fffffff, v8
	v_cmp_nlt_f32_e64 s[0:1], |v8|, s62
	s_and_saveexec_b64 s[10:11], s[0:1]
	s_xor_b64 s[16:17], exec, s[10:11]
	s_cbranch_execz .LBB0_114
	v_lshrrev_b32_e32 v10, 23, v9
	v_add_u32_e32 v10, 0xffffff88, v10
	v_cmp_lt_u32_e32 vcc, 63, v10
	v_mov_b32_e32 v13, v1
	v_mov_b32_e32 v15, v1
	v_cndmask_b32_e32 v11, 0, v28, vcc
	v_add_u32_e32 v10, v11, v10
	v_cmp_lt_u32_e64 s[10:11], 31, v10
	v_mov_b32_e32 v17, v1
	v_mov_b32_e32 v39, v1
	v_cndmask_b32_e64 v11, 0, v29, s[10:11]
	v_add_u32_e32 v10, v11, v10
	v_cmp_lt_u32_e64 s[12:13], 31, v10
	v_mov_b32_e32 v41, v1
	v_mov_b32_e32 v43, v1
	v_cndmask_b32_e64 v11, 0, v29, s[12:13]
	v_add_u32_e32 v37, v11, v10
	v_and_b32_e32 v10, 0x7fffff, v9
	v_or_b32_e32 v44, 0x800000, v10
	v_mad_u64_u32 v[10:11], s[0:1], v44, s63, 0
	v_mov_b32_e32 v12, v11
	v_mad_u64_u32 v[12:13], s[0:1], v44, s64, v[12:13]
	v_mov_b32_e32 v14, v13
	v_mad_u64_u32 v[14:15], s[0:1], v44, s65, v[14:15]
	v_mov_b32_e32 v16, v15
	v_mad_u64_u32 v[16:17], s[0:1], v44, s66, v[16:17]
	v_mov_b32_e32 v38, v17
	v_mad_u64_u32 v[38:39], s[0:1], v44, s67, v[38:39]
	v_mov_b32_e32 v40, v39
	v_mad_u64_u32 v[40:41], s[0:1], v44, s73, v[40:41]
	v_mov_b32_e32 v42, v41
	v_mad_u64_u32 v[42:43], s[0:1], v44, s69, v[42:43]
	v_cndmask_b32_e32 v11, v40, v16, vcc
	v_cndmask_b32_e32 v13, v42, v38, vcc
	v_cndmask_b32_e32 v17, v43, v40, vcc
	v_cndmask_b32_e64 v15, v13, v11, s[10:11]
	v_cndmask_b32_e64 v13, v17, v13, s[10:11]
	v_cndmask_b32_e32 v17, v38, v14, vcc
	v_cndmask_b32_e64 v11, v11, v17, s[10:11]
	v_cndmask_b32_e32 v12, v16, v12, vcc
	v_cndmask_b32_e64 v13, v13, v15, s[12:13]
	v_cndmask_b32_e64 v15, v15, v11, s[12:13]
	v_sub_u32_e32 v38, 32, v37
	v_cndmask_b32_e64 v16, v17, v12, s[10:11]
	v_alignbit_b32 v39, v13, v15, v38
	v_cmp_eq_u32_e64 s[14:15], 0, v37
	v_cndmask_b32_e64 v11, v11, v16, s[12:13]
	v_alignbit_b32 v17, v15, v11, v38
	v_cndmask_b32_e64 v13, v39, v13, s[14:15]
	v_cndmask_b32_e32 v10, v14, v10, vcc
	v_cndmask_b32_e64 v15, v17, v15, s[14:15]
	v_bfe_u32 v39, v13, 29, 1
	v_cndmask_b32_e64 v10, v12, v10, s[10:11]
	v_alignbit_b32 v17, v13, v15, 30
	v_sub_u32_e32 v40, 0, v39
	v_cndmask_b32_e64 v10, v16, v10, s[12:13]
	v_xor_b32_e32 v17, v17, v40
	v_alignbit_b32 v12, v11, v10, v38
	v_cndmask_b32_e64 v11, v12, v11, s[14:15]
	v_ffbh_u32_e32 v14, v17
	v_alignbit_b32 v12, v15, v11, 30
	v_min_u32_e32 v14, 32, v14
	v_alignbit_b32 v10, v11, v10, 30
	v_xor_b32_e32 v12, v12, v40
	v_sub_u32_e32 v15, 31, v14
	v_xor_b32_e32 v10, v10, v40
	v_alignbit_b32 v16, v17, v12, v15
	v_alignbit_b32 v10, v12, v10, v15
	v_alignbit_b32 v11, v16, v10, 9
	v_ffbh_u32_e32 v12, v11
	v_min_u32_e32 v12, 32, v12
	v_lshrrev_b32_e32 v37, 29, v13
	v_not_b32_e32 v15, v12
	v_alignbit_b32 v10, v11, v10, v15
	v_lshlrev_b32_e32 v11, 31, v37
	v_or_b32_e32 v15, 0x33000000, v11
	v_add_lshl_u32 v12, v12, v14, 23
	v_lshrrev_b32_e32 v10, 9, v10
	v_sub_u32_e32 v12, v15, v12
	v_or_b32_e32 v11, 0.5, v11
	v_lshlrev_b32_e32 v14, 23, v14
	v_or_b32_e32 v10, v12, v10
	v_lshrrev_b32_e32 v12, 9, v16
	v_sub_u32_e32 v11, v11, v14
	v_or_b32_e32 v11, v12, v11
	v_mul_f32_e32 v12, 0x3fc90fda, v11
	v_fma_f32 v14, v11, s70, -v12
	v_fmac_f32_e32 v14, 0x33a22168, v11
	v_fmac_f32_e32 v14, 0x3fc90fda, v10
	v_lshrrev_b32_e32 v10, 30, v13
	v_add_f32_e32 v11, v12, v14
	v_add_u32_e32 v10, v39, v10

.Lflt_l3b:
	v_add_u32_e32 v102, s10, v101
	ds_read_b32 v40, v102
	ds_read_b32 v41, v102 offset:256
	ds_read_b32 v42, v102 offset:512
	ds_read_b32 v43, v102 offset:768
	ds_read_b32 v44, v102 offset:1024
	ds_read_b32 v45, v102 offset:1280
	ds_read_b32 v46, v102 offset:1536
	ds_read_b32 v47, v102 offset:1792
	ds_read_b32 v48, v102 offset:2048
	ds_read_b32 v49, v102 offset:2304
	ds_read_b32 v50, v102 offset:2560
	ds_read_b32 v51, v102 offset:2816
	ds_read_b32 v52, v102 offset:3072
	ds_read_b32 v53, v102 offset:3328
	ds_read_b32 v54, v102 offset:3584
	ds_read_b32 v55, v102 offset:3840
	ds_read_b32 v56, v102 offset:4096
	ds_read_b32 v57, v102 offset:4352
	ds_read_b32 v58, v102 offset:4608
	ds_read_b32 v59, v102 offset:4864
	ds_read_b32 v60, v102 offset:5120
	ds_read_b32 v61, v102 offset:5376
	ds_read_b32 v62, v102 offset:5632
	ds_read_b32 v63, v102 offset:5888
	ds_read_b32 v64, v102 offset:6144
	ds_read_b32 v65, v102 offset:6400
	ds_read_b32 v66, v102 offset:6656
	ds_read_b32 v67, v102 offset:6912
	ds_read_b32 v68, v102 offset:7168
	ds_read_b32 v69, v102 offset:7424
	ds_read_b32 v70, v102 offset:7680
	ds_read_b32 v71, v102 offset:7936
	s_lshr_b32 s96, s10, 11
	v_readlane_b32 s88, v37, s96
	s_add_i32 s96, s96, 1
	v_readlane_b32 s90, v37, s96
	s_add_i32 s96, s96, 1
	v_readlane_b32 s92, v37, s96
	s_add_i32 s96, s96, 1
	v_readlane_b32 s94, v37, s96
	s_add_u32 s10, s10, 0x2000
	s_addc_u32 s11, s11, 0
	s_cmp_eq_u32 s10, 0x20000
	s_waitcnt lgkmcnt(15)
	v_pk_fma_f32 v[14:15], v[40:41], s[88:89], v[14:15] op_sel_hi:[1,0,1]
	v_pk_fma_f32 v[12:13], v[42:43], s[88:89], v[12:13] op_sel_hi:[1,0,1]
	v_pk_fma_f32 v[10:11], v[44:45], s[88:89], v[10:11] op_sel_hi:[1,0,1]
	v_pk_fma_f32 v[8:9], v[46:47], s[88:89], v[8:9] op_sel_hi:[1,0,1]
	v_pk_fma_f32 v[14:15], v[48:49], s[90:91], v[14:15] op_sel_hi:[1,0,1]
	v_pk_fma_f32 v[12:13], v[50:51], s[90:91], v[12:13] op_sel_hi:[1,0,1]
	v_pk_fma_f32 v[10:11], v[52:53], s[90:91], v[10:11] op_sel_hi:[1,0,1]
	v_pk_fma_f32 v[8:9], v[54:55], s[90:91], v[8:9] op_sel_hi:[1,0,1]
	s_waitcnt lgkmcnt(7)
	v_pk_fma_f32 v[14:15], v[56:57], s[92:93], v[14:15] op_sel_hi:[1,0,1]
	v_pk_fma_f32 v[12:13], v[58:59], s[92:93], v[12:13] op_sel_hi:[1,0,1]
	v_pk_fma_f32 v[10:11], v[60:61], s[92:93], v[10:11] op_sel_hi:[1,0,1]
	v_pk_fma_f32 v[8:9], v[62:63], s[92:93], v[8:9] op_sel_hi:[1,0,1]
	s_waitcnt lgkmcnt(0)
	v_pk_fma_f32 v[14:15], v[64:65], s[94:95], v[14:15] op_sel_hi:[1,0,1]
	v_pk_fma_f32 v[12:13], v[66:67], s[94:95], v[12:13] op_sel_hi:[1,0,1]
	v_pk_fma_f32 v[10:11], v[68:69], s[94:95], v[10:11] op_sel_hi:[1,0,1]
	v_pk_fma_f32 v[8:9], v[70:71], s[94:95], v[8:9] op_sel_hi:[1,0,1]
	s_cbranch_scc0 .Lflt_l3b
	s_branch .Lflt_l3b_done

.LBB0_1017:
	v_max_f32_e32 v2, v173, v173
	v_max_f32_e32 v184, v172, v172
	v_max_f32_e32 v2, v184, v2
	v_max_f32_e32 v184, v175, v175
	v_max_f32_e32 v185, v174, v174
	v_max_f32_e32 v184, v185, v184
	v_max_f32_e32 v185, v179, v179
	v_max_f32_e32 v186, v178, v178
	v_max_f32_e32 v185, v186, v185
	v_max3_f32 v185, v176, v177, v185
	v_max3_f32 v2, v2, v184, v185
	v_mov_b32_e32 v184, v2
	s_nop 1
	v_permlane16_swap_b32_e32 v184, v2
	s_xor_b64 s[8:9], s[46:47], -1
	s_andn2_b64 vcc, exec, s[8:9]
	s_waitcnt lgkmcnt(0)
	v_max_f32_e32 v184, v184, v184
	v_max_f32_e32 v2, v2, v184
	v_mov_b32_e32 v184, v2
	s_nop 1
	v_permlane32_swap_b32_e32 v184, v2
	s_waitcnt lgkmcnt(0)
	v_max3_f32 v213, v180, v2, v184
	v_sub_f32_e32 v172, v172, v213
	v_mul_f32_e32 v172, 0x3fb8aa3b, v172
	v_exp_f32_e32 v209, v172
	v_sub_f32_e32 v172, v173, v213
	v_mul_f32_e32 v172, 0x3fb8aa3b, v172
	v_exp_f32_e32 v215, v172
	v_sub_f32_e32 v172, v174, v213
	v_mul_f32_e32 v172, 0x3fb8aa3b, v172
	v_exp_f32_e32 v216, v172
	v_sub_f32_e32 v172, v175, v213
	v_mul_f32_e32 v172, 0x3fb8aa3b, v172
	v_exp_f32_e32 v217, v172
	v_sub_f32_e32 v172, v176, v213
	v_mul_f32_e32 v172, 0x3fb8aa3b, v172
	v_exp_f32_e32 v218, v172
	v_sub_f32_e32 v172, v177, v213
	v_mul_f32_e32 v172, 0x3fb8aa3b, v172
	v_exp_f32_e32 v219, v172
	v_sub_f32_e32 v172, v178, v213
	v_mul_f32_e32 v172, 0x3fb8aa3b, v172
	v_exp_f32_e32 v220, v172
	v_sub_f32_e32 v172, v179, v213
	v_sub_f32_e32 v2, v180, v213
	v_mul_f32_e32 v172, 0x3fb8aa3b, v172
	v_mul_f32_e32 v2, 0x3fb8aa3b, v2
	v_exp_f32_e32 v221, v172
	v_exp_f32_e32 v2, v2
	v_add_u32_e32 v172, 0x8000, v215
	v_add_u32_e32 v173, 0x8000, v209
	v_perm_b32 v172, v172, v173, s87
	v_add_u32_e32 v173, 0x8000, v217
	v_add_u32_e32 v174, 0x8000, v216
	v_perm_b32 v173, v173, v174, s87
	v_add_u32_e32 v174, 0x8000, v219
	v_add_u32_e32 v175, 0x8000, v218
	v_perm_b32 v174, v174, v175, s87
	v_add_u32_e32 v175, 0x8000, v221
	v_add_u32_e32 v176, 0x8000, v220
	v_perm_b32 v175, v175, v176, s87
	v_pk_mul_f32 v[122:123], v[122:123], v[2:3] op_sel_hi:[1,0]
	v_pk_mul_f32 v[120:121], v[120:121], v[2:3] op_sel_hi:[1,0]
	v_pk_mul_f32 v[102:103], v[102:103], v[2:3] op_sel_hi:[1,0]
	v_pk_mul_f32 v[100:101], v[100:101], v[2:3] op_sel_hi:[1,0]
	v_pk_mul_f32 v[98:99], v[98:99], v[2:3] op_sel_hi:[1,0]
	v_pk_mul_f32 v[96:97], v[96:97], v[2:3] op_sel_hi:[1,0]
	v_pk_mul_f32 v[94:95], v[94:95], v[2:3] op_sel_hi:[1,0]
	v_pk_mul_f32 v[92:93], v[92:93], v[2:3] op_sel_hi:[1,0]
	s_waitcnt vmcnt(3)
	v_mfma_f32_16x16x32_bf16 v[120:123], v[76:79], v[172:175], v[120:123]
	v_cndmask_b32_e64 v180, 0, 1, s[8:9]
	v_cmp_ne_u32_e64 s[6:7], 1, v180
	s_waitcnt vmcnt(2)
	v_mfma_f32_16x16x32_bf16 v[100:103], v[80:83], v[172:175], v[100:103]
	s_waitcnt vmcnt(1)
	v_mfma_f32_16x16x32_bf16 v[96:99], v[84:87], v[172:175], v[96:99]
	s_waitcnt vmcnt(0)
	v_mfma_f32_16x16x32_bf16 v[92:95], v[88:91], v[172:175], v[92:95]
	v_mfma_f32_16x16x32_bf16 v[172:175], v[60:63], v[28:31], 0
	v_mfma_f32_16x16x32_bf16 v[176:179], v[68:71], v[28:31], 0
	v_mfma_f32_16x16x32_bf16 v[172:175], v[64:67], v[32:35], v[172:175]
	v_mfma_f32_16x16x32_bf16 v[176:179], v[72:75], v[32:35], v[176:179]
	s_cbranch_vccnz .LBB0_1019
	v_cmp_lt_u32_e32 vcc, s72, v0
	s_nop 4
	v_cndmask_b32_e32 v172, v245, v172, vcc
	v_cmp_lt_u32_e32 vcc, s72, v235
	s_nop 1
	v_cndmask_b32_e32 v173, v245, v173, vcc
	v_cmp_lt_u32_e32 vcc, s72, v244
	s_nop 1
	v_cndmask_b32_e32 v174, v245, v174, vcc
	v_cmp_lt_u32_e32 vcc, s72, v253
	s_nop 1
	v_cndmask_b32_e32 v175, v245, v175, vcc
	v_cmp_lt_u32_e32 vcc, s72, v252
	s_nop 1
	v_cndmask_b32_e32 v176, v245, v176, vcc
	v_cmp_lt_u32_e32 vcc, s72, v251
	s_nop 1
	v_cndmask_b32_e32 v177, v245, v177, vcc
	v_cmp_lt_u32_e32 vcc, s72, v208
	s_nop 1
	v_cndmask_b32_e32 v178, v245, v178, vcc
	v_cmp_lt_u32_e32 vcc, s72, v201
	s_nop 1
	v_cndmask_b32_e32 v179, v245, v179, vcc
.LBB0_1019:
	s_nop 5
	v_max_f32_e32 v180, v173, v173
	v_max_f32_e32 v184, v172, v172
	v_max_f32_e32 v180, v184, v180
	v_max_f32_e32 v184, v175, v175
	v_max_f32_e32 v185, v174, v174
	v_max_f32_e32 v184, v185, v184
	v_max_f32_e32 v185, v179, v179
	v_max_f32_e32 v186, v178, v178
	v_max_f32_e32 v185, v186, v185
	v_max3_f32 v185, v176, v177, v185
	v_max3_f32 v180, v180, v184, v185
	v_mov_b32_e32 v184, v180
	s_nop 1
	v_permlane16_swap_b32_e32 v184, v180
	v_mfma_f32_16x16x32_bf16 v[238:241], v[68:71], v[36:39], 0
	s_and_b64 vcc, exec, s[6:7]
	s_waitcnt lgkmcnt(0)
	v_max_f32_e32 v184, v184, v184
	v_max_f32_e32 v180, v180, v184
	v_mov_b32_e32 v184, v180
	s_nop 1
	v_permlane32_swap_b32_e32 v184, v180
	s_waitcnt lgkmcnt(0)
	v_max3_f32 v214, v181, v180, v184
	v_sub_f32_e32 v172, v172, v214
	v_mul_f32_e32 v172, 0x3fb8aa3b, v172
	v_exp_f32_e32 v210, v172
	v_sub_f32_e32 v172, v173, v214
	v_mul_f32_e32 v172, 0x3fb8aa3b, v172
	v_exp_f32_e32 v222, v172
	v_sub_f32_e32 v172, v174, v214
	v_mul_f32_e32 v172, 0x3fb8aa3b, v172
	v_exp_f32_e32 v223, v172
	v_sub_f32_e32 v172, v175, v214
	v_mul_f32_e32 v172, 0x3fb8aa3b, v172
	v_exp_f32_e32 v246, v172
	v_sub_f32_e32 v172, v176, v214
	v_mul_f32_e32 v172, 0x3fb8aa3b, v172
	v_exp_f32_e32 v247, v172
	v_sub_f32_e32 v172, v177, v214
	v_mul_f32_e32 v172, 0x3fb8aa3b, v172
	v_exp_f32_e32 v248, v172
	v_sub_f32_e32 v172, v178, v214
	v_mul_f32_e32 v172, 0x3fb8aa3b, v172
	v_exp_f32_e32 v249, v172
	v_sub_f32_e32 v172, v179, v214
	v_sub_f32_e32 v180, v181, v214
	v_mul_f32_e32 v172, 0x3fb8aa3b, v172
	v_mul_f32_e32 v180, 0x3fb8aa3b, v180
	v_exp_f32_e32 v250, v172
	v_exp_f32_e32 v180, v180
	v_add_u32_e32 v172, 0x8000, v222
	v_add_u32_e32 v173, 0x8000, v210
	v_perm_b32 v172, v172, v173, s87
	v_add_u32_e32 v173, 0x8000, v246
	v_add_u32_e32 v174, 0x8000, v223
	v_perm_b32 v173, v173, v174, s87
	v_add_u32_e32 v174, 0x8000, v248
	v_add_u32_e32 v175, 0x8000, v247
	v_perm_b32 v174, v174, v175, s87
	v_add_u32_e32 v175, 0x8000, v250
	v_add_u32_e32 v176, 0x8000, v249
	v_perm_b32 v175, v175, v176, s87
	v_pk_mul_f32 v[58:59], v[58:59], v[180:181] op_sel_hi:[1,0]
	v_pk_mul_f32 v[56:57], v[56:57], v[180:181] op_sel_hi:[1,0]
	v_pk_mul_f32 v[54:55], v[54:55], v[180:181] op_sel_hi:[1,0]
	v_pk_mul_f32 v[52:53], v[52:53], v[180:181] op_sel_hi:[1,0]
	v_pk_mul_f32 v[50:51], v[50:51], v[180:181] op_sel_hi:[1,0]
	v_pk_mul_f32 v[48:49], v[48:49], v[180:181] op_sel_hi:[1,0]
	v_pk_mul_f32 v[46:47], v[46:47], v[180:181] op_sel_hi:[1,0]
	v_pk_mul_f32 v[44:45], v[44:45], v[180:181] op_sel_hi:[1,0]
	v_mfma_f32_16x16x32_bf16 v[56:59], v[76:79], v[172:175], v[56:59]
	v_mfma_f32_16x16x32_bf16 v[52:55], v[80:83], v[172:175], v[52:55]
	v_mfma_f32_16x16x32_bf16 v[48:51], v[84:87], v[172:175], v[48:51]
	v_mfma_f32_16x16x32_bf16 v[44:47], v[88:91], v[172:175], v[44:47]
	v_mfma_f32_16x16x32_bf16 v[172:175], v[60:63], v[36:39], 0
	v_mfma_f32_16x16x32_bf16 v[176:179], v[64:67], v[40:43], v[172:175]
	v_mfma_f32_16x16x32_bf16 v[172:175], v[72:75], v[40:43], v[238:241]
	s_cbranch_vccnz .LBB0_1021
	v_cmp_lt_u32_e32 vcc, s72, v0
	s_nop 4
	v_cndmask_b32_e32 v176, v245, v176, vcc
	v_cmp_lt_u32_e32 vcc, s72, v235
	s_nop 1
	v_cndmask_b32_e32 v177, v245, v177, vcc
	v_cmp_lt_u32_e32 vcc, s72, v244
	s_nop 1
	v_cndmask_b32_e32 v178, v245, v178, vcc
	v_cmp_lt_u32_e32 vcc, s72, v253
	s_nop 1
	v_cndmask_b32_e32 v179, v245, v179, vcc
	v_cmp_lt_u32_e32 vcc, s72, v252
	s_nop 1
	v_cndmask_b32_e32 v172, v245, v172, vcc
	v_cmp_lt_u32_e32 vcc, s72, v251
	s_nop 1
	v_cndmask_b32_e32 v173, v245, v173, vcc
	v_cmp_lt_u32_e32 vcc, s72, v208
	s_nop 1
	v_cndmask_b32_e32 v174, v245, v174, vcc
	v_cmp_lt_u32_e32 vcc, s72, v201
	s_nop 1
	v_cndmask_b32_e32 v175, v245, v175, vcc
.LBB0_1021:
	s_nop 5
	v_max_f32_e32 v0, v177, v177
	v_max_f32_e32 v181, v176, v176
	v_max_f32_e32 v0, v181, v0
	v_max_f32_e32 v181, v179, v179
	v_max_f32_e32 v184, v178, v178
	v_max_f32_e32 v181, v184, v181
	v_max_f32_e32 v184, v175, v175
	v_max_f32_e32 v185, v174, v174
	v_max_f32_e32 v184, v185, v184
	v_max3_f32 v184, v172, v173, v184
	v_max3_f32 v0, v0, v181, v184
	v_mov_b32_e32 v181, v0
	s_nop 1
	v_permlane16_swap_b32_e32 v181, v0
	s_add_i32 s61, s57, 3
	s_add_i32 s6, s56, 1
	s_cmp_ge_i32 s6, s1
	s_waitcnt lgkmcnt(0)
	v_max_f32_e32 v181, v181, v181
	v_max_f32_e32 v0, v0, v181
	v_mov_b32_e32 v181, v0
	s_nop 1
	v_permlane32_swap_b32_e32 v181, v0
	s_waitcnt lgkmcnt(0)
	v_max3_f32 v181, v182, v0, v181
	v_sub_f32_e32 v172, v172, v181
	v_mul_f32_e32 v172, 0x3fb8aa3b, v172
	v_sub_f32_e32 v0, v182, v181
	v_exp_f32_e32 v182, v172
	v_sub_f32_e32 v172, v173, v181
	v_sub_f32_e32 v176, v176, v181
	v_sub_f32_e32 v177, v177, v181
	v_mul_f32_e32 v172, 0x3fb8aa3b, v172
	v_mul_f32_e32 v176, 0x3fb8aa3b, v176
	v_mul_f32_e32 v177, 0x3fb8aa3b, v177
	v_sub_f32_e32 v178, v178, v181
	v_sub_f32_e32 v179, v179, v181
	v_exp_f32_e32 v173, v172
	v_sub_f32_e32 v172, v174, v181
	v_exp_f32_e32 v176, v176
	v_exp_f32_e32 v177, v177
	v_mul_f32_e32 v178, 0x3fb8aa3b, v178
	v_mul_f32_e32 v179, 0x3fb8aa3b, v179
	v_mul_f32_e32 v172, 0x3fb8aa3b, v172
	v_exp_f32_e32 v178, v178
	v_exp_f32_e32 v179, v179
	v_exp_f32_e32 v174, v172
	v_sub_f32_e32 v172, v175, v181
	v_mul_f32_e32 v172, 0x3fb8aa3b, v172
	v_mul_f32_e32 v0, 0x3fb8aa3b, v0
	v_exp_f32_e32 v175, v172
	v_exp_f32_e32 v172, v0
	v_add_u32_e32 v0, 0x8000, v177
	v_add_u32_e32 v184, 0x8000, v176
	v_perm_b32 v238, v0, v184, s87
	v_add_u32_e32 v0, 0x8000, v179
	v_add_u32_e32 v184, 0x8000, v178
	v_perm_b32 v239, v0, v184, s87
	v_add_u32_e32 v0, 0x8000, v173
	v_add_u32_e32 v184, 0x8000, v182
	v_perm_b32 v240, v0, v184, s87
	v_add_u32_e32 v0, 0x8000, v175
	v_add_u32_e32 v184, 0x8000, v174
	v_perm_b32 v241, v0, v184, s87
	v_pk_mul_f32 v[18:19], v[18:19], v[172:173] op_sel_hi:[1,0]
	v_pk_mul_f32 v[16:17], v[16:17], v[172:173] op_sel_hi:[1,0]
	v_pk_mul_f32 v[14:15], v[14:15], v[172:173] op_sel_hi:[1,0]
	v_pk_mul_f32 v[12:13], v[12:13], v[172:173] op_sel_hi:[1,0]
	v_pk_mul_f32 v[10:11], v[10:11], v[172:173] op_sel_hi:[1,0]
	v_pk_mul_f32 v[8:9], v[8:9], v[172:173] op_sel_hi:[1,0]
	v_pk_mul_f32 v[6:7], v[6:7], v[172:173] op_sel_hi:[1,0]
	v_pk_mul_f32 v[4:5], v[4:5], v[172:173] op_sel_hi:[1,0]
	v_mfma_f32_16x16x32_bf16 v[16:19], v[76:79], v[238:241], v[16:19]
	v_mfma_f32_16x16x32_bf16 v[12:15], v[80:83], v[238:241], v[12:15]
	v_mfma_f32_16x16x32_bf16 v[8:11], v[84:87], v[238:241], v[8:11]
	v_mfma_f32_16x16x32_bf16 v[4:7], v[88:91], v[238:241], v[4:7]
	s_cbranch_scc1 .LBB0_1027
	s_cmp_ge_i32 s6, s0
	s_mov_b64 s[10:11], -1
	s_cbranch_scc0 .LBB0_1024
	s_add_i32 s6, s3, s56
	s_add_i32 s8, s6, 1
	s_add_i32 s6, s33, s2
	s_add_i32 s44, s6, 0x60
	s_lshl_b64 s[6:7], s[44:45], 8
	s_add_u32 s6, s30, s6
	s_addc_u32 s7, s31, s7
	s_mov_b64 s[10:11], 0
	s_mov_b32 s44, s8

.LBB0_1030:
	v_max_f32_e32 v2, v177, v177
	v_max_f32_e32 v180, v176, v176
	v_max_f32_e32 v2, v180, v2
	v_max_f32_e32 v180, v179, v179
	v_max_f32_e32 v182, v178, v178
	v_max_f32_e32 v180, v182, v180
	v_max_f32_e32 v182, v175, v175
	v_max_f32_e32 v184, v174, v174
	v_max_f32_e32 v182, v184, v182
	v_max3_f32 v182, v172, v173, v182
	v_max3_f32 v2, v2, v180, v182
	v_mov_b32_e32 v180, v2
	s_nop 1
	v_permlane16_swap_b32_e32 v180, v2
	s_xor_b64 s[8:9], s[46:47], -1
	s_andn2_b64 vcc, exec, s[8:9]
	s_waitcnt lgkmcnt(0)
	v_max_f32_e32 v180, v180, v180
	v_max_f32_e32 v2, v2, v180
	v_mov_b32_e32 v180, v2
	s_nop 1
	v_permlane32_swap_b32_e32 v180, v2
	s_waitcnt lgkmcnt(0)
	v_max3_f32 v202, v213, v2, v180
	v_sub_f32_e32 v176, v176, v202
	v_mul_f32_e32 v176, 0x3fb8aa3b, v176
	v_exp_f32_e32 v211, v176
	v_sub_f32_e32 v176, v177, v202
	v_sub_f32_e32 v172, v172, v202
	v_mul_f32_e32 v176, 0x3fb8aa3b, v176
	v_mul_f32_e32 v172, 0x3fb8aa3b, v172
	v_exp_f32_e32 v212, v176
	v_sub_f32_e32 v176, v178, v202
	v_exp_f32_e32 v217, v172
	v_sub_f32_e32 v172, v173, v202
	v_mul_f32_e32 v176, 0x3fb8aa3b, v176
	v_mul_f32_e32 v172, 0x3fb8aa3b, v172
	v_exp_f32_e32 v215, v176
	v_sub_f32_e32 v176, v179, v202
	v_exp_f32_e32 v218, v172
	v_sub_f32_e32 v172, v174, v202
	v_mul_f32_e32 v176, 0x3fb8aa3b, v176
	v_mul_f32_e32 v172, 0x3fb8aa3b, v172
	v_exp_f32_e32 v216, v176
	v_exp_f32_e32 v219, v172
	v_sub_f32_e32 v172, v175, v202
	v_sub_f32_e32 v2, v213, v202
	v_mul_f32_e32 v172, 0x3fb8aa3b, v172
	v_mul_f32_e32 v2, 0x3fb8aa3b, v2
	v_exp_f32_e32 v220, v172
	v_exp_f32_e32 v2, v2
	v_add_u32_e32 v172, 0x8000, v212
	v_add_u32_e32 v173, 0x8000, v211
	v_perm_b32 v172, v172, v173, s87
	v_add_u32_e32 v173, 0x8000, v216
	v_add_u32_e32 v174, 0x8000, v215
	v_perm_b32 v173, v173, v174, s87
	v_add_u32_e32 v174, 0x8000, v218
	v_add_u32_e32 v175, 0x8000, v217
	v_perm_b32 v174, v174, v175, s87
	v_add_u32_e32 v175, 0x8000, v220
	v_add_u32_e32 v176, 0x8000, v219
	v_perm_b32 v175, v175, v176, s87
	v_pk_mul_f32 v[122:123], v[122:123], v[2:3] op_sel_hi:[1,0]
	v_pk_mul_f32 v[120:121], v[120:121], v[2:3] op_sel_hi:[1,0]
	v_pk_mul_f32 v[102:103], v[102:103], v[2:3] op_sel_hi:[1,0]
	v_pk_mul_f32 v[100:101], v[100:101], v[2:3] op_sel_hi:[1,0]
	v_pk_mul_f32 v[98:99], v[98:99], v[2:3] op_sel_hi:[1,0]
	v_pk_mul_f32 v[96:97], v[96:97], v[2:3] op_sel_hi:[1,0]
	v_pk_mul_f32 v[94:95], v[94:95], v[2:3] op_sel_hi:[1,0]
	v_pk_mul_f32 v[92:93], v[92:93], v[2:3] op_sel_hi:[1,0]
	v_mfma_f32_16x16x32_bf16 v[120:123], v[124:127], v[172:175], v[120:123]
	v_cndmask_b32_e64 v180, 0, 1, s[8:9]
	v_cmp_ne_u32_e64 s[6:7], 1, v180
	v_mfma_f32_16x16x32_bf16 v[100:103], v[128:131], v[172:175], v[100:103]
	v_mfma_f32_16x16x32_bf16 v[96:99], v[132:135], v[172:175], v[96:99]
	v_mfma_f32_16x16x32_bf16 v[92:95], v[136:139], v[172:175], v[92:95]
	v_mfma_f32_16x16x32_bf16 v[172:175], v[104:107], v[28:31], 0
	v_mfma_f32_16x16x32_bf16 v[176:179], v[112:115], v[28:31], 0
	v_mfma_f32_16x16x32_bf16 v[172:175], v[108:111], v[32:35], v[172:175]
	v_mfma_f32_16x16x32_bf16 v[176:179], v[116:119], v[32:35], v[176:179]
	s_cbranch_vccnz .LBB0_1032
	v_cmp_lt_u32_e32 vcc, s72, v0
	s_nop 4
	v_cndmask_b32_e32 v172, v245, v172, vcc
	v_cmp_lt_u32_e32 vcc, s72, v244
	s_nop 1
	v_cndmask_b32_e32 v173, v245, v173, vcc
	v_cmp_lt_u32_e32 vcc, s72, v252
	s_nop 1
	v_cndmask_b32_e32 v174, v245, v174, vcc
	v_cmp_lt_u32_e32 vcc, s72, v251
	s_nop 1
	v_cndmask_b32_e32 v175, v245, v175, vcc
	v_cmp_lt_u32_e32 vcc, s72, v249
	s_nop 1
	v_cndmask_b32_e32 v176, v245, v176, vcc
	v_cmp_lt_u32_e32 vcc, s72, v248
	s_nop 1
	v_cndmask_b32_e32 v177, v245, v177, vcc
	v_cmp_lt_u32_e32 vcc, s72, v246
	s_nop 1
	v_cndmask_b32_e32 v178, v245, v178, vcc
	v_cmp_lt_u32_e32 vcc, s72, v201
	s_nop 1
	v_cndmask_b32_e32 v179, v245, v179, vcc
.LBB0_1032:
	s_nop 5
	v_max_f32_e32 v180, v173, v173
	v_max_f32_e32 v182, v172, v172
	v_max_f32_e32 v180, v182, v180
	v_max_f32_e32 v182, v175, v175
	v_max_f32_e32 v184, v174, v174
	v_max_f32_e32 v182, v184, v182
	v_max_f32_e32 v184, v179, v179
	v_max_f32_e32 v185, v178, v178
	v_max_f32_e32 v184, v185, v184
	v_max3_f32 v184, v176, v177, v184
	v_max3_f32 v180, v180, v182, v184
	v_mov_b32_e32 v182, v180
	s_nop 1
	v_permlane16_swap_b32_e32 v182, v180
	v_mfma_f32_16x16x32_bf16 v[238:241], v[112:115], v[36:39], 0
	s_and_b64 vcc, exec, s[6:7]
	s_waitcnt lgkmcnt(0)
	v_max_f32_e32 v182, v182, v182
	v_max_f32_e32 v180, v180, v182
	v_mov_b32_e32 v182, v180
	s_nop 1
	v_permlane32_swap_b32_e32 v182, v180
	s_waitcnt lgkmcnt(0)
	v_max3_f32 v182, v214, v180, v182
	v_sub_f32_e32 v172, v172, v182
	v_mul_f32_e32 v172, 0x3fb8aa3b, v172
	v_sub_f32_e32 v180, v214, v182
	v_exp_f32_e32 v214, v172
	v_sub_f32_e32 v172, v173, v182
	v_mul_f32_e32 v172, 0x3fb8aa3b, v172
	v_exp_f32_e32 v221, v172
	v_sub_f32_e32 v172, v174, v182
	v_mul_f32_e32 v172, 0x3fb8aa3b, v172
	v_exp_f32_e32 v222, v172
	v_sub_f32_e32 v172, v175, v182
	v_mul_f32_e32 v172, 0x3fb8aa3b, v172
	v_exp_f32_e32 v223, v172
	v_sub_f32_e32 v172, v176, v182
	v_mul_f32_e32 v172, 0x3fb8aa3b, v172
	v_exp_f32_e32 v247, v172
	v_sub_f32_e32 v172, v177, v182
	v_mul_f32_e32 v172, 0x3fb8aa3b, v172
	v_exp_f32_e32 v250, v172
	v_sub_f32_e32 v172, v178, v182
	v_mul_f32_e32 v172, 0x3fb8aa3b, v172
	v_exp_f32_e32 v253, v172
	v_sub_f32_e32 v172, v179, v182
	v_mul_f32_e32 v172, 0x3fb8aa3b, v172
	v_mul_f32_e32 v180, 0x3fb8aa3b, v180
	v_exp_f32_e32 v235, v172
	v_exp_f32_e32 v180, v180
	v_add_u32_e32 v172, 0x8000, v221
	v_add_u32_e32 v173, 0x8000, v214
	v_perm_b32 v172, v172, v173, s87
	v_add_u32_e32 v173, 0x8000, v223
	v_add_u32_e32 v174, 0x8000, v222
	v_perm_b32 v173, v173, v174, s87
	v_add_u32_e32 v174, 0x8000, v250
	v_add_u32_e32 v175, 0x8000, v247
	v_perm_b32 v174, v174, v175, s87
	v_add_u32_e32 v175, 0x8000, v235
	v_add_u32_e32 v176, 0x8000, v253
	v_perm_b32 v175, v175, v176, s87
	v_pk_mul_f32 v[58:59], v[58:59], v[180:181] op_sel_hi:[1,0]
	v_pk_mul_f32 v[56:57], v[56:57], v[180:181] op_sel_hi:[1,0]
	v_pk_mul_f32 v[54:55], v[54:55], v[180:181] op_sel_hi:[1,0]
	v_pk_mul_f32 v[52:53], v[52:53], v[180:181] op_sel_hi:[1,0]
	v_pk_mul_f32 v[50:51], v[50:51], v[180:181] op_sel_hi:[1,0]
	v_pk_mul_f32 v[48:49], v[48:49], v[180:181] op_sel_hi:[1,0]
	v_pk_mul_f32 v[46:47], v[46:47], v[180:181] op_sel_hi:[1,0]
	v_pk_mul_f32 v[44:45], v[44:45], v[180:181] op_sel_hi:[1,0]
	v_mfma_f32_16x16x32_bf16 v[56:59], v[124:127], v[172:175], v[56:59]
	v_mfma_f32_16x16x32_bf16 v[52:55], v[128:131], v[172:175], v[52:55]
	v_mfma_f32_16x16x32_bf16 v[48:51], v[132:135], v[172:175], v[48:51]
	v_mfma_f32_16x16x32_bf16 v[44:47], v[136:139], v[172:175], v[44:47]
	v_mfma_f32_16x16x32_bf16 v[172:175], v[104:107], v[36:39], 0
	v_mfma_f32_16x16x32_bf16 v[176:179], v[108:111], v[40:43], v[172:175]
	v_mfma_f32_16x16x32_bf16 v[172:175], v[116:119], v[40:43], v[238:241]
	s_cbranch_vccnz .LBB0_1034
	v_cmp_lt_u32_e32 vcc, s72, v0
	s_nop 4
	v_cndmask_b32_e32 v176, v245, v176, vcc
	v_cmp_lt_u32_e32 vcc, s72, v244
	s_nop 1
	v_cndmask_b32_e32 v177, v245, v177, vcc
	v_cmp_lt_u32_e32 vcc, s72, v252
	s_nop 1
	v_cndmask_b32_e32 v178, v245, v178, vcc
	v_cmp_lt_u32_e32 vcc, s72, v251
	s_nop 1
	v_cndmask_b32_e32 v179, v245, v179, vcc
	v_cmp_lt_u32_e32 vcc, s72, v249
	s_nop 1
	v_cndmask_b32_e32 v172, v245, v172, vcc
	v_cmp_lt_u32_e32 vcc, s72, v248
	s_nop 1
	v_cndmask_b32_e32 v173, v245, v173, vcc
	v_cmp_lt_u32_e32 vcc, s72, v246
	s_nop 1
	v_cndmask_b32_e32 v174, v245, v174, vcc
	v_cmp_lt_u32_e32 vcc, s72, v201
	s_nop 1
	v_cndmask_b32_e32 v175, v245, v175, vcc
.LBB0_1034:
	s_nop 5
	v_max_f32_e32 v0, v177, v177
	v_max_f32_e32 v184, v176, v176
	v_max_f32_e32 v0, v184, v0
	v_max_f32_e32 v184, v179, v179
	v_max_f32_e32 v185, v178, v178
	v_max_f32_e32 v184, v185, v184
	v_max_f32_e32 v185, v175, v175
	v_max_f32_e32 v186, v174, v174
	v_max_f32_e32 v185, v186, v185
	v_max3_f32 v185, v172, v173, v185
	v_max3_f32 v0, v0, v184, v185
	v_mov_b32_e32 v184, v0
	s_nop 1
	v_permlane16_swap_b32_e32 v184, v0
	s_add_i32 s6, s56, 2
	s_cmp_ge_i32 s6, s1
	s_waitcnt lgkmcnt(0)
	v_max_f32_e32 v184, v184, v184
	v_max_f32_e32 v0, v0, v184
	v_mov_b32_e32 v184, v0
	s_nop 1
	v_permlane32_swap_b32_e32 v184, v0
	s_waitcnt lgkmcnt(0)
	v_max3_f32 v213, v181, v0, v184
	v_sub_f32_e32 v172, v172, v213
	v_mul_f32_e32 v172, 0x3fb8aa3b, v172
	v_sub_f32_e32 v0, v181, v213
	v_exp_f32_e32 v181, v172
	v_sub_f32_e32 v172, v173, v213
	v_sub_f32_e32 v176, v176, v213
	v_sub_f32_e32 v177, v177, v213
	v_mul_f32_e32 v172, 0x3fb8aa3b, v172
	v_mul_f32_e32 v176, 0x3fb8aa3b, v176
	v_mul_f32_e32 v177, 0x3fb8aa3b, v177
	v_sub_f32_e32 v178, v178, v213
	v_sub_f32_e32 v179, v179, v213
	v_exp_f32_e32 v173, v172
	v_sub_f32_e32 v172, v174, v213
	v_exp_f32_e32 v176, v176
	v_exp_f32_e32 v177, v177
	v_mul_f32_e32 v178, 0x3fb8aa3b, v178
	v_mul_f32_e32 v179, 0x3fb8aa3b, v179
	v_mul_f32_e32 v172, 0x3fb8aa3b, v172
	v_exp_f32_e32 v178, v178
	v_exp_f32_e32 v179, v179
	v_exp_f32_e32 v174, v172
	v_sub_f32_e32 v172, v175, v213
	v_mul_f32_e32 v172, 0x3fb8aa3b, v172
	v_mul_f32_e32 v0, 0x3fb8aa3b, v0
	v_exp_f32_e32 v175, v172
	v_exp_f32_e32 v172, v0
	v_add_u32_e32 v0, 0x8000, v177
	v_add_u32_e32 v184, 0x8000, v176
	v_perm_b32 v238, v0, v184, s87
	v_add_u32_e32 v0, 0x8000, v179
	v_add_u32_e32 v184, 0x8000, v178
	v_perm_b32 v239, v0, v184, s87
	v_add_u32_e32 v0, 0x8000, v173
	v_add_u32_e32 v184, 0x8000, v181
	v_perm_b32 v240, v0, v184, s87
	v_add_u32_e32 v0, 0x8000, v175
	v_add_u32_e32 v184, 0x8000, v174
	v_perm_b32 v241, v0, v184, s87
	v_pk_mul_f32 v[18:19], v[18:19], v[172:173] op_sel_hi:[1,0]
	v_pk_mul_f32 v[16:17], v[16:17], v[172:173] op_sel_hi:[1,0]
	v_pk_mul_f32 v[14:15], v[14:15], v[172:173] op_sel_hi:[1,0]
	v_pk_mul_f32 v[12:13], v[12:13], v[172:173] op_sel_hi:[1,0]
	v_pk_mul_f32 v[10:11], v[10:11], v[172:173] op_sel_hi:[1,0]
	v_pk_mul_f32 v[8:9], v[8:9], v[172:173] op_sel_hi:[1,0]
	v_pk_mul_f32 v[6:7], v[6:7], v[172:173] op_sel_hi:[1,0]
	v_pk_mul_f32 v[4:5], v[4:5], v[172:173] op_sel_hi:[1,0]
	v_mfma_f32_16x16x32_bf16 v[16:19], v[124:127], v[238:241], v[16:19]
	v_mfma_f32_16x16x32_bf16 v[12:15], v[128:131], v[238:241], v[12:15]
	v_mfma_f32_16x16x32_bf16 v[8:11], v[132:135], v[238:241], v[8:11]
	v_mfma_f32_16x16x32_bf16 v[4:7], v[136:139], v[238:241], v[4:7]
	s_cbranch_scc1 .LBB0_1040
	s_cmp_lt_i32 s6, s0
	s_mov_b64 s[10:11], -1
	s_cbranch_scc1 .LBB0_1037
	s_add_i32 s6, s3, s56
	s_add_i32 s8, s6, 2
	s_add_i32 s6, s33, s2
	s_add_i32 s44, s6, 0x80
	s_lshl_b64 s[6:7], s[44:45], 8
	s_add_u32 s6, s30, s6
	s_addc_u32 s7, s31, s7
	s_mov_b64 s[10:11], 0
	s_mov_b32 s44, s8

.LBB0_1046:
	v_max_f32_e32 v2, v177, v177
	v_max_f32_e32 v3, v176, v176
	v_max_f32_e32 v2, v3, v2
	v_max_f32_e32 v3, v179, v179
	v_max_f32_e32 v180, v178, v178
	v_max_f32_e32 v3, v180, v3
	v_max_f32_e32 v180, v175, v175
	v_max_f32_e32 v181, v174, v174
	v_max_f32_e32 v180, v181, v180
	v_max3_f32 v180, v172, v173, v180
	v_max3_f32 v2, v2, v3, v180
	v_mov_b32_e32 v3, v2
	s_nop 1
	v_permlane16_swap_b32_e32 v3, v2
	s_xor_b64 s[8:9], s[46:47], -1
	v_cndmask_b32_e64 v181, 0, 1, s[8:9]
	v_cmp_ne_u32_e64 s[6:7], 1, v181
	s_andn2_b64 vcc, exec, s[8:9]
	s_waitcnt lgkmcnt(0)
	v_max_f32_e32 v3, v3, v3
	v_max_f32_e32 v2, v2, v3
	v_mov_b32_e32 v3, v2
	s_nop 1
	v_permlane32_swap_b32_e32 v3, v2
	s_waitcnt lgkmcnt(0)
	v_max3_f32 v180, v202, v2, v3
	v_sub_f32_e32 v3, v176, v180
	v_sub_f32_e32 v176, v177, v180
	v_sub_f32_e32 v172, v172, v180
	v_mul_f32_e32 v176, 0x3fb8aa3b, v176
	v_mul_f32_e32 v172, 0x3fb8aa3b, v172
	v_exp_f32_e32 v212, v176
	v_sub_f32_e32 v176, v178, v180
	v_exp_f32_e32 v216, v172
	v_sub_f32_e32 v172, v173, v180
	v_mul_f32_e32 v176, 0x3fb8aa3b, v176
	v_mul_f32_e32 v172, 0x3fb8aa3b, v172
	v_mul_f32_e32 v3, 0x3fb8aa3b, v3
	v_exp_f32_e32 v214, v176
	v_sub_f32_e32 v176, v179, v180
	v_exp_f32_e32 v217, v172
	v_sub_f32_e32 v172, v174, v180
	v_exp_f32_e32 v3, v3
	v_mul_f32_e32 v176, 0x3fb8aa3b, v176
	v_mul_f32_e32 v172, 0x3fb8aa3b, v172
	v_exp_f32_e32 v215, v176
	v_exp_f32_e32 v218, v172
	v_sub_f32_e32 v172, v175, v180
	v_sub_f32_e32 v2, v202, v180
	v_mul_f32_e32 v172, 0x3fb8aa3b, v172
	v_mul_f32_e32 v2, 0x3fb8aa3b, v2
	v_exp_f32_e32 v219, v172
	v_exp_f32_e32 v2, v2
	v_add_u32_e32 v172, 0x8000, v212
	v_add_u32_e32 v173, 0x8000, v3
	v_perm_b32 v172, v172, v173, s87
	v_add_u32_e32 v173, 0x8000, v215
	v_add_u32_e32 v174, 0x8000, v214
	v_perm_b32 v173, v173, v174, s87
	v_add_u32_e32 v174, 0x8000, v217
	v_add_u32_e32 v175, 0x8000, v216
	v_perm_b32 v174, v174, v175, s87
	v_add_u32_e32 v175, 0x8000, v219
	v_add_u32_e32 v176, 0x8000, v218
	v_perm_b32 v175, v175, v176, s87
	v_pk_mul_f32 v[122:123], v[122:123], v[2:3] op_sel_hi:[1,0]
	v_pk_mul_f32 v[120:121], v[120:121], v[2:3] op_sel_hi:[1,0]
	v_pk_mul_f32 v[102:103], v[102:103], v[2:3] op_sel_hi:[1,0]
	v_pk_mul_f32 v[100:101], v[100:101], v[2:3] op_sel_hi:[1,0]
	v_pk_mul_f32 v[98:99], v[98:99], v[2:3] op_sel_hi:[1,0]
	v_pk_mul_f32 v[96:97], v[96:97], v[2:3] op_sel_hi:[1,0]
	v_pk_mul_f32 v[94:95], v[94:95], v[2:3] op_sel_hi:[1,0]
	v_pk_mul_f32 v[92:93], v[92:93], v[2:3] op_sel_hi:[1,0]
	v_mfma_f32_16x16x32_bf16 v[120:123], v[156:159], v[172:175], v[120:123]
	v_mfma_f32_16x16x32_bf16 v[100:103], v[160:163], v[172:175], v[100:103]
	v_mfma_f32_16x16x32_bf16 v[96:99], v[164:167], v[172:175], v[96:99]
	v_mfma_f32_16x16x32_bf16 v[92:95], v[168:171], v[172:175], v[92:95]
	v_mfma_f32_16x16x32_bf16 v[172:175], v[140:143], v[28:31], 0
	v_mfma_f32_16x16x32_bf16 v[176:179], v[148:151], v[28:31], 0
	v_mfma_f32_16x16x32_bf16 v[172:175], v[144:147], v[32:35], v[172:175]
	v_mfma_f32_16x16x32_bf16 v[176:179], v[152:155], v[32:35], v[176:179]
	s_cbranch_vccnz .LBB0_1048
	v_cmp_lt_u32_e32 vcc, s72, v0
	s_nop 4
	v_cndmask_b32_e32 v172, v245, v172, vcc
	v_cmp_lt_u32_e32 vcc, s72, v253
	s_nop 1
	v_cndmask_b32_e32 v173, v245, v173, vcc
	v_cmp_lt_u32_e32 vcc, s72, v251
	s_nop 1
	v_cndmask_b32_e32 v174, v245, v174, vcc
	v_cmp_lt_u32_e32 vcc, s72, v250
	s_nop 1
	v_cndmask_b32_e32 v175, v245, v175, vcc
	v_cmp_lt_u32_e32 vcc, s72, v248
	s_nop 1
	v_cndmask_b32_e32 v176, v245, v176, vcc
	v_cmp_lt_u32_e32 vcc, s72, v247
	s_nop 1
	v_cndmask_b32_e32 v177, v245, v177, vcc
	v_cmp_lt_u32_e32 vcc, s72, v223
	s_nop 1
	v_cndmask_b32_e32 v178, v245, v178, vcc
	v_cmp_lt_u32_e32 vcc, s72, v201
	s_nop 1
	v_cndmask_b32_e32 v179, v245, v179, vcc
.LBB0_1048:
	s_nop 5
	v_max_f32_e32 v181, v173, v173
	v_max_f32_e32 v184, v172, v172
	v_max_f32_e32 v181, v184, v181
	v_max_f32_e32 v184, v175, v175
	v_max_f32_e32 v185, v174, v174
	v_max_f32_e32 v184, v185, v184
	v_max_f32_e32 v185, v179, v179
	v_max_f32_e32 v186, v178, v178
	v_max_f32_e32 v185, v186, v185
	v_max3_f32 v185, v176, v177, v185
	v_max3_f32 v181, v181, v184, v185
	v_mov_b32_e32 v184, v181
	s_nop 1
	v_permlane16_swap_b32_e32 v184, v181
	v_mfma_f32_16x16x32_bf16 v[238:241], v[148:151], v[36:39], 0
	s_and_b64 vcc, exec, s[6:7]
	s_waitcnt lgkmcnt(0)
	v_max_f32_e32 v184, v184, v184
	v_max_f32_e32 v181, v181, v184
	v_mov_b32_e32 v184, v181
	s_nop 1
	v_permlane32_swap_b32_e32 v184, v181
	s_waitcnt lgkmcnt(0)
	v_max3_f32 v181, v182, v181, v184
	v_sub_f32_e32 v172, v172, v181
	v_mul_f32_e32 v172, 0x3fb8aa3b, v172
	v_exp_f32_e32 v211, v172
	v_sub_f32_e32 v172, v173, v181
	v_mul_f32_e32 v172, 0x3fb8aa3b, v172
	v_exp_f32_e32 v220, v172
	v_sub_f32_e32 v172, v174, v181
	v_mul_f32_e32 v172, 0x3fb8aa3b, v172
	v_exp_f32_e32 v221, v172
	v_sub_f32_e32 v172, v175, v181
	v_mul_f32_e32 v172, 0x3fb8aa3b, v172
	v_exp_f32_e32 v222, v172
	v_sub_f32_e32 v172, v176, v181
	v_mul_f32_e32 v172, 0x3fb8aa3b, v172
	v_exp_f32_e32 v246, v172
	v_sub_f32_e32 v172, v177, v181
	v_mul_f32_e32 v172, 0x3fb8aa3b, v172
	v_exp_f32_e32 v249, v172
	v_sub_f32_e32 v172, v178, v181
	v_mul_f32_e32 v172, 0x3fb8aa3b, v172
	v_exp_f32_e32 v252, v172
	v_sub_f32_e32 v172, v179, v181
	v_sub_f32_e32 v182, v182, v181
	v_mul_f32_e32 v172, 0x3fb8aa3b, v172
	v_mul_f32_e32 v182, 0x3fb8aa3b, v182
	v_exp_f32_e32 v235, v172
	v_exp_f32_e32 v202, v182
	v_add_u32_e32 v172, 0x8000, v220
	v_add_u32_e32 v173, 0x8000, v211
	v_perm_b32 v172, v172, v173, s87
	v_add_u32_e32 v173, 0x8000, v222
	v_add_u32_e32 v174, 0x8000, v221
	v_perm_b32 v173, v173, v174, s87
	v_add_u32_e32 v174, 0x8000, v249
	v_add_u32_e32 v175, 0x8000, v246
	v_perm_b32 v174, v174, v175, s87
	v_add_u32_e32 v175, 0x8000, v235
	v_add_u32_e32 v176, 0x8000, v252
	v_perm_b32 v175, v175, v176, s87
	v_pk_mul_f32 v[58:59], v[58:59], v[202:203] op_sel_hi:[1,0]
	v_pk_mul_f32 v[56:57], v[56:57], v[202:203] op_sel_hi:[1,0]
	v_pk_mul_f32 v[54:55], v[54:55], v[202:203] op_sel_hi:[1,0]
	v_pk_mul_f32 v[52:53], v[52:53], v[202:203] op_sel_hi:[1,0]
	v_pk_mul_f32 v[50:51], v[50:51], v[202:203] op_sel_hi:[1,0]
	v_pk_mul_f32 v[48:49], v[48:49], v[202:203] op_sel_hi:[1,0]
	v_pk_mul_f32 v[46:47], v[46:47], v[202:203] op_sel_hi:[1,0]
	v_pk_mul_f32 v[44:45], v[44:45], v[202:203] op_sel_hi:[1,0]
	v_mfma_f32_16x16x32_bf16 v[56:59], v[156:159], v[172:175], v[56:59]
	v_mfma_f32_16x16x32_bf16 v[52:55], v[160:163], v[172:175], v[52:55]
	v_mfma_f32_16x16x32_bf16 v[48:51], v[164:167], v[172:175], v[48:51]
	v_mfma_f32_16x16x32_bf16 v[44:47], v[168:171], v[172:175], v[44:47]
	v_mfma_f32_16x16x32_bf16 v[172:175], v[140:143], v[36:39], 0
	v_mfma_f32_16x16x32_bf16 v[176:179], v[144:147], v[40:43], v[172:175]
	v_mfma_f32_16x16x32_bf16 v[172:175], v[152:155], v[40:43], v[238:241]
	s_cbranch_vccnz .LBB0_1050
	v_cmp_lt_u32_e32 vcc, s72, v0
	s_nop 4
	v_cndmask_b32_e32 v176, v245, v176, vcc
	v_cmp_lt_u32_e32 vcc, s72, v253
	s_nop 1
	v_cndmask_b32_e32 v177, v245, v177, vcc
	v_cmp_lt_u32_e32 vcc, s72, v251
	s_nop 1
	v_cndmask_b32_e32 v178, v245, v178, vcc
	v_cmp_lt_u32_e32 vcc, s72, v250
	s_nop 1
	v_cndmask_b32_e32 v179, v245, v179, vcc
	v_cmp_lt_u32_e32 vcc, s72, v248
	s_nop 1
	v_cndmask_b32_e32 v172, v245, v172, vcc
	v_cmp_lt_u32_e32 vcc, s72, v247
	s_nop 1
	v_cndmask_b32_e32 v173, v245, v173, vcc
	v_cmp_lt_u32_e32 vcc, s72, v223
	s_nop 1
	v_cndmask_b32_e32 v174, v245, v174, vcc
	v_cmp_lt_u32_e32 vcc, s72, v201
	s_nop 1
	v_cndmask_b32_e32 v175, v245, v175, vcc
.LBB0_1050:
	s_nop 5
	v_max_f32_e32 v0, v177, v177
	v_max_f32_e32 v182, v176, v176
	v_max_f32_e32 v0, v182, v0
	v_max_f32_e32 v182, v179, v179
	v_max_f32_e32 v184, v178, v178
	v_max_f32_e32 v182, v184, v182
	v_max_f32_e32 v184, v175, v175
	v_max_f32_e32 v185, v174, v174
	v_max_f32_e32 v184, v185, v184
	v_max3_f32 v184, v172, v173, v184
	v_max3_f32 v0, v0, v182, v184
	v_mov_b32_e32 v182, v0
	s_nop 1
	v_permlane16_swap_b32_e32 v182, v0
	s_add_i32 s12, s56, 3
	s_cmp_ge_i32 s12, s1
	s_waitcnt lgkmcnt(0)
	v_max_f32_e32 v182, v182, v182
	v_max_f32_e32 v0, v0, v182
	v_mov_b32_e32 v182, v0
	s_nop 1
	v_permlane32_swap_b32_e32 v182, v0
	s_waitcnt lgkmcnt(0)
	v_max3_f32 v182, v213, v0, v182
	v_sub_f32_e32 v172, v172, v182
	v_mul_f32_e32 v172, 0x3fb8aa3b, v172
	v_sub_f32_e32 v0, v213, v182
	v_exp_f32_e32 v213, v172
	v_sub_f32_e32 v172, v173, v182
	v_sub_f32_e32 v176, v176, v182
	v_sub_f32_e32 v177, v177, v182
	v_mul_f32_e32 v172, 0x3fb8aa3b, v172
	v_mul_f32_e32 v176, 0x3fb8aa3b, v176
	v_mul_f32_e32 v177, 0x3fb8aa3b, v177
	v_sub_f32_e32 v178, v178, v182
	v_sub_f32_e32 v179, v179, v182
	v_exp_f32_e32 v173, v172
	v_sub_f32_e32 v172, v174, v182
	v_exp_f32_e32 v176, v176
	v_exp_f32_e32 v177, v177
	v_mul_f32_e32 v178, 0x3fb8aa3b, v178
	v_mul_f32_e32 v179, 0x3fb8aa3b, v179
	v_mul_f32_e32 v172, 0x3fb8aa3b, v172
	v_exp_f32_e32 v178, v178
	v_exp_f32_e32 v179, v179
	v_exp_f32_e32 v174, v172
	v_sub_f32_e32 v172, v175, v182
	v_mul_f32_e32 v172, 0x3fb8aa3b, v172
	v_mul_f32_e32 v0, 0x3fb8aa3b, v0
	v_exp_f32_e32 v175, v172
	v_exp_f32_e32 v172, v0
	v_add_u32_e32 v0, 0x8000, v177
	v_add_u32_e32 v184, 0x8000, v176
	v_perm_b32 v238, v0, v184, s87
	v_add_u32_e32 v0, 0x8000, v179
	v_add_u32_e32 v184, 0x8000, v178
	v_perm_b32 v239, v0, v184, s87
	v_add_u32_e32 v0, 0x8000, v173
	v_add_u32_e32 v184, 0x8000, v213
	v_perm_b32 v240, v0, v184, s87
	v_add_u32_e32 v0, 0x8000, v175
	v_add_u32_e32 v184, 0x8000, v174
	v_perm_b32 v241, v0, v184, s87
	v_pk_mul_f32 v[18:19], v[18:19], v[172:173] op_sel_hi:[1,0]
	v_pk_mul_f32 v[16:17], v[16:17], v[172:173] op_sel_hi:[1,0]
	v_pk_mul_f32 v[14:15], v[14:15], v[172:173] op_sel_hi:[1,0]
	v_pk_mul_f32 v[12:13], v[12:13], v[172:173] op_sel_hi:[1,0]
	v_pk_mul_f32 v[10:11], v[10:11], v[172:173] op_sel_hi:[1,0]
	v_pk_mul_f32 v[8:9], v[8:9], v[172:173] op_sel_hi:[1,0]
	v_pk_mul_f32 v[6:7], v[6:7], v[172:173] op_sel_hi:[1,0]
	v_pk_mul_f32 v[4:5], v[4:5], v[172:173] op_sel_hi:[1,0]
	v_mfma_f32_16x16x32_bf16 v[16:19], v[156:159], v[238:241], v[16:19]
	v_mfma_f32_16x16x32_bf16 v[12:15], v[160:163], v[238:241], v[12:15]
	v_mfma_f32_16x16x32_bf16 v[8:11], v[164:167], v[238:241], v[8:11]
	v_mfma_f32_16x16x32_bf16 v[4:7], v[168:171], v[238:241], v[4:7]
	s_cbranch_scc1 .LBB0_1056
	s_cmp_lt_i32 s12, s0
	s_mov_b64 s[10:11], -1
	s_cbranch_scc1 .LBB0_1053
	s_add_i32 s6, s3, s56
	s_add_i32 s8, s6, 3
	s_add_i32 s6, s33, s2
	s_add_i32 s44, s6, 0xa0
	s_lshl_b64 s[6:7], s[44:45], 8
	s_add_u32 s6, s30, s6
	s_addc_u32 s7, s31, s7
	s_mov_b64 s[10:11], 0
	s_mov_b32 s44, s8

.LBB0_1062:
	s_or_b64 exec, exec, s[12:13]
	v_add_f32_e32 v94, 0, v153
	v_add_f32_e32 v94, v155, v94
	v_add_f32_e32 v11, 0, v11
	v_add_f32_e32 v94, v157, v94
	v_add_f32_e32 v11, v164, v11
	v_add_f32_e32 v94, v159, v94
	v_add_f32_e32 v11, v165, v11
	v_add_f32_e32 v94, v160, v94
	v_add_f32_e32 v11, v166, v11
	v_add_f32_e32 v94, v161, v94
	v_add_f32_e32 v11, v167, v11
	v_add_f32_e32 v94, v162, v94
	v_add_f32_e32 v11, v168, v11
	v_add_f32_e32 v94, v163, v94
	v_add_f32_e32 v11, v169, v11
	v_add_f32_e32 v10, v10, v94
	v_add_f32_e32 v11, v170, v11
	v_fmac_f32_e32 v11, v10, v152
	v_add_f32_e32 v10, 0, v171
	v_add_f32_e32 v10, v172, v10
	v_add_f32_e32 v10, v173, v10
	v_add_f32_e32 v10, v174, v10
	v_add_f32_e32 v10, v175, v10
	v_add_f32_e32 v10, v176, v10
	v_add_f32_e32 v10, v177, v10
	v_add_f32_e32 v10, v178, v10
	v_fmac_f32_e32 v10, v11, v154
	v_add_f32_e32 v11, 0, v191
	v_add_f32_e32 v11, v193, v11
	v_add_f32_e32 v11, v194, v11
	v_add_f32_e32 v11, v195, v11
	v_add_f32_e32 v11, v196, v11
	v_add_f32_e32 v11, v197, v11
	v_add_f32_e32 v11, v198, v11
	v_add_f32_e32 v11, v199, v11
	v_fmac_f32_e32 v11, v10, v156
	v_add_f32_e32 v10, 0, v200
	v_add_f32_e32 v10, v201, v10
	v_add_f32_e32 v10, v202, v10
	v_add_f32_e32 v10, v203, v10
	v_add_f32_e32 v10, v204, v10
	v_add_f32_e32 v10, v205, v10
	v_add_f32_e32 v10, v206, v10
	v_add_f32_e32 v10, v207, v10
	v_fmac_f32_e32 v10, v11, v158
	v_add_f32_e32 v11, 0, v125
	v_add_f32_e32 v11, v126, v11
	v_add_f32_e32 v11, v127, v11
	v_add_f32_e32 v11, v128, v11
	v_add_f32_e32 v11, v129, v11
	v_add_f32_e32 v11, v208, v11
	v_add_f32_e32 v11, v209, v11
	v_add_f32_e32 v11, v210, v11
	v_fmac_f32_e32 v11, v10, v0
	v_add_f32_e32 v0, 0, v213
	v_add_f32_e32 v0, v214, v0
	v_add_f32_e32 v0, v215, v0
	v_add_f32_e32 v0, v216, v0
	v_add_f32_e32 v0, v217, v0
	v_add_f32_e32 v0, v218, v0
	v_add_f32_e32 v0, v219, v0
	v_add_f32_e32 v101, v220, v0
	v_lshlrev_b32_e32 v0, 11, v141
	v_fmac_f32_e32 v101, v11, v124
	v_lshl_add_u64 v[10:11], s[8:9], 0, v[0:1]
	s_mov_b32 s31, s45
	v_lshl_add_u64 v[128:129], v[10:11], 0, s[30:31]
	v_max_f32_e32 v0, v100, v100
	v_max_f32_e32 v10, v211, v211
	v_max_f32_e32 v0, v10, v0
	v_max_f32_e32 v10, v98, v98
	v_max_f32_e32 v11, v96, v96
	v_max_f32_e32 v10, v11, v10
	v_max_f32_e32 v11, v93, v93
	v_max_f32_e32 v94, v92, v92
	v_max_f32_e32 v11, v94, v11
	v_max3_f32 v11, v97, v99, v11
	v_max3_f32 v0, v0, v10, v11
	v_mov_b32_e32 v10, v0
	s_nop 1
	v_permlane16_swap_b32_e32 v10, v0
	v_mov_b32_e32 v149, v1
	v_mov_b32_e32 v145, v1
	s_mov_b64 s[0:1], 0xc000
	s_waitcnt vmcnt(15)
	v_mfma_f32_16x16x32_bf16 v[88:91], v[88:91], v[6:9], 0
	s_waitcnt lgkmcnt(0)
	v_max_f32_e32 v10, v10, v10
	v_max_f32_e32 v0, v0, v10
	v_mov_b32_e32 v10, v0
	s_nop 1
	v_permlane32_swap_b32_e32 v10, v0
	v_mov_b32_e32 v143, v1
	s_waitcnt vmcnt(13)
	v_mfma_f32_16x16x32_bf16 v[84:87], v[84:87], v[6:9], 0
	v_mov_b32_e32 v147, v1
	s_waitcnt lgkmcnt(0)
	v_max3_f32 v124, v212, v0, v10
	v_sub_f32_e32 v94, v96, v124
	v_mul_f32_e32 v94, 0x3fb8aa3b, v94
	v_sub_f32_e32 v10, v211, v124
	v_sub_f32_e32 v11, v100, v124
	v_exp_f32_e32 v100, v94
	v_sub_f32_e32 v94, v98, v124
	v_mul_f32_e32 v10, 0x3fb8aa3b, v10
	v_mul_f32_e32 v94, 0x3fb8aa3b, v94
	v_exp_f32_e32 v10, v10
	v_mul_f32_e32 v11, 0x3fb8aa3b, v11
	v_exp_f32_e32 v102, v94
	v_sub_f32_e32 v94, v97, v124
	v_exp_f32_e32 v11, v11
	v_mul_f32_e32 v94, 0x3fb8aa3b, v94
	v_sub_f32_e32 v92, v92, v124
	v_exp_f32_e32 v103, v94
	v_sub_f32_e32 v94, v99, v124
	v_mul_f32_e32 v92, 0x3fb8aa3b, v92
	v_mul_f32_e32 v94, 0x3fb8aa3b, v94
	v_exp_f32_e32 v126, v92
	v_sub_f32_e32 v92, v93, v124
	v_sub_f32_e32 v0, v212, v124
	v_exp_f32_e32 v125, v94
	v_mul_f32_e32 v92, 0x3fb8aa3b, v92
	v_add_u32_e32 v93, 0x8000, v10
	v_add_f32_e32 v10, 0, v10
	v_mul_f32_e32 v0, 0x3fb8aa3b, v0
	v_exp_f32_e32 v127, v92
	v_add_f32_e32 v10, v11, v10
	v_exp_f32_e32 v0, v0
	v_add_u32_e32 v92, 0x8000, v11
	v_add_f32_e32 v10, v100, v10
	v_perm_b32 v92, v92, v93, s87
	v_add_u32_e32 v93, 0x8000, v102
	v_add_u32_e32 v94, 0x8000, v100
	v_add_f32_e32 v10, v102, v10
	v_perm_b32 v93, v93, v94, s87
	v_add_u32_e32 v94, 0x8000, v125
	v_add_u32_e32 v95, 0x8000, v103
	v_add_f32_e32 v10, v103, v10
	v_perm_b32 v94, v94, v95, s87
	v_add_u32_e32 v95, 0x8000, v127
	v_add_u32_e32 v96, 0x8000, v126
	v_add_f32_e32 v10, v125, v10
	v_perm_b32 v95, v95, v96, s87
	v_pk_mul_f32 v[98:99], v[122:123], v[0:1] op_sel_hi:[1,0]
	v_pk_mul_f32 v[96:97], v[120:121], v[0:1] op_sel_hi:[1,0]
	v_add_f32_e32 v10, v126, v10
	v_add_f32_e32 v125, v127, v10
	v_mfma_f32_16x16x32_bf16 v[120:123], v[60:63], v[92:95], v[96:99]
	v_mul_f32_e64 v62, v118, v0
	v_mul_f32_e64 v63, v119, v0
	v_pk_mul_f32 v[60:61], v[116:117], v[0:1] op_sel_hi:[1,0]
	v_lshl_add_u64 v[10:11], s[28:29], 0, v[148:149]
	v_lshl_add_u64 v[144:145], v[10:11], 0, v[144:145]
	v_mfma_f32_16x16x32_bf16 v[108:111], v[52:55], v[92:95], v[60:63]
	v_mul_f32_e64 v54, v114, v0
	v_mul_f32_e64 v55, v115, v0
	v_pk_mul_f32 v[52:53], v[112:113], v[0:1] op_sel_hi:[1,0]
	v_lshl_add_u64 v[10:11], v[144:145], 0, s[0:1]
	s_mov_b32 s0, 0xc000
	v_mfma_f32_16x16x32_bf16 v[112:115], v[48:51], v[92:95], v[52:55]
	v_mul_f32_e64 v50, v106, v0
	v_mul_f32_e64 v51, v107, v0
	v_pk_mul_f32 v[48:49], v[104:105], v[0:1] op_sel_hi:[1,0]
	v_fmac_f32_e32 v125, v101, v0
	v_mfma_f32_16x16x32_bf16 v[80:83], v[80:83], v[2:5], v[88:91]
	v_mfma_f32_16x16x32_bf16 v[116:119], v[44:47], v[92:95], v[48:51]
	v_add_co_u32_e32 v44, vcc, s0, v144
	s_mov_b64 s[0:1], 0x2000
	s_nop 0
	v_addc_co_u32_e32 v45, vcc, 0, v145, vcc
	global_load_dwordx4 v[104:107], v[44:45], off
	global_load_dwordx4 v[96:99], v[10:11], off offset:16
	global_load_dwordx4 v[100:103], v[10:11], off offset:3072
	global_load_dwordx4 v[92:95], v[10:11], off offset:3088
	v_lshl_add_u64 v[10:11], s[26:27], 0, v[142:143]
	v_lshl_add_u64 v[142:143], v[10:11], 0, v[146:147]
	v_lshl_add_u64 v[10:11], v[142:143], 0, s[0:1]
	s_movk_i32 s0, 0x2000
	v_add_co_u32_e32 v44, vcc, s0, v142
	s_waitcnt vmcnt(16)
	v_mfma_f32_16x16x32_bf16 v[68:71], v[68:71], v[2:5], v[84:87]
	v_addc_co_u32_e32 v45, vcc, 0, v143, vcc
	global_load_dwordx4 v[60:63], v[44:45], off
	global_load_dwordx4 v[52:55], v[10:11], off offset:256
	global_load_dwordx4 v[48:51], v[10:11], off offset:512
	s_nop 0
	global_load_dwordx4 v[44:47], v[10:11], off offset:768
	v_max_f32_e32 v0, v81, v81
	v_max_f32_e32 v10, v80, v80
	v_max_f32_e32 v0, v10, v0
	v_max_f32_e32 v10, v83, v83
	v_max_f32_e32 v11, v82, v82
	v_max_f32_e32 v10, v11, v10
	v_max_f32_e32 v11, v71, v71
	v_max_f32_e32 v84, v70, v70
	v_max_f32_e32 v11, v84, v11
	v_max3_f32 v11, v68, v69, v11
	v_max3_f32 v0, v0, v10, v11
	v_mov_b32_e32 v10, v0
	s_nop 1
	v_permlane16_swap_b32_e32 v10, v0
	s_waitcnt vmcnt(13)
	v_mfma_f32_16x16x32_bf16 v[76:79], v[76:79], v[6:9], 0
	s_mov_b32 s0, 0x12000
	s_waitcnt lgkmcnt(0)
	v_max_f32_e32 v10, v10, v10
	v_max_f32_e32 v0, v0, v10
	v_mov_b32_e32 v10, v0
	s_nop 1
	v_permlane32_swap_b32_e32 v10, v0
	v_mfma_f32_16x16x32_bf16 v[72:75], v[72:75], v[6:9], 0
	s_waitcnt lgkmcnt(0)
	v_max3_f32 v11, v124, v0, v10
	v_sub_f32_e32 v10, v80, v11
	v_sub_f32_e32 v68, v68, v11
	v_mul_f32_e32 v10, 0x3fb8aa3b, v10
	v_mul_f32_e32 v68, 0x3fb8aa3b, v68
	v_exp_f32_e32 v88, v10
	v_sub_f32_e32 v10, v81, v11
	v_exp_f32_e32 v148, v68
	v_sub_f32_e32 v68, v69, v11
	v_mul_f32_e32 v10, 0x3fb8aa3b, v10
	v_mul_f32_e32 v68, 0x3fb8aa3b, v68
	v_exp_f32_e32 v89, v10
	v_sub_f32_e32 v10, v82, v11
	v_sub_f32_e32 v80, v83, v11
	v_exp_f32_e32 v152, v68
	v_sub_f32_e32 v68, v70, v11
	v_mul_f32_e32 v10, 0x3fb8aa3b, v10
	v_mul_f32_e32 v80, 0x3fb8aa3b, v80
	v_mul_f32_e32 v68, 0x3fb8aa3b, v68
	v_exp_f32_e32 v10, v10
	v_exp_f32_e32 v146, v80
	v_exp_f32_e32 v154, v68
	v_sub_f32_e32 v68, v71, v11
	v_sub_f32_e32 v0, v124, v11
	v_mul_f32_e32 v68, 0x3fb8aa3b, v68
	v_mul_f32_e32 v0, 0x3fb8aa3b, v0
	v_exp_f32_e32 v156, v68
	v_exp_f32_e32 v0, v0
	v_add_u32_e32 v68, 0x8000, v89
	v_add_u32_e32 v69, 0x8000, v88
	v_perm_b32 v68, v68, v69, s87
	v_add_u32_e32 v69, 0x8000, v146
	v_add_u32_e32 v70, 0x8000, v10
	v_perm_b32 v69, v69, v70, s87
	v_add_u32_e32 v70, 0x8000, v152
	v_add_u32_e32 v71, 0x8000, v148
	v_perm_b32 v70, v70, v71, s87
	v_add_u32_e32 v71, 0x8000, v156
	v_add_u32_e32 v80, 0x8000, v154
	v_perm_b32 v71, v71, v80, s87
	v_pk_mul_f32 v[82:83], v[122:123], v[0:1] op_sel_hi:[1,0]
	v_pk_mul_f32 v[80:81], v[120:121], v[0:1] op_sel_hi:[1,0]
	v_mfma_f32_16x16x32_bf16 v[64:67], v[64:67], v[2:5], v[76:79]
	v_mul_f32_e32 v158, v125, v0
	v_mfma_f32_16x16x32_bf16 v[120:123], v[40:43], v[68:71], v[80:83]
	v_mul_f32_e64 v42, v110, v0
	v_mul_f32_e64 v43, v111, v0
	v_pk_mul_f32 v[40:41], v[108:109], v[0:1] op_sel_hi:[1,0]
	s_waitcnt vmcnt(12)
	v_mfma_f32_16x16x32_bf16 v[56:59], v[56:59], v[2:5], v[72:75]
	v_mfma_f32_16x16x32_bf16 v[124:127], v[36:39], v[68:71], v[40:43]
	v_mul_f32_e64 v38, v114, v0
	v_mul_f32_e64 v39, v115, v0
	v_pk_mul_f32 v[36:37], v[112:113], v[0:1] op_sel_hi:[1,0]
	v_max_f32_e32 v72, v65, v65
	v_max_f32_e32 v73, v64, v64
	v_mfma_f32_16x16x32_bf16 v[40:43], v[32:35], v[68:71], v[36:39]
	v_mul_f32_e64 v34, v118, v0
	v_mul_f32_e64 v35, v119, v0
	v_pk_mul_f32 v[32:33], v[116:117], v[0:1] op_sel_hi:[1,0]
	v_add_f32_e32 v0, 0, v88
	v_add_f32_e32 v0, v89, v0
	v_mfma_f32_16x16x32_bf16 v[84:87], v[28:31], v[68:71], v[32:35]
	v_add_co_u32_e32 v28, vcc, s0, v130
	v_max_f32_e32 v72, v73, v72
	s_nop 0
	v_addc_co_u32_e32 v29, vcc, 0, v131, vcc
	global_load_dwordx4 v[112:115], v[28:29], off
	global_load_dwordx4 v[88:91], v[28:29], off offset:16
	global_load_dwordx4 v[108:111], v[28:29], off offset:3072
	global_load_dwordx4 v[80:83], v[28:29], off offset:3088
	v_max_f32_e32 v73, v67, v67
	v_max_f32_e32 v74, v66, v66
	v_max_f32_e32 v73, v74, v73
	v_max_f32_e32 v74, v59, v59
	v_max_f32_e32 v75, v58, v58
	v_max_f32_e32 v74, v75, v74
	v_max3_f32 v74, v56, v57, v74
	v_max3_f32 v72, v72, v73, v74
	v_mov_b32_e32 v73, v72
	s_nop 1
	v_permlane16_swap_b32_e32 v73, v72
	s_waitcnt vmcnt(11)
	v_mfma_f32_16x16x32_bf16 v[104:107], v[104:107], v[6:9], 0
	s_movk_i32 s0, 0x3000
	v_add_co_u32_e32 v28, vcc, s0, v150
	s_waitcnt lgkmcnt(0)
	v_max_f32_e32 v73, v73, v73
	v_max_f32_e32 v72, v72, v73
	v_mov_b32_e32 v73, v72
	s_nop 1
	v_permlane32_swap_b32_e32 v73, v72
	s_waitcnt vmcnt(9)
	v_mfma_f32_16x16x32_bf16 v[100:103], v[100:103], v[6:9], 0
	s_mov_b64 s[0:1], 0x18000
	v_addc_co_u32_e32 v29, vcc, 0, v151, vcc
	s_waitcnt lgkmcnt(0)
	v_max3_f32 v141, v11, v72, v73
	v_sub_f32_e32 v11, v11, v141
	v_mul_f32_e32 v72, 0x3fb8aa3b, v11
	v_sub_f32_e32 v11, v64, v141
	v_sub_f32_e32 v64, v65, v141
	v_sub_f32_e32 v56, v56, v141
	v_mul_f32_e32 v64, 0x3fb8aa3b, v64
	v_mul_f32_e32 v56, 0x3fb8aa3b, v56
	v_exp_f32_e32 v147, v64
	v_sub_f32_e32 v64, v66, v141
	v_exp_f32_e32 v155, v56
	v_sub_f32_e32 v56, v57, v141
	v_mul_f32_e32 v11, 0x3fb8aa3b, v11
	v_mul_f32_e32 v64, 0x3fb8aa3b, v64
	v_mul_f32_e32 v56, 0x3fb8aa3b, v56
	v_exp_f32_e32 v11, v11
	v_exp_f32_e32 v149, v64
	v_sub_f32_e32 v64, v67, v141
	v_exp_f32_e32 v157, v56
	v_sub_f32_e32 v56, v58, v141
	v_mul_f32_e32 v64, 0x3fb8aa3b, v64
	v_mul_f32_e32 v56, 0x3fb8aa3b, v56
	v_exp_f32_e32 v153, v64
	v_exp_f32_e32 v159, v56
	v_sub_f32_e32 v56, v59, v141
	v_mul_f32_e32 v56, 0x3fb8aa3b, v56
	v_exp_f32_e32 v73, v56
	v_add_u32_e32 v57, 0x8000, v11
	v_pk_add_f32 v[10:11], v[10:11], v[0:1]
	v_exp_f32_e32 v72, v72
	v_add_u32_e32 v56, 0x8000, v147
	v_pk_add_f32 v[10:11], v[146:147], v[10:11]
	v_perm_b32 v56, v56, v57, s87
	v_add_u32_e32 v57, 0x8000, v153
	v_add_u32_e32 v58, 0x8000, v149
	v_pk_add_f32 v[10:11], v[148:149], v[10:11]
	v_perm_b32 v57, v57, v58, s87
	v_add_u32_e32 v58, 0x8000, v157
	v_add_u32_e32 v59, 0x8000, v155
	v_pk_add_f32 v[10:11], v[152:153], v[10:11]
	v_perm_b32 v58, v58, v59, s87
	v_add_u32_e32 v59, 0x8000, v73
	v_add_u32_e32 v64, 0x8000, v159
	v_pk_add_f32 v[10:11], v[154:155], v[10:11]
	v_mfma_f32_16x16x32_bf16 v[96:99], v[96:99], v[2:5], v[104:107]
	v_perm_b32 v59, v59, v64, s87
	v_pk_mul_f32 v[66:67], v[122:123], v[72:73] op_sel_hi:[1,0]
	v_pk_mul_f32 v[64:65], v[120:121], v[72:73] op_sel_hi:[1,0]
	v_pk_add_f32 v[10:11], v[156:157], v[10:11]
	s_waitcnt vmcnt(8)
	v_mfma_f32_16x16x32_bf16 v[92:95], v[92:95], v[2:5], v[100:103]
	v_add_f32_e64 v10, v158, v10
	v_add_f32_e64 v11, v159, v11
	v_max_f32_e32 v0, v97, v97
	global_load_dwordx4 v[68:71], v[28:29], off
	global_load_dwordx4 v[36:39], v[28:29], off offset:256
	global_load_dwordx4 v[32:35], v[28:29], off offset:512
	s_nop 0
	global_load_dwordx4 v[28:31], v[28:29], off offset:768
	v_mfma_f32_16x16x32_bf16 v[120:123], v[24:27], v[56:59], v[64:67]
	v_mul_f32_e64 v26, v126, v72
	v_mul_f32_e64 v27, v127, v72
	v_pk_mul_f32 v[24:25], v[124:125], v[72:73] op_sel_hi:[1,0]
	v_max_f32_e32 v100, v98, v98
	v_max_f32_e32 v101, v94, v94
	v_mfma_f32_16x16x32_bf16 v[116:119], v[20:23], v[56:59], v[24:27]
	v_mul_f32_e64 v22, v42, v72
	v_mul_f32_e64 v23, v43, v72
	v_pk_mul_f32 v[20:21], v[40:41], v[72:73] op_sel_hi:[1,0]
	v_add_f32_e32 v27, v11, v73
	s_nop 0
	v_mfma_f32_16x16x32_bf16 v[40:43], v[16:19], v[56:59], v[20:23]
	v_mul_f32_e64 v18, v86, v72
	v_mul_f32_e64 v19, v87, v72
	v_pk_mul_f32 v[16:17], v[84:85], v[72:73] op_sel_hi:[1,0]
	v_fmac_f32_e32 v27, v10, v72
	v_lshl_add_u64 v[10:11], v[144:145], 0, s[0:1]
	s_mov_b32 s0, 0x18000
	v_max_f32_e32 v26, v96, v96
	v_mfma_f32_16x16x32_bf16 v[56:59], v[12:15], v[56:59], v[16:19]
	v_add_co_u32_e32 v12, vcc, s0, v144
	v_max_f32_e32 v0, v26, v0
	v_max_f32_e32 v26, v99, v99
	v_addc_co_u32_e32 v13, vcc, 0, v145, vcc
	v_max_f32_e32 v26, v100, v26
	v_max_f32_e32 v100, v95, v95
	global_load_dwordx4 v[84:87], v[12:13], off
	global_load_dwordx4 v[72:75], v[10:11], off offset:16
	global_load_dwordx4 v[76:79], v[10:11], off offset:3072
	global_load_dwordx4 v[64:67], v[10:11], off offset:3088
	v_max_f32_e32 v100, v101, v100
	v_max3_f32 v100, v92, v93, v100
	v_max3_f32 v0, v0, v26, v100
	v_mov_b32_e32 v26, v0
	s_nop 1
	v_permlane16_swap_b32_e32 v26, v0
	s_mov_b64 s[0:1], 0x4000
	v_lshl_add_u64 v[10:11], v[142:143], 0, s[0:1]
	s_movk_i32 s0, 0x5000
	v_add_co_u32_e32 v156, vcc, s0, v142
	s_waitcnt lgkmcnt(0)
	v_max_f32_e32 v26, v26, v26
	v_max_f32_e32 v0, v0, v26
	v_mov_b32_e32 v26, v0
	s_nop 1
	v_permlane32_swap_b32_e32 v26, v0
	s_mov_b64 s[0:1], 0x1e000
	v_addc_co_u32_e32 v157, vcc, 0, v143, vcc
	global_load_dwordx4 v[22:25], v[156:157], off offset:-4096
	global_load_dwordx4 v[18:21], v[10:11], off offset:256
	global_load_dwordx4 v[14:17], v[10:11], off offset:512
	s_nop 0
	global_load_dwordx4 v[10:13], v[10:11], off offset:768
	s_waitcnt lgkmcnt(0)
	v_max3_f32 v125, v141, v0, v26
	v_sub_f32_e32 v26, v96, v125
	v_sub_f32_e32 v92, v92, v125
	v_mul_f32_e32 v26, 0x3fb8aa3b, v26
	v_mul_f32_e32 v92, 0x3fb8aa3b, v92
	v_exp_f32_e32 v100, v26
	v_sub_f32_e32 v26, v97, v125
	v_exp_f32_e32 v126, v92
	v_sub_f32_e32 v92, v93, v125
	v_sub_f32_e32 v0, v141, v125
	v_mul_f32_e32 v26, 0x3fb8aa3b, v26
	v_mul_f32_e32 v92, 0x3fb8aa3b, v92
	v_mul_f32_e32 v0, 0x3fb8aa3b, v0
	v_exp_f32_e32 v101, v26
	v_sub_f32_e32 v26, v98, v125
	v_sub_f32_e32 v96, v99, v125
	v_exp_f32_e32 v146, v92
	v_sub_f32_e32 v92, v94, v125
	v_mul_f32_e32 v26, 0x3fb8aa3b, v26
	v_mul_f32_e32 v96, 0x3fb8aa3b, v96
	v_mul_f32_e32 v92, 0x3fb8aa3b, v92
	v_exp_f32_e32 v0, v0
	v_exp_f32_e32 v26, v26
	v_exp_f32_e32 v124, v96
	v_exp_f32_e32 v148, v92
	v_sub_f32_e32 v92, v95, v125
	v_mul_f32_e32 v92, 0x3fb8aa3b, v92
	v_exp_f32_e32 v152, v92
	v_mul_f32_e32 v154, v27, v0
	v_add_u32_e32 v27, 0x8000, v101
	v_add_u32_e32 v92, 0x8000, v100
	v_perm_b32 v92, v27, v92, s87
	v_add_u32_e32 v27, 0x8000, v124
	v_add_u32_e32 v93, 0x8000, v26
	v_perm_b32 v93, v27, v93, s87
	v_add_u32_e32 v27, 0x8000, v146
	v_add_u32_e32 v94, 0x8000, v126
	v_perm_b32 v94, v27, v94, s87
	v_add_u32_e32 v27, 0x8000, v152
	v_add_u32_e32 v95, 0x8000, v148
	v_perm_b32 v95, v27, v95, s87
	v_pk_mul_f32 v[42:43], v[42:43], v[0:1] op_sel_hi:[1,0]
	v_pk_mul_f32 v[40:41], v[40:41], v[0:1] op_sel_hi:[1,0]
	v_pk_mul_f32 v[98:99], v[122:123], v[0:1] op_sel_hi:[1,0]
	v_pk_mul_f32 v[96:97], v[120:121], v[0:1] op_sel_hi:[1,0]
	s_waitcnt vmcnt(17)
	v_mfma_f32_16x16x32_bf16 v[104:107], v[48:51], v[92:95], v[40:43]
	s_nop 2
	v_mul_f32_e64 v42, v58, v0
	v_mul_f32_e64 v43, v59, v0
	v_pk_mul_f32 v[40:41], v[56:57], v[0:1] op_sel_hi:[1,0]
	v_mfma_f32_16x16x32_bf16 v[120:123], v[60:63], v[92:95], v[96:99]
	v_mul_f32_e64 v62, v118, v0
	v_mul_f32_e64 v63, v119, v0
	v_pk_mul_f32 v[60:61], v[116:117], v[0:1] op_sel_hi:[1,0]
	v_add_f32_e32 v0, 0, v100
	s_waitcnt vmcnt(16)
	v_mfma_f32_16x16x32_bf16 v[56:59], v[44:47], v[92:95], v[40:43]
	v_add_f32_e32 v0, v101, v0
	s_nop 1
	v_lshl_add_u64 v[40:41], v[144:145], 0, s[0:1]
	s_mov_b32 s0, 0x1e000
	v_add_co_u32_e32 v42, vcc, s0, v144
	v_mfma_f32_16x16x32_bf16 v[116:119], v[52:55], v[92:95], v[60:63]
	s_nop 0
	v_addc_co_u32_e32 v43, vcc, 0, v145, vcc
	global_load_dwordx4 v[100:103], v[42:43], off
	global_load_dwordx4 v[92:95], v[40:41], off offset:16
	global_load_dwordx4 v[96:99], v[40:41], off offset:3072
	global_load_dwordx4 v[60:63], v[40:41], off offset:3088
	s_waitcnt vmcnt(19)
	v_mfma_f32_16x16x32_bf16 v[112:115], v[112:115], v[6:9], 0
	s_mov_b64 s[0:1], 0x5000
	v_lshl_add_u64 v[40:41], v[142:143], 0, s[0:1]
	global_load_dwordx4 v[52:55], v[156:157], off
	global_load_dwordx4 v[48:51], v[40:41], off offset:256
	global_load_dwordx4 v[44:47], v[40:41], off offset:512
	s_nop 0
	global_load_dwordx4 v[40:43], v[40:41], off offset:768
	s_waitcnt vmcnt(21)
	v_mfma_f32_16x16x32_bf16 v[108:111], v[108:111], v[6:9], 0
	s_mov_b32 s0, 0x24000
	v_mfma_f32_16x16x32_bf16 v[88:91], v[88:91], v[2:5], v[112:115]
	s_waitcnt vmcnt(20)
	v_mfma_f32_16x16x32_bf16 v[80:83], v[80:83], v[2:5], v[108:111]
	s_waitcnt vmcnt(15)
	v_mfma_f32_16x16x32_bf16 v[84:87], v[84:87], v[6:9], 0
	s_nop 3
	v_max_f32_e32 v27, v89, v89
	v_max_f32_e32 v108, v88, v88
	v_max_f32_e32 v27, v108, v27
	v_max_f32_e32 v108, v91, v91
	v_max_f32_e32 v109, v90, v90
	v_max_f32_e32 v108, v109, v108
	v_max_f32_e32 v109, v83, v83
	v_max_f32_e32 v110, v82, v82
	v_max_f32_e32 v109, v110, v109
	v_max3_f32 v109, v80, v81, v109
	v_max3_f32 v27, v27, v108, v109
	v_mov_b32_e32 v108, v27
	s_nop 1
	v_permlane16_swap_b32_e32 v108, v27
	s_waitcnt vmcnt(13)
	v_mfma_f32_16x16x32_bf16 v[76:79], v[76:79], v[6:9], 0
	s_waitcnt lgkmcnt(0)
	v_max_f32_e32 v108, v108, v108
	v_max_f32_e32 v27, v27, v108
	v_mov_b32_e32 v108, v27
	s_nop 1
	v_permlane32_swap_b32_e32 v108, v27
	v_mfma_f32_16x16x32_bf16 v[72:75], v[72:75], v[2:5], v[84:87]
	s_waitcnt lgkmcnt(0)
	v_max3_f32 v141, v125, v27, v108
	v_sub_f32_e32 v27, v125, v141
	v_mul_f32_e32 v108, 0x3fb8aa3b, v27
	v_sub_f32_e32 v27, v88, v141
	v_sub_f32_e32 v88, v89, v141
	v_sub_f32_e32 v80, v80, v141
	v_mul_f32_e32 v88, 0x3fb8aa3b, v88
	v_mul_f32_e32 v80, 0x3fb8aa3b, v80
	v_exp_f32_e32 v125, v88
	v_sub_f32_e32 v88, v90, v141
	v_exp_f32_e32 v149, v80
	v_sub_f32_e32 v80, v81, v141
	v_mul_f32_e32 v88, 0x3fb8aa3b, v88
	v_mul_f32_e32 v80, 0x3fb8aa3b, v80
	v_mul_f32_e32 v27, 0x3fb8aa3b, v27
	v_exp_f32_e32 v127, v88
	v_sub_f32_e32 v88, v91, v141
	v_exp_f32_e32 v153, v80
	v_sub_f32_e32 v80, v82, v141
	v_exp_f32_e32 v27, v27
	v_mul_f32_e32 v88, 0x3fb8aa3b, v88
	v_mul_f32_e32 v80, 0x3fb8aa3b, v80
	v_exp_f32_e32 v147, v88
	v_exp_f32_e32 v155, v80
	v_sub_f32_e32 v80, v83, v141
	v_mul_f32_e32 v80, 0x3fb8aa3b, v80
	v_exp_f32_e32 v157, v80
	v_exp_f32_e32 v156, v108
	v_add_u32_e32 v80, 0x8000, v125
	v_add_u32_e32 v81, 0x8000, v27
	v_pk_add_f32 v[26:27], v[26:27], v[0:1]
	v_perm_b32 v80, v80, v81, s87
	v_add_u32_e32 v81, 0x8000, v147
	v_add_u32_e32 v82, 0x8000, v127
	v_pk_add_f32 v[26:27], v[124:125], v[26:27]
	v_perm_b32 v81, v81, v82, s87
	v_add_u32_e32 v82, 0x8000, v153
	v_add_u32_e32 v83, 0x8000, v149
	v_pk_add_f32 v[26:27], v[126:127], v[26:27]
	v_perm_b32 v82, v82, v83, s87
	v_add_u32_e32 v83, 0x8000, v157
	v_add_u32_e32 v88, 0x8000, v155
	v_pk_add_f32 v[26:27], v[146:147], v[26:27]
	v_perm_b32 v83, v83, v88, s87
	v_pk_mul_f32 v[90:91], v[122:123], v[156:157] op_sel_hi:[1,0]
	v_pk_mul_f32 v[88:89], v[120:121], v[156:157] op_sel_hi:[1,0]
	v_pk_add_f32 v[26:27], v[148:149], v[26:27]
	s_waitcnt vmcnt(12)
	v_mfma_f32_16x16x32_bf16 v[64:67], v[64:67], v[2:5], v[76:79]
	v_add_f32_e64 v26, v152, v26
	v_add_f32_e64 v27, v153, v27
	v_max_f32_e32 v0, v73, v73
	v_pk_add_f32 v[26:27], v[154:155], v[26:27]
	v_mfma_f32_16x16x32_bf16 v[112:115], v[68:71], v[80:83], v[88:91]
	v_mul_f32_e64 v70, v118, v156
	v_mul_f32_e64 v71, v119, v156
	v_pk_mul_f32 v[68:69], v[116:117], v[156:157] op_sel_hi:[1,0]
	v_max_f32_e32 v76, v74, v74
	v_max_f32_e32 v77, v66, v66
	v_mfma_f32_16x16x32_bf16 v[120:123], v[36:39], v[80:83], v[68:71]
	v_mul_f32_e64 v38, v106, v156
	v_mul_f32_e64 v39, v107, v156
	v_pk_mul_f32 v[36:37], v[104:105], v[156:157] op_sel_hi:[1,0]
	s_waitcnt vmcnt(7)
	v_mfma_f32_16x16x32_bf16 v[100:103], v[100:103], v[6:9], 0
	v_mfma_f32_16x16x32_bf16 v[108:111], v[32:35], v[80:83], v[36:39]
	v_mul_f32_e64 v34, v58, v156
	v_mul_f32_e64 v35, v59, v156
	v_pk_mul_f32 v[32:33], v[56:57], v[156:157] op_sel_hi:[1,0]
	v_add_f32_e32 v38, v27, v157
	v_fmac_f32_e32 v38, v26, v156
	v_add_co_u32_e32 v26, vcc, s0, v130
	v_max_f32_e32 v39, v72, v72
	s_nop 0
	v_addc_co_u32_e32 v27, vcc, 0, v131, vcc
	v_mfma_f32_16x16x32_bf16 v[116:119], v[28:31], v[80:83], v[32:35]
	global_load_dwordx4 v[104:107], v[26:27], off
	global_load_dwordx4 v[80:83], v[26:27], off offset:16
	global_load_dwordx4 v[88:91], v[26:27], off offset:3072
	global_load_dwordx4 v[68:71], v[26:27], off offset:3088
	v_max_f32_e32 v0, v39, v0
	v_max_f32_e32 v39, v75, v75
	v_max_f32_e32 v39, v76, v39
	v_max_f32_e32 v76, v67, v67
	v_max_f32_e32 v76, v77, v76
	v_max3_f32 v76, v64, v65, v76
	v_max3_f32 v0, v0, v39, v76
	v_mov_b32_e32 v39, v0
	s_nop 1
	v_permlane16_swap_b32_e32 v39, v0
	s_movk_i32 s0, 0x6000
	v_add_co_u32_e32 v26, vcc, s0, v150
	s_waitcnt vmcnt(9)
	v_mfma_f32_16x16x32_bf16 v[96:99], v[96:99], v[6:9], 0
	s_waitcnt lgkmcnt(0)
	v_max_f32_e32 v39, v39, v39
	v_max_f32_e32 v0, v0, v39
	v_mov_b32_e32 v39, v0
	s_nop 1
	v_permlane32_swap_b32_e32 v39, v0
	v_mfma_f32_16x16x32_bf16 v[92:95], v[92:95], v[2:5], v[100:103]
	v_addc_co_u32_e32 v27, vcc, 0, v151, vcc
	s_mov_b64 s[0:1], 0x2a000
	s_waitcnt lgkmcnt(0)
	v_max3_f32 v39, v141, v0, v39
	v_sub_f32_e32 v72, v72, v39
	v_mul_f32_e32 v72, 0x3fb8aa3b, v72
	v_exp_f32_e32 v76, v72
	v_sub_f32_e32 v72, v73, v39
	v_sub_f32_e32 v64, v64, v39
	v_mul_f32_e32 v72, 0x3fb8aa3b, v72
	v_mul_f32_e32 v64, 0x3fb8aa3b, v64
	v_exp_f32_e32 v77, v72
	v_sub_f32_e32 v72, v74, v39
	v_exp_f32_e32 v148, v64
	v_sub_f32_e32 v64, v65, v39
	v_sub_f32_e32 v0, v141, v39
	v_mul_f32_e32 v72, 0x3fb8aa3b, v72
	v_mul_f32_e32 v64, 0x3fb8aa3b, v64
	v_mul_f32_e32 v0, 0x3fb8aa3b, v0
	v_exp_f32_e32 v130, v72
	v_sub_f32_e32 v72, v75, v39
	v_exp_f32_e32 v150, v64
	v_sub_f32_e32 v64, v66, v39
	v_mul_f32_e32 v72, 0x3fb8aa3b, v72
	v_mul_f32_e32 v64, 0x3fb8aa3b, v64
	v_exp_f32_e32 v0, v0
	v_exp_f32_e32 v146, v72
	v_exp_f32_e32 v152, v64
	v_sub_f32_e32 v64, v67, v39
	v_mul_f32_e32 v64, 0x3fb8aa3b, v64
	v_exp_f32_e32 v154, v64
	v_mul_f32_e32 v156, v38, v0
	v_add_u32_e32 v38, 0x8000, v77
	v_add_u32_e32 v64, 0x8000, v76
	v_perm_b32 v64, v38, v64, s87
	v_add_u32_e32 v38, 0x8000, v146
	v_add_u32_e32 v65, 0x8000, v130
	v_perm_b32 v65, v38, v65, s87
	v_add_u32_e32 v38, 0x8000, v150
	v_add_u32_e32 v66, 0x8000, v148
	s_waitcnt vmcnt(8)
	v_mfma_f32_16x16x32_bf16 v[60:63], v[60:63], v[2:5], v[96:99]
	v_perm_b32 v66, v38, v66, s87
	v_add_u32_e32 v38, 0x8000, v154
	v_add_u32_e32 v67, 0x8000, v152
	v_perm_b32 v67, v38, v67, s87
	v_max_f32_e32 v38, v93, v93
	v_max_f32_e32 v96, v92, v92
	v_max_f32_e32 v38, v96, v38
	v_max_f32_e32 v96, v95, v95
	v_max_f32_e32 v97, v94, v94
	v_max_f32_e32 v96, v97, v96
	v_max_f32_e32 v97, v63, v63
	v_max_f32_e32 v98, v62, v62
	v_max_f32_e32 v97, v98, v97
	v_max3_f32 v97, v60, v61, v97
	v_max3_f32 v38, v38, v96, v97
	v_mov_b32_e32 v96, v38
	s_nop 1
	v_permlane16_swap_b32_e32 v96, v38
	v_pk_mul_f32 v[74:75], v[114:115], v[0:1] op_sel_hi:[1,0]
	v_pk_mul_f32 v[72:73], v[112:113], v[0:1] op_sel_hi:[1,0]
	global_load_dwordx4 v[56:59], v[26:27], off
	global_load_dwordx4 v[34:37], v[26:27], off offset:256
	global_load_dwordx4 v[30:33], v[26:27], off offset:512
	s_nop 0
	global_load_dwordx4 v[26:29], v[26:27], off offset:768
	v_mfma_f32_16x16x32_bf16 v[124:127], v[22:25], v[64:67], v[72:75]
	v_mul_f32_e64 v24, v122, v0
	v_mul_f32_e64 v25, v123, v0
	v_pk_mul_f32 v[22:23], v[120:121], v[0:1] op_sel_hi:[1,0]
	s_waitcnt lgkmcnt(0)
	v_max_f32_e32 v96, v96, v96
	v_max_f32_e32 v38, v38, v96
	v_mfma_f32_16x16x32_bf16 v[120:123], v[18:21], v[64:67], v[22:25]
	v_mul_f32_e64 v20, v110, v0
	v_mul_f32_e64 v21, v111, v0
	v_pk_mul_f32 v[18:19], v[108:109], v[0:1] op_sel_hi:[1,0]
	v_mov_b32_e32 v96, v38
	s_nop 1
	v_permlane32_swap_b32_e32 v96, v38
	s_waitcnt vmcnt(5)
	v_mfma_f32_16x16x32_bf16 v[88:91], v[88:91], v[6:9], 0
	v_mov_b32_e32 v141, v1
	s_waitcnt lgkmcnt(0)
	v_max3_f32 v97, v39, v38, v96
	v_mfma_f32_16x16x32_bf16 v[108:111], v[14:17], v[64:67], v[18:21]
	v_mul_f32_e64 v16, v118, v0
	v_mul_f32_e64 v17, v119, v0
	v_pk_mul_f32 v[14:15], v[116:117], v[0:1] op_sel_hi:[1,0]
	v_add_f32_e32 v0, 0, v76
	v_add_f32_e32 v0, v77, v0
	v_mfma_f32_16x16x32_bf16 v[112:115], v[10:13], v[64:67], v[14:17]
	v_lshl_add_u64 v[10:11], v[144:145], 0, s[0:1]
	s_mov_b32 s0, 0x2a000
	v_add_co_u32_e32 v12, vcc, s0, v144
	v_sub_f32_e32 v38, v39, v97
	s_nop 0
	v_addc_co_u32_e32 v13, vcc, 0, v145, vcc
	global_load_dwordx4 v[84:87], v[12:13], off
	global_load_dwordx4 v[72:75], v[10:11], off offset:16
	global_load_dwordx4 v[76:79], v[10:11], off offset:3072
	global_load_dwordx4 v[64:67], v[10:11], off offset:3088
	v_sub_f32_e32 v39, v92, v97
	v_mul_f32_e32 v39, 0x3fb8aa3b, v39
	v_exp_f32_e32 v131, v39
	v_sub_f32_e32 v39, v93, v97
	v_mul_f32_e32 v39, 0x3fb8aa3b, v39
	v_exp_f32_e32 v147, v39
	v_sub_f32_e32 v39, v94, v97
	v_mul_f32_e32 v39, 0x3fb8aa3b, v39
	v_exp_f32_e32 v149, v39
	v_sub_f32_e32 v39, v95, v97
	v_mul_f32_e32 v39, 0x3fb8aa3b, v39
	v_exp_f32_e32 v151, v39
	v_sub_f32_e32 v39, v60, v97
	v_mul_f32_e32 v39, 0x3fb8aa3b, v39
	v_exp_f32_e32 v153, v39
	v_sub_f32_e32 v39, v61, v97
	v_mul_f32_e32 v39, 0x3fb8aa3b, v39
	v_exp_f32_e32 v155, v39
	v_sub_f32_e32 v39, v62, v97
	v_mul_f32_e32 v39, 0x3fb8aa3b, v39
	v_exp_f32_e32 v157, v39
	v_sub_f32_e32 v39, v63, v97
	v_mul_f32_e32 v39, 0x3fb8aa3b, v39
	v_mul_f32_e32 v38, 0x3fb8aa3b, v38
	v_exp_f32_e32 v98, v39
	v_exp_f32_e32 v96, v38
	v_add_u32_e32 v38, 0x8000, v147
	v_add_u32_e32 v39, 0x8000, v131
	v_perm_b32 v60, v38, v39, s87
	v_add_u32_e32 v38, 0x8000, v151
	v_add_u32_e32 v39, 0x8000, v149
	v_perm_b32 v61, v38, v39, s87
	v_add_u32_e32 v38, 0x8000, v155
	v_add_u32_e32 v39, 0x8000, v153
	v_perm_b32 v62, v38, v39, s87
	v_add_u32_e32 v38, 0x8000, v98
	v_add_u32_e32 v39, 0x8000, v157
	v_perm_b32 v63, v38, v39, s87
	v_pk_mul_f32 v[94:95], v[126:127], v[96:97] op_sel_hi:[1,0]
	v_pk_mul_f32 v[92:93], v[124:125], v[96:97] op_sel_hi:[1,0]
	s_waitcnt vmcnt(8)
	v_mfma_f32_16x16x32_bf16 v[88:91], v[68:71], v[2:5], v[88:91]
	s_mov_b64 s[0:1], 0x7000
	v_lshl_add_u64 v[10:11], v[142:143], 0, s[0:1]
	s_movk_i32 s0, 0x7000
	v_mfma_f32_16x16x32_bf16 v[52:55], v[52:55], v[60:63], v[92:95]
	v_add_co_u32_e32 v12, vcc, s0, v142
	s_nop 2
	v_max_f32_e32 v69, v90, v90
	v_pk_mul_f32 v[94:95], v[122:123], v[96:97] op_sel_hi:[1,0]
	v_pk_mul_f32 v[92:93], v[120:121], v[96:97] op_sel_hi:[1,0]
	v_addc_co_u32_e32 v13, vcc, 0, v143, vcc
	s_nop 0
	v_mfma_f32_16x16x32_bf16 v[48:51], v[48:51], v[60:63], v[92:95]
	global_load_dwordx4 v[22:25], v[12:13], off
	global_load_dwordx4 v[18:21], v[10:11], off offset:256
	global_load_dwordx4 v[14:17], v[10:11], off offset:512
	s_nop 0
	global_load_dwordx4 v[10:13], v[10:11], off offset:768
	v_pk_mul_f32 v[94:95], v[110:111], v[96:97] op_sel_hi:[1,0]
	v_pk_mul_f32 v[92:93], v[108:109], v[96:97] op_sel_hi:[1,0]
	s_mov_b64 s[0:1], 0xd800200
	s_nop 0
	v_mfma_f32_16x16x32_bf16 v[44:47], v[44:47], v[60:63], v[92:95]
	s_nop 2
	v_mul_f32_e64 v94, v114, v96
	v_mul_f32_e64 v95, v115, v96
	v_pk_mul_f32 v[92:93], v[112:113], v[96:97] op_sel_hi:[1,0]
	s_nop 1
	v_mfma_f32_16x16x32_bf16 v[38:41], v[40:43], v[60:63], v[92:95]
	v_add_f32_e64 v42, v130, v0
	v_add_f32_e64 v43, v131, v1
	v_pk_add_f32 v[42:43], v[146:147], v[42:43]
	v_mfma_f32_16x16x32_bf16 v[60:63], v[104:107], v[6:9], 0
	v_add_f32_e64 v42, v148, v42
	v_add_f32_e64 v43, v149, v43
	v_pk_add_f32 v[42:43], v[150:151], v[42:43]
	v_mfma_f32_16x16x32_bf16 v[60:63], v[80:83], v[2:5], v[60:63]
	v_add_f32_e64 v42, v152, v42
	v_add_f32_e64 v43, v153, v43
	v_pk_add_f32 v[42:43], v[154:155], v[42:43]
	s_nop 0
	v_pk_add_f32 v[42:43], v[156:157], v[42:43]
	s_nop 2
	v_max_f32_e32 v0, v61, v61
	v_add_f32_e32 v43, v43, v98
	v_fmac_f32_e32 v43, v42, v96
	v_max_f32_e32 v42, v60, v60
	v_max_f32_e32 v0, v42, v0
	v_max_f32_e32 v42, v63, v63
	v_max_f32_e32 v68, v62, v62
	v_max_f32_e32 v42, v68, v42
	v_max_f32_e32 v68, v91, v91
	v_max_f32_e32 v68, v69, v68
	v_max3_f32 v68, v88, v89, v68
	v_max3_f32 v0, v0, v42, v68
	v_mov_b32_e32 v42, v0
	s_nop 1
	v_permlane16_swap_b32_e32 v42, v0
	s_waitcnt lgkmcnt(0)
	v_max_f32_e32 v42, v42, v42
	v_max_f32_e32 v0, v0, v42
	v_mov_b32_e32 v42, v0
	s_nop 1
	v_permlane32_swap_b32_e32 v42, v0
	s_waitcnt lgkmcnt(0)
	v_max3_f32 v69, v97, v0, v42
	v_sub_f32_e32 v42, v60, v69
	v_mul_f32_e32 v42, 0x3fb8aa3b, v42
	v_exp_f32_e32 v71, v42
	v_sub_f32_e32 v42, v61, v69
	v_mul_f32_e32 v42, 0x3fb8aa3b, v42
	v_exp_f32_e32 v61, v42
	v_sub_f32_e32 v42, v62, v69
	v_mul_f32_e32 v42, 0x3fb8aa3b, v42
	v_exp_f32_e32 v82, v42
	v_sub_f32_e32 v42, v63, v69
	v_mul_f32_e32 v42, 0x3fb8aa3b, v42
	v_exp_f32_e32 v80, v42
	v_sub_f32_e32 v42, v88, v69
	v_mul_f32_e32 v42, 0x3fb8aa3b, v42
	v_exp_f32_e32 v70, v42
	v_sub_f32_e32 v42, v89, v69
	v_sub_f32_e32 v0, v97, v69
	v_mul_f32_e32 v42, 0x3fb8aa3b, v42
	v_mul_f32_e32 v0, 0x3fb8aa3b, v0
	v_exp_f32_e32 v68, v42
	v_sub_f32_e32 v42, v90, v69
	v_mul_f32_e32 v42, 0x3fb8aa3b, v42
	v_exp_f32_e32 v0, v0
	v_exp_f32_e32 v62, v42
	v_sub_f32_e32 v42, v91, v69
	v_mul_f32_e32 v42, 0x3fb8aa3b, v42
	v_exp_f32_e32 v60, v42
	v_mul_f32_e32 v42, v43, v0
	v_add_u32_e32 v43, 0x8000, v61
	v_add_u32_e32 v63, 0x8000, v71
	v_perm_b32 v88, v43, v63, s87
	v_add_u32_e32 v43, 0x8000, v80
	v_add_u32_e32 v63, 0x8000, v82
	v_perm_b32 v89, v43, v63, s87
	v_add_u32_e32 v43, 0x8000, v68
	v_add_u32_e32 v63, 0x8000, v70
	v_perm_b32 v90, v43, v63, s87
	v_add_u32_e32 v43, 0x8000, v60
	v_add_u32_e32 v63, 0x8000, v62
	v_perm_b32 v91, v43, v63, s87
	v_pk_mul_f32 v[40:41], v[40:41], v[0:1] op_sel_hi:[1,0]
	v_pk_mul_f32 v[38:39], v[38:39], v[0:1] op_sel_hi:[1,0]
	v_pk_mul_f32 v[54:55], v[54:55], v[0:1] op_sel_hi:[1,0]
	v_pk_mul_f32 v[52:53], v[52:53], v[0:1] op_sel_hi:[1,0]
	s_waitcnt vmcnt(8)
	v_mfma_f32_16x16x32_bf16 v[26:29], v[26:29], v[88:91], v[38:41]
	v_mul_f32_e64 v50, v50, v0
	v_mul_f32_e64 v51, v51, v0
	v_pk_mul_f32 v[48:49], v[48:49], v[0:1] op_sel_hi:[1,0]
	v_pk_mul_f32 v[46:47], v[46:47], v[0:1] op_sel_hi:[1,0]
	s_waitcnt vmcnt(7)
	v_mfma_f32_16x16x32_bf16 v[38:41], v[84:87], v[6:9], 0
	v_mul_f32_e64 v44, v44, v0
	v_mul_f32_e64 v45, v45, v0
	v_add_f32_e32 v0, 0, v71
	v_add_f32_e32 v0, v61, v0
	s_waitcnt vmcnt(5)
	v_mfma_f32_16x16x32_bf16 v[6:9], v[76:79], v[6:9], 0
	v_mfma_f32_16x16x32_bf16 v[38:41], v[72:75], v[2:5], v[38:41]
	s_waitcnt vmcnt(4)
	v_mfma_f32_16x16x32_bf16 v[2:5], v[64:67], v[2:5], v[6:9]
	v_mfma_f32_16x16x32_bf16 v[52:55], v[56:59], v[88:91], v[52:55]
	s_nop 4
	v_max_f32_e32 v6, v39, v39
	v_max_f32_e32 v7, v38, v38
	v_max_f32_e32 v6, v7, v6
	v_max_f32_e32 v7, v41, v41
	v_max_f32_e32 v8, v40, v40
	v_max_f32_e32 v7, v8, v7
	v_max_f32_e32 v8, v5, v5
	v_max_f32_e32 v9, v4, v4
	v_max_f32_e32 v8, v9, v8
	v_max3_f32 v8, v2, v3, v8
	v_max3_f32 v6, v6, v7, v8
	v_mov_b32_e32 v7, v6
	s_nop 1
	v_permlane16_swap_b32_e32 v7, v6
	v_mfma_f32_16x16x32_bf16 v[34:37], v[34:37], v[88:91], v[48:51]
	s_waitcnt lgkmcnt(0)
	v_max_f32_e32 v7, v7, v7
	v_max_f32_e32 v6, v6, v7
	v_mov_b32_e32 v7, v6
	s_nop 1
	v_permlane32_swap_b32_e32 v7, v6
	v_mfma_f32_16x16x32_bf16 v[30:33], v[30:33], v[88:91], v[44:47]
	s_waitcnt lgkmcnt(0)
	v_max3_f32 v6, v69, v6, v7
	v_sub_f32_e32 v8, v38, v6
	v_mul_f32_e32 v8, 0x3fb8aa3b, v8
	v_exp_f32_e32 v83, v8
	v_sub_f32_e32 v8, v39, v6
	v_sub_f32_e32 v2, v2, v6
	v_mul_f32_e32 v8, 0x3fb8aa3b, v8
	v_mul_f32_e32 v2, 0x3fb8aa3b, v2
	v_exp_f32_e32 v81, v8
	v_sub_f32_e32 v8, v40, v6
	v_exp_f32_e32 v63, v2
	v_sub_f32_e32 v2, v3, v6
	v_mul_f32_e32 v8, 0x3fb8aa3b, v8
	v_mul_f32_e32 v2, 0x3fb8aa3b, v2
	v_exp_f32_e32 v71, v8
	v_sub_f32_e32 v8, v41, v6
	v_exp_f32_e32 v61, v2
	v_sub_f32_e32 v2, v4, v6
	v_mul_f32_e32 v8, 0x3fb8aa3b, v8
	v_mul_f32_e32 v2, 0x3fb8aa3b, v2
	v_sub_f32_e32 v7, v69, v6
	v_exp_f32_e32 v69, v8
	v_exp_f32_e32 v43, v2
	v_sub_f32_e32 v2, v5, v6
	v_mul_f32_e32 v2, 0x3fb8aa3b, v2
	v_mul_f32_e32 v7, 0x3fb8aa3b, v7
	v_exp_f32_e32 v39, v2
	v_exp_f32_e32 v38, v7
	v_add_u32_e32 v2, 0x8000, v81
	v_add_u32_e32 v3, 0x8000, v83
	v_perm_b32 v2, v2, v3, s87
	v_add_u32_e32 v3, 0x8000, v69
	v_add_u32_e32 v4, 0x8000, v71
	v_perm_b32 v3, v3, v4, s87
	v_add_u32_e32 v4, 0x8000, v61
	v_add_u32_e32 v5, 0x8000, v63
	v_perm_b32 v4, v4, v5, s87
	v_add_u32_e32 v5, 0x8000, v39
	v_add_u32_e32 v6, 0x8000, v43
	v_perm_b32 v5, v5, v6, s87
	v_pk_mul_f32 v[8:9], v[54:55], v[38:39] op_sel_hi:[1,0]
	v_pk_mul_f32 v[6:7], v[52:53], v[38:39] op_sel_hi:[1,0]
	s_waitcnt vmcnt(3)
	s_nop 0
	v_mfma_f32_16x16x32_bf16 v[6:9], v[22:25], v[2:5], v[6:9]
	v_mul_f32_e64 v24, v36, v38
	v_mul_f32_e64 v25, v37, v38
	v_pk_mul_f32 v[22:23], v[34:35], v[38:39] op_sel_hi:[1,0]
	s_waitcnt vmcnt(2)
	s_nop 0
	v_mfma_f32_16x16x32_bf16 v[18:21], v[18:21], v[2:5], v[22:25]
	s_nop 2
	v_mul_f32_e64 v24, v32, v38
	v_mul_f32_e64 v25, v33, v38
	v_pk_mul_f32 v[22:23], v[30:31], v[38:39] op_sel_hi:[1,0]
	s_waitcnt vmcnt(1)
	s_nop 0
	v_mfma_f32_16x16x32_bf16 v[14:17], v[14:17], v[2:5], v[22:25]
	s_nop 2
	v_mul_f32_e64 v24, v28, v38
	v_mul_f32_e64 v25, v29, v38
	v_pk_mul_f32 v[22:23], v[26:27], v[38:39] op_sel_hi:[1,0]
	s_waitcnt vmcnt(0)
	s_nop 0
	v_mfma_f32_16x16x32_bf16 v[2:5], v[10:13], v[2:5], v[22:25]
	v_add_f32_e64 v10, v82, v0
	v_add_f32_e64 v11, v83, v1
	v_pk_add_f32 v[10:11], v[80:81], v[10:11]
	s_nop 0
	v_pk_add_f32 v[10:11], v[70:71], v[10:11]
	s_nop 0
	v_pk_add_f32 v[10:11], v[68:69], v[10:11]
	s_nop 0
	v_pk_add_f32 v[10:11], v[62:63], v[10:11]
	s_nop 0
	v_pk_add_f32 v[10:11], v[60:61], v[10:11]
	s_nop 0
	v_pk_add_f32 v[10:11], v[42:43], v[10:11]
	s_nop 0
	v_add_f32_e32 v0, v11, v39
	v_fmac_f32_e32 v0, v10, v38
	v_mov_b32_e32 v22, v0
	s_nop 1
	v_permlane16_swap_b32_e32 v22, v0
	v_lshl_add_u64 v[10:11], v[128:129], 0, v[140:141]
	v_lshl_add_u64 v[12:13], v[10:11], 0, s[0:1]
	s_waitcnt lgkmcnt(0)
	v_add_f32_e32 v0, v0, v22
	v_mov_b32_e32 v22, v0
	s_nop 1
	v_permlane32_swap_b32_e32 v22, v0
	s_waitcnt lgkmcnt(0)
	v_add_f32_e32 v0, v0, v22
	v_div_scale_f32 v22, s[0:1], v0, v0, 1.0
	v_rcp_f32_e32 v23, v22
	s_mov_b32 s0, 0xd800000
	v_fma_f32 v24, -v22, v23, 1.0
	v_fmac_f32_e32 v23, v24, v23
	v_div_scale_f32 v24, vcc, 1.0, v0, 1.0
	v_mul_f32_e32 v25, v24, v23
	v_fma_f32 v26, -v22, v25, v24
	v_fmac_f32_e32 v25, v26, v23
	v_fma_f32 v22, -v22, v25, v24
	v_div_fmas_f32 v22, v22, v23, v25
	v_div_fixup_f32 v0, v22, v0, 1.0
	v_mov_b32_e32 v22, v6
	v_mov_b32_e32 v23, v8
	v_pk_mul_f32 v[22:23], v[22:23], v[0:1] op_sel_hi:[1,0]
	v_mov_b32_e32 v8, v7
	v_pk_mul_f32 v[6:7], v[8:9], v[0:1] op_sel_hi:[1,0]
	v_and_b32_sdwa v9, v22, v236 dst_sel:DWORD dst_unused:UNUSED_PAD src0_sel:WORD_1 src1_sel:DWORD
	v_and_b32_sdwa v8, v23, v236 dst_sel:DWORD dst_unused:UNUSED_PAD src0_sel:WORD_1 src1_sel:DWORD
	v_add3_u32 v9, v22, v9, s60
	v_and_b32_sdwa v22, v7, v236 dst_sel:DWORD dst_unused:UNUSED_PAD src0_sel:WORD_1 src1_sel:DWORD
	v_add3_u32 v8, v23, v8, s60
	v_and_b32_sdwa v23, v6, v236 dst_sel:DWORD dst_unused:UNUSED_PAD src0_sel:WORD_1 src1_sel:DWORD
	v_add3_u32 v7, v7, v22, s60
	v_add3_u32 v6, v6, v23, s60
	v_and_b32_e32 v7, 0xffff0000, v7
	v_and_b32_e32 v6, 0xffff0000, v6
	v_or_b32_sdwa v7, v7, v8 dst_sel:DWORD dst_unused:UNUSED_PAD src0_sel:DWORD src1_sel:WORD_1
	v_add_co_u32_e32 v8, vcc, s0, v10
	v_or_b32_sdwa v6, v6, v9 dst_sel:DWORD dst_unused:UNUSED_PAD src0_sel:DWORD src1_sel:WORD_1
	s_nop 0
	v_addc_co_u32_e32 v9, vcc, 0, v11, vcc
	global_store_dwordx2 v[8:9], v[6:7], off offset:512
	v_mov_b32_e32 v6, v18
	v_mov_b32_e32 v7, v20
	v_pk_mul_f32 v[6:7], v[6:7], v[0:1] op_sel_hi:[1,0]
	v_mov_b32_e32 v20, v19
	v_pk_mul_f32 v[8:9], v[20:21], v[0:1] op_sel_hi:[1,0]
	v_and_b32_sdwa v10, v7, v236 dst_sel:DWORD dst_unused:UNUSED_PAD src0_sel:WORD_1 src1_sel:DWORD
	v_and_b32_sdwa v11, v6, v236 dst_sel:DWORD dst_unused:UNUSED_PAD src0_sel:WORD_1 src1_sel:DWORD
	v_add3_u32 v6, v6, v11, s60
	v_add3_u32 v7, v7, v10, s60
	v_and_b32_sdwa v10, v9, v236 dst_sel:DWORD dst_unused:UNUSED_PAD src0_sel:WORD_1 src1_sel:DWORD
	v_and_b32_sdwa v11, v8, v236 dst_sel:DWORD dst_unused:UNUSED_PAD src0_sel:WORD_1 src1_sel:DWORD
	v_add3_u32 v9, v9, v10, s60
	v_add3_u32 v8, v8, v11, s60
	v_and_b32_e32 v9, 0xffff0000, v9
	v_and_b32_e32 v8, 0xffff0000, v8
	v_or_b32_sdwa v7, v9, v7 dst_sel:DWORD dst_unused:UNUSED_PAD src0_sel:DWORD src1_sel:WORD_1
	v_or_b32_sdwa v6, v8, v6 dst_sel:DWORD dst_unused:UNUSED_PAD src0_sel:DWORD src1_sel:WORD_1
	global_store_dwordx2 v[12:13], v[6:7], off offset:32
	v_mov_b32_e32 v6, v14
	v_mov_b32_e32 v7, v16
	v_pk_mul_f32 v[6:7], v[6:7], v[0:1] op_sel_hi:[1,0]
	v_mov_b32_e32 v16, v15
	v_pk_mul_f32 v[8:9], v[16:17], v[0:1] op_sel_hi:[1,0]
	v_and_b32_sdwa v10, v7, v236 dst_sel:DWORD dst_unused:UNUSED_PAD src0_sel:WORD_1 src1_sel:DWORD
	v_and_b32_sdwa v11, v6, v236 dst_sel:DWORD dst_unused:UNUSED_PAD src0_sel:WORD_1 src1_sel:DWORD
	v_add3_u32 v6, v6, v11, s60
	v_add3_u32 v7, v7, v10, s60
	v_and_b32_sdwa v10, v9, v236 dst_sel:DWORD dst_unused:UNUSED_PAD src0_sel:WORD_1 src1_sel:DWORD
	v_and_b32_sdwa v11, v8, v236 dst_sel:DWORD dst_unused:UNUSED_PAD src0_sel:WORD_1 src1_sel:DWORD
	v_add3_u32 v9, v9, v10, s60
	v_add3_u32 v8, v8, v11, s60
	v_and_b32_e32 v9, 0xffff0000, v9
	v_and_b32_e32 v8, 0xffff0000, v8
	v_or_b32_sdwa v7, v9, v7 dst_sel:DWORD dst_unused:UNUSED_PAD src0_sel:DWORD src1_sel:WORD_1
	v_or_b32_sdwa v6, v8, v6 dst_sel:DWORD dst_unused:UNUSED_PAD src0_sel:DWORD src1_sel:WORD_1
	global_store_dwordx2 v[12:13], v[6:7], off offset:64
	v_mov_b32_e32 v6, v2
	v_mov_b32_e32 v7, v4
	v_pk_mul_f32 v[6:7], v[6:7], v[0:1] op_sel_hi:[1,0]
	v_mov_b32_e32 v4, v3
	v_pk_mul_f32 v[2:3], v[4:5], v[0:1] op_sel_hi:[1,0]
	v_and_b32_sdwa v4, v6, v236 dst_sel:DWORD dst_unused:UNUSED_PAD src0_sel:WORD_1 src1_sel:DWORD
	v_add3_u32 v4, v6, v4, s60
	v_and_b32_sdwa v5, v3, v236 dst_sel:DWORD dst_unused:UNUSED_PAD src0_sel:WORD_1 src1_sel:DWORD
	v_and_b32_sdwa v6, v2, v236 dst_sel:DWORD dst_unused:UNUSED_PAD src0_sel:WORD_1 src1_sel:DWORD
	v_and_b32_sdwa v0, v7, v236 dst_sel:DWORD dst_unused:UNUSED_PAD src0_sel:WORD_1 src1_sel:DWORD
	v_add3_u32 v3, v3, v5, s60
	v_add3_u32 v2, v2, v6, s60
	v_add3_u32 v0, v7, v0, s60
	v_and_b32_e32 v3, 0xffff0000, v3
	v_and_b32_e32 v2, 0xffff0000, v2
	v_or_b32_sdwa v3, v3, v0 dst_sel:DWORD dst_unused:UNUSED_PAD src0_sel:DWORD src1_sel:WORD_1
	v_or_b32_sdwa v2, v2, v4 dst_sel:DWORD dst_unused:UNUSED_PAD src0_sel:DWORD src1_sel:WORD_1
	global_store_dwordx2 v[12:13], v[2:3], off offset:96

.LBB0_1081:
	s_or_b64 exec, exec, s[34:35]
	v_cmp_lt_i32_e32 vcc, v231, v226
	v_max_f32_e32 v13, v66, v66
	v_max_f32_e32 v67, v77, v77
	v_cndmask_b32_e32 v12, v225, v231, vcc
	v_lshlrev_b32_e32 v137, 2, v12
	v_max_f32_e32 v12, v0, v0
	v_max_f32_e32 v12, v13, v12
	v_max_f32_e32 v13, v76, v76
	v_max_f32_e32 v13, v67, v13
	v_max_f32_e32 v67, v10, v10
	v_max_f32_e32 v92, v11, v11
	v_max_f32_e32 v67, v92, v67
	v_max3_f32 v67, v79, v78, v67
	v_max3_f32 v12, v12, v13, v67
	v_mov_b32_e32 v13, v12
	s_nop 1
	v_permlane16_swap_b32_e32 v13, v12
	v_cmp_lt_i32_e32 vcc, v232, v226
	s_mov_b32 s1, 0xf149f2ca
	v_mov_b32_e32 v149, v1
	v_cndmask_b32_e32 v67, v225, v232, vcc
	s_waitcnt lgkmcnt(0)
	v_max_f32_e32 v13, v13, v13
	v_lshlrev_b32_e32 v139, 2, v67
	v_max_f32_e32 v12, v12, v13
	v_mov_b32_e32 v13, v12
	s_nop 1
	v_permlane32_swap_b32_e32 v13, v12
	v_mov_b32_e32 v145, v1
	v_mfma_f32_16x16x32_bf16 v[34:37], v[34:37], v[6:9], 0
	v_mov_b32_e32 v143, v1
	v_mov_b32_e32 v147, v1
	s_waitcnt lgkmcnt(0)
	v_max3_f32 v121, v12, v13, s1
	v_sub_f32_e32 v0, v0, v121
	v_mul_f32_e32 v0, 0x3fb8aa3b, v0
	v_exp_f32_e32 v155, v0
	v_sub_f32_e32 v0, v77, v121
	v_mul_f32_e32 v0, 0x3fb8aa3b, v0
	v_exp_f32_e32 v157, v0
	v_sub_f32_e32 v0, v76, v121
	v_mul_f32_e32 v0, 0x3fb8aa3b, v0
	v_exp_f32_e32 v159, v0
	v_sub_f32_e32 v0, v79, v121
	v_mul_f32_e32 v0, 0x3fb8aa3b, v0
	v_exp_f32_e32 v160, v0
	v_sub_f32_e32 v0, v78, v121
	v_mul_f32_e32 v0, 0x3fb8aa3b, v0
	v_sub_f32_e32 v12, 0xf149f2ca, v121
	v_sub_f32_e32 v13, v66, v121
	v_exp_f32_e32 v161, v0
	v_sub_f32_e32 v0, v11, v121
	v_mul_f32_e32 v12, 0x3fb8aa3b, v12
	v_mul_f32_e32 v13, 0x3fb8aa3b, v13
	v_mul_f32_e32 v0, 0x3fb8aa3b, v0
	v_exp_f32_e32 v153, v13
	v_exp_f32_e32 v162, v0
	v_exp_f32_e32 v0, v12
	v_sub_f32_e32 v10, v10, v121
	v_mul_f32_e32 v10, 0x3fb8aa3b, v10
	v_exp_f32_e32 v163, v10
	v_mul_f32_e32 v10, 0, v0
	v_add_u32_e32 v0, 0x8000, v155
	v_add_u32_e32 v11, 0x8000, v153
	v_perm_b32 v76, v0, v11, s87
	v_add_u32_e32 v0, 0x8000, v159
	v_add_u32_e32 v11, 0x8000, v157
	v_perm_b32 v77, v0, v11, s87
	v_add_u32_e32 v0, 0x8000, v161
	v_add_u32_e32 v11, 0x8000, v160
	v_perm_b32 v78, v0, v11, s87
	v_add_u32_e32 v0, 0x8000, v163
	v_add_u32_e32 v11, 0x8000, v162
	v_perm_b32 v79, v0, v11, s87
	v_mov_b32_e32 v11, v10
	v_mov_b32_e32 v12, v10
	v_mov_b32_e32 v13, v10
	v_mfma_f32_16x16x32_bf16 v[122:125], v[100:103], v[6:9], 0
	s_nop 0
	v_mfma_f32_16x16x32_bf16 v[116:119], v[50:53], v[76:79], v[10:13]
	v_add_u32_e32 v50, 0xc0, v150
	v_lshlrev_b32_e32 v0, 7, v50
	v_mfma_f32_16x16x32_bf16 v[104:107], v[62:65], v[76:79], v[10:13]
	v_mfma_f32_16x16x32_bf16 v[108:111], v[72:75], v[76:79], v[10:13]
	v_mfma_f32_16x16x32_bf16 v[112:115], v[42:45], v[76:79], v[10:13]
	s_nop 2
	v_lshl_add_u64 v[12:13], s[30:31], 0, v[0:1]
	v_mul_lo_u32 v0, v50, s33
	v_lshl_add_u64 v[42:43], s[28:29], 0, v[0:1]
	v_lshl_add_u64 v[42:43], v[42:43], 0, v[148:149]
	v_lshl_add_u64 v[42:43], v[42:43], 0, v[144:145]
	global_load_dwordx4 v[92:95], v[42:43], off
	global_load_dwordx4 v[72:75], v[42:43], off offset:16
	global_load_dwordx4 v[76:79], v[42:43], off offset:3072
	global_load_dwordx4 v[64:67], v[42:43], off offset:3088
	v_lshl_add_u64 v[12:13], v[12:13], 0, v[142:143]
	v_lshl_add_u64 v[12:13], v[12:13], 0, v[146:147]
	global_load_dwordx4 v[50:53], v[12:13], off
	global_load_dwordx4 v[42:45], v[12:13], off offset:256
	v_mfma_f32_16x16x32_bf16 v[100:103], v[30:33], v[2:5], v[34:37]
	s_nop 2
	global_load_dwordx4 v[34:37], v[12:13], off offset:512
	global_load_dwordx4 v[30:33], v[12:13], off offset:768
	v_mov_b32_e32 v0, 0xff800000
	v_mov_b32_e32 v11, 0xff800000
	v_mfma_f32_16x16x32_bf16 v[96:99], v[96:99], v[2:5], v[122:125]
	s_and_saveexec_b64 s[34:35], s[12:13]
	s_cbranch_execz .LBB0_1083
	v_lshl_add_u32 v11, v156, 2, v151
	ds_read_b32 v11, v11 offset:1052
	s_waitcnt lgkmcnt(0)
	v_add_f32_e32 v11, v100, v11

.LBB0_1097:
	s_or_b64 exec, exec, s[34:35]
	v_max_f32_e32 v12, v0, v0
	v_max_f32_e32 v98, v11, v11
	v_max_f32_e32 v12, v98, v12
	v_max_f32_e32 v98, v13, v13
	v_max_f32_e32 v99, v62, v62
	v_max_f32_e32 v98, v99, v98
	v_max_f32_e32 v99, v96, v96
	v_max_f32_e32 v101, v97, v97
	v_max_f32_e32 v99, v101, v99
	v_max3_f32 v99, v100, v63, v99
	v_max3_f32 v12, v12, v98, v99
	v_mov_b32_e32 v98, v12
	s_nop 1
	v_permlane16_swap_b32_e32 v98, v12
	v_mov_b32_e32 v149, v1
	v_mov_b32_e32 v145, v1
	v_mov_b32_e32 v143, v1
	v_mov_b32_e32 v147, v1
	s_waitcnt lgkmcnt(0)
	v_max_f32_e32 v98, v98, v98
	v_max_f32_e32 v12, v12, v98
	v_mov_b32_e32 v98, v12
	s_nop 1
	v_permlane32_swap_b32_e32 v98, v12
	s_waitcnt vmcnt(14)
	v_mfma_f32_16x16x32_bf16 v[122:125], v[46:49], v[6:9], 0
	s_waitcnt lgkmcnt(0)
	v_max3_f32 v12, v121, v12, v98
	v_sub_f32_e32 v0, v0, v12
	v_mul_f32_e32 v0, 0x3fb8aa3b, v0
	v_exp_f32_e32 v164, v0
	v_sub_f32_e32 v0, v62, v12
	v_mul_f32_e32 v0, 0x3fb8aa3b, v0
	v_exp_f32_e32 v165, v0
	v_sub_f32_e32 v0, v13, v12
	v_mul_f32_e32 v0, 0x3fb8aa3b, v0
	v_exp_f32_e32 v166, v0
	v_sub_f32_e32 v0, v100, v12
	v_mul_f32_e32 v0, 0x3fb8aa3b, v0
	v_exp_f32_e32 v167, v0
	v_sub_f32_e32 v0, v63, v12
	v_sub_f32_e32 v11, v11, v12
	v_mul_f32_e32 v0, 0x3fb8aa3b, v0
	v_mul_f32_e32 v11, 0x3fb8aa3b, v11
	v_exp_f32_e32 v168, v0
	v_sub_f32_e32 v0, v97, v12
	v_exp_f32_e32 v11, v11
	v_mul_f32_e32 v0, 0x3fb8aa3b, v0
	v_exp_f32_e32 v169, v0
	v_sub_f32_e32 v0, v96, v12
	v_sub_f32_e32 v98, v121, v12
	v_mul_f32_e32 v0, 0x3fb8aa3b, v0
	v_mul_f32_e32 v98, 0x3fb8aa3b, v98
	v_exp_f32_e32 v170, v0
	v_exp_f32_e32 v152, v98
	v_add_u32_e32 v0, 0x8000, v164
	v_add_u32_e32 v13, 0x8000, v11
	v_perm_b32 v96, v0, v13, s87
	v_add_u32_e32 v0, 0x8000, v166
	v_add_u32_e32 v13, 0x8000, v165
	v_perm_b32 v97, v0, v13, s87
	v_add_u32_e32 v0, 0x8000, v168
	v_add_u32_e32 v13, 0x8000, v167
	v_perm_b32 v98, v0, v13, s87
	v_add_u32_e32 v0, 0x8000, v170
	v_add_u32_e32 v13, 0x8000, v169
	v_perm_b32 v99, v0, v13, s87
	v_pk_mul_f32 v[102:103], v[118:119], v[152:153] op_sel_hi:[1,0]
	v_pk_mul_f32 v[100:101], v[116:117], v[152:153] op_sel_hi:[1,0]
	v_add_u32_e32 v13, 0x100, v150
	v_lshlrev_b32_e32 v0, 7, v13
	v_mfma_f32_16x16x32_bf16 v[100:103], v[88:91], v[96:99], v[100:103]
	v_mul_f32_e64 v90, v106, v152
	v_mul_f32_e64 v91, v107, v152
	v_pk_mul_f32 v[88:89], v[104:105], v[152:153] op_sel_hi:[1,0]
	v_lshl_add_u64 v[62:63], s[30:31], 0, v[0:1]
	v_mul_lo_u32 v0, v13, s33
	v_mfma_f32_16x16x32_bf16 v[104:107], v[84:87], v[96:99], v[88:91]
	v_mul_f32_e64 v86, v110, v152
	v_mul_f32_e64 v87, v111, v152
	v_pk_mul_f32 v[84:85], v[108:109], v[152:153] op_sel_hi:[1,0]
	v_mov_b32_e32 v13, 0xff800000
	s_waitcnt vmcnt(13)
	v_mfma_f32_16x16x32_bf16 v[116:119], v[58:61], v[6:9], 0
	v_lshl_add_u64 v[58:59], v[62:63], 0, v[142:143]
	v_lshl_add_u64 v[58:59], v[58:59], 0, v[146:147]
	v_mfma_f32_16x16x32_bf16 v[108:111], v[80:83], v[96:99], v[84:87]
	v_mul_f32_e64 v82, v114, v152
	v_mul_f32_e64 v83, v115, v152
	v_pk_mul_f32 v[80:81], v[112:113], v[152:153] op_sel_hi:[1,0]
	v_mfma_f32_16x16x32_bf16 v[116:119], v[38:41], v[2:5], v[116:119]
	s_nop 0
	v_mfma_f32_16x16x32_bf16 v[112:115], v[68:71], v[96:99], v[80:83]
	v_lshl_add_u64 v[68:69], s[28:29], 0, v[0:1]
	v_lshl_add_u64 v[68:69], v[68:69], 0, v[148:149]
	v_lshl_add_u64 v[68:69], v[68:69], 0, v[144:145]
	global_load_dwordx4 v[96:99], v[68:69], off
	global_load_dwordx4 v[84:87], v[68:69], off offset:16
	global_load_dwordx4 v[88:91], v[68:69], off offset:3072
	global_load_dwordx4 v[80:83], v[68:69], off offset:3088
	s_nop 0
	global_load_dwordx4 v[68:71], v[58:59], off
	global_load_dwordx4 v[60:63], v[58:59], off offset:256
	global_load_dwordx4 v[46:49], v[58:59], off offset:512
	global_load_dwordx4 v[38:41], v[58:59], off offset:768
	s_waitcnt vmcnt(20)
	v_mfma_f32_16x16x32_bf16 v[54:57], v[54:57], v[2:5], v[122:125]
	v_mov_b32_e32 v0, 0xff800000
	s_and_saveexec_b64 s[34:35], s[12:13]
	s_cbranch_execz .LBB0_1099
	v_lshl_add_u32 v13, v156, 2, v151
	ds_read_b32 v13, v13 offset:1176
	s_waitcnt lgkmcnt(0)
	v_add_f32_e32 v13, v116, v13

.LBB0_1113:
	s_or_b64 exec, exec, s[34:35]
	v_max_f32_e32 v56, v0, v0
	v_max_f32_e32 v57, v13, v13
	v_max_f32_e32 v56, v57, v56
	v_max_f32_e32 v57, v58, v58
	v_max_f32_e32 v119, v59, v59
	v_max_f32_e32 v57, v119, v57
	v_max_f32_e32 v119, v55, v55
	v_max_f32_e32 v120, v118, v118
	v_max_f32_e32 v119, v120, v119
	v_max3_f32 v119, v117, v116, v119
	v_max3_f32 v56, v56, v57, v119
	v_mov_b32_e32 v57, v56
	s_nop 1
	v_permlane16_swap_b32_e32 v57, v56
	v_mov_b32_e32 v149, v1
	v_mov_b32_e32 v145, v1
	v_mov_b32_e32 v143, v1
	v_mov_b32_e32 v147, v1
	s_waitcnt lgkmcnt(0)
	v_max_f32_e32 v57, v57, v57
	v_max_f32_e32 v56, v56, v57
	v_mov_b32_e32 v57, v56
	s_nop 1
	v_permlane32_swap_b32_e32 v57, v56
	s_waitcnt vmcnt(13)
	v_mfma_f32_16x16x32_bf16 v[76:79], v[76:79], v[6:9], 0
	v_lshl_add_u32 v179, v156, 2, v151
	s_waitcnt lgkmcnt(0)
	v_max3_f32 v193, v12, v56, v57
	v_sub_f32_e32 v0, v0, v193
	v_mul_f32_e32 v0, 0x3fb8aa3b, v0
	v_exp_f32_e32 v172, v0
	v_sub_f32_e32 v0, v59, v193
	v_mul_f32_e32 v0, 0x3fb8aa3b, v0
	v_exp_f32_e32 v173, v0
	v_sub_f32_e32 v0, v58, v193
	v_mul_f32_e32 v0, 0x3fb8aa3b, v0
	v_exp_f32_e32 v174, v0
	v_sub_f32_e32 v0, v117, v193
	v_mul_f32_e32 v0, 0x3fb8aa3b, v0
	v_exp_f32_e32 v175, v0
	v_sub_f32_e32 v0, v116, v193
	v_sub_f32_e32 v13, v13, v193
	v_mul_f32_e32 v0, 0x3fb8aa3b, v0
	v_mul_f32_e32 v13, 0x3fb8aa3b, v13
	v_exp_f32_e32 v176, v0
	v_sub_f32_e32 v0, v118, v193
	v_exp_f32_e32 v171, v13
	v_mul_f32_e32 v0, 0x3fb8aa3b, v0
	v_exp_f32_e32 v177, v0
	v_sub_f32_e32 v0, v55, v193
	v_sub_f32_e32 v12, v12, v193
	v_mul_f32_e32 v0, 0x3fb8aa3b, v0
	v_mul_f32_e32 v12, 0x3fb8aa3b, v12
	v_exp_f32_e32 v178, v0
	v_exp_f32_e32 v154, v12
	v_add_u32_e32 v0, 0x8000, v172
	v_add_u32_e32 v12, 0x8000, v171
	v_perm_b32 v56, v0, v12, s87
	v_add_u32_e32 v0, 0x8000, v174
	v_add_u32_e32 v12, 0x8000, v173
	v_perm_b32 v57, v0, v12, s87
	v_add_u32_e32 v0, 0x8000, v176
	v_add_u32_e32 v12, 0x8000, v175
	v_perm_b32 v58, v0, v12, s87
	v_add_u32_e32 v0, 0x8000, v178
	v_add_u32_e32 v12, 0x8000, v177
	v_perm_b32 v59, v0, v12, s87
	v_pk_mul_f32 v[102:103], v[102:103], v[154:155] op_sel_hi:[1,0]
	v_pk_mul_f32 v[100:101], v[100:101], v[154:155] op_sel_hi:[1,0]
	v_add_u32_e32 v12, 0x140, v150
	v_lshlrev_b32_e32 v0, 7, v12
	v_mfma_f32_16x16x32_bf16 v[26:29], v[26:29], v[56:59], v[100:103]
	s_nop 2
	v_mul_f32_e64 v102, v106, v154
	v_mul_f32_e64 v103, v107, v154
	v_pk_mul_f32 v[100:101], v[104:105], v[154:155] op_sel_hi:[1,0]
	s_waitcnt vmcnt(12)
	v_mfma_f32_16x16x32_bf16 v[64:67], v[64:67], v[2:5], v[76:79]
	v_mfma_f32_16x16x32_bf16 v[100:103], v[22:25], v[56:59], v[100:103]
	v_mul_f32_e64 v24, v110, v154
	v_mul_f32_e64 v25, v111, v154
	v_pk_mul_f32 v[22:23], v[108:109], v[154:155] op_sel_hi:[1,0]
	s_nop 1
	v_mfma_f32_16x16x32_bf16 v[104:107], v[18:21], v[56:59], v[22:25]
	v_mul_f32_e64 v20, v114, v154
	v_mul_f32_e64 v21, v115, v154
	v_pk_mul_f32 v[18:19], v[112:113], v[154:155] op_sel_hi:[1,0]
	s_nop 1
	v_mfma_f32_16x16x32_bf16 v[108:111], v[14:17], v[56:59], v[18:21]
	v_lshl_add_u64 v[16:17], s[30:31], 0, v[0:1]
	v_mul_lo_u32 v0, v12, s33
	v_lshl_add_u64 v[12:13], s[28:29], 0, v[0:1]
	v_lshl_add_u64 v[12:13], v[12:13], 0, v[148:149]
	v_lshl_add_u64 v[12:13], v[12:13], 0, v[144:145]
	global_load_dwordx4 v[128:131], v[12:13], off
	global_load_dwordx4 v[120:123], v[12:13], off offset:16
	global_load_dwordx4 v[124:127], v[12:13], off offset:3072
	global_load_dwordx4 v[116:119], v[12:13], off offset:3088
	v_mfma_f32_16x16x32_bf16 v[12:15], v[92:95], v[6:9], 0
	v_lshl_add_u64 v[16:17], v[16:17], 0, v[142:143]
	v_lshl_add_u64 v[24:25], v[16:17], 0, v[146:147]
	global_load_dwordx4 v[56:59], v[24:25], off
	global_load_dwordx4 v[20:23], v[24:25], off offset:256
	v_mfma_f32_16x16x32_bf16 v[72:75], v[72:75], v[2:5], v[12:15]
	global_load_dwordx4 v[16:19], v[24:25], off offset:512
	s_nop 1
	global_load_dwordx4 v[12:15], v[24:25], off offset:768
	s_and_saveexec_b64 s[34:35], s[12:13]
	s_cbranch_execz .LBB0_1115
	ds_read_b32 v0, v179 offset:1300
	s_waitcnt lgkmcnt(0)
	v_add_f32_e32 v54, v72, v0

.LBB0_1129:
	s_or_b64 exec, exec, s[34:35]
	v_max_f32_e32 v66, v24, v24
	v_max_f32_e32 v67, v54, v54
	v_max_f32_e32 v66, v67, v66
	v_max_f32_e32 v67, v72, v72
	v_max_f32_e32 v74, v0, v0
	v_max_f32_e32 v67, v74, v67
	v_max_f32_e32 v74, v65, v65
	v_max_f32_e32 v75, v64, v64
	v_max_f32_e32 v74, v75, v74
	v_max3_f32 v74, v25, v73, v74
	v_max3_f32 v66, v66, v67, v74
	v_mov_b32_e32 v67, v66
	s_nop 1
	v_permlane16_swap_b32_e32 v67, v66
	v_mov_b32_e32 v149, v1
	v_mov_b32_e32 v145, v1
	v_mov_b32_e32 v143, v1
	v_mov_b32_e32 v147, v1
	s_waitcnt lgkmcnt(0)
	v_max_f32_e32 v67, v67, v67
	v_max_f32_e32 v66, v66, v67
	v_mov_b32_e32 v67, v66
	s_nop 1
	v_permlane32_swap_b32_e32 v67, v66
	s_waitcnt vmcnt(13)
	v_mfma_f32_16x16x32_bf16 v[88:91], v[88:91], v[6:9], 0
	s_waitcnt lgkmcnt(0)
	v_max3_f32 v158, v193, v66, v67
	v_sub_f32_e32 v0, v0, v158
	v_mul_f32_e32 v0, 0x3fb8aa3b, v0
	v_exp_f32_e32 v194, v0
	v_sub_f32_e32 v0, v72, v158
	v_mul_f32_e32 v0, 0x3fb8aa3b, v0
	v_exp_f32_e32 v195, v0
	v_sub_f32_e32 v0, v25, v158
	v_mul_f32_e32 v0, 0x3fb8aa3b, v0
	v_exp_f32_e32 v196, v0
	v_sub_f32_e32 v0, v73, v158
	v_sub_f32_e32 v54, v54, v158
	v_sub_f32_e32 v24, v24, v158
	v_mul_f32_e32 v0, 0x3fb8aa3b, v0
	v_mul_f32_e32 v54, 0x3fb8aa3b, v54
	v_mul_f32_e32 v24, 0x3fb8aa3b, v24
	v_exp_f32_e32 v197, v0
	v_sub_f32_e32 v0, v64, v158
	v_sub_f32_e32 v66, v193, v158
	v_exp_f32_e32 v191, v54
	v_exp_f32_e32 v193, v24
	v_mul_f32_e32 v0, 0x3fb8aa3b, v0
	v_exp_f32_e32 v198, v0
	v_sub_f32_e32 v0, v65, v158
	v_mul_f32_e32 v0, 0x3fb8aa3b, v0
	v_mul_f32_e32 v66, 0x3fb8aa3b, v66
	v_exp_f32_e32 v199, v0
	v_exp_f32_e32 v156, v66
	v_add_u32_e32 v0, 0x8000, v193
	v_add_u32_e32 v24, 0x8000, v191
	v_perm_b32 v64, v0, v24, s87
	v_add_u32_e32 v0, 0x8000, v195
	v_add_u32_e32 v24, 0x8000, v194
	v_perm_b32 v65, v0, v24, s87
	v_add_u32_e32 v0, 0x8000, v197
	v_add_u32_e32 v24, 0x8000, v196
	v_perm_b32 v66, v0, v24, s87
	v_add_u32_e32 v0, 0x8000, v199
	v_add_u32_e32 v24, 0x8000, v198
	v_perm_b32 v67, v0, v24, s87
	v_pk_mul_f32 v[28:29], v[28:29], v[156:157] op_sel_hi:[1,0]
	v_pk_mul_f32 v[26:27], v[26:27], v[156:157] op_sel_hi:[1,0]
	v_pk_mul_f32 v[24:25], v[100:101], v[156:157] op_sel_hi:[1,0]
	s_waitcnt vmcnt(12)
	v_mfma_f32_16x16x32_bf16 v[80:83], v[80:83], v[2:5], v[88:91]
	v_mfma_f32_16x16x32_bf16 v[50:53], v[50:53], v[64:67], v[26:29]
	s_nop 2
	v_mul_f32_e64 v26, v102, v156
	v_mul_f32_e64 v27, v103, v156
	s_nop 1
	v_mfma_f32_16x16x32_bf16 v[42:45], v[42:45], v[64:67], v[24:27]
	s_nop 2
	v_mul_f32_e64 v26, v106, v156
	v_mul_f32_e64 v27, v107, v156
	v_pk_mul_f32 v[24:25], v[104:105], v[156:157] op_sel_hi:[1,0]
	s_nop 1
	v_mfma_f32_16x16x32_bf16 v[92:95], v[34:37], v[64:67], v[24:27]
	s_nop 2
	v_mul_f32_e64 v26, v110, v156
	v_mul_f32_e64 v27, v111, v156
	v_pk_mul_f32 v[24:25], v[108:109], v[156:157] op_sel_hi:[1,0]
	s_nop 1
	v_mfma_f32_16x16x32_bf16 v[100:103], v[30:33], v[64:67], v[24:27]
	s_nop 2
	v_add_u32_e32 v24, 0x180, v150
	v_lshlrev_b32_e32 v0, 7, v24
	v_lshl_add_u64 v[36:37], s[30:31], 0, v[0:1]
	v_mul_lo_u32 v0, v24, s33
	v_lshl_add_u64 v[24:25], s[28:29], 0, v[0:1]
	v_lshl_add_u64 v[24:25], v[24:25], 0, v[148:149]
	v_lshl_add_u64 v[24:25], v[24:25], 0, v[144:145]
	global_load_dwordx4 v[112:115], v[24:25], off
	global_load_dwordx4 v[28:31], v[24:25], off offset:16
	global_load_dwordx4 v[32:35], v[24:25], off offset:3072
	global_load_dwordx4 v[104:107], v[24:25], off offset:3088
	v_mfma_f32_16x16x32_bf16 v[24:27], v[96:99], v[6:9], 0
	v_lshl_add_u64 v[36:37], v[36:37], 0, v[142:143]
	v_lshl_add_u64 v[36:37], v[36:37], 0, v[146:147]
	global_load_dwordx4 v[76:79], v[36:37], off
	global_load_dwordx4 v[72:75], v[36:37], off offset:256
	v_mfma_f32_16x16x32_bf16 v[84:87], v[84:87], v[2:5], v[24:27]
	global_load_dwordx4 v[64:67], v[36:37], off offset:512
	s_nop 1
	global_load_dwordx4 v[24:27], v[36:37], off offset:768
	s_and_saveexec_b64 s[34:35], s[12:13]
	s_cbranch_execz .LBB0_1131
	ds_read_b32 v0, v179 offset:1424
	s_waitcnt lgkmcnt(0)
	v_add_f32_e32 v55, v84, v0

.LBB0_1145:
	s_or_b64 exec, exec, s[34:35]
	v_max_f32_e32 v82, v36, v36
	v_max_f32_e32 v83, v55, v55
	v_max_f32_e32 v82, v83, v82
	v_max_f32_e32 v83, v54, v54
	v_max_f32_e32 v85, v0, v0
	v_max_f32_e32 v83, v85, v83
	v_max_f32_e32 v85, v81, v81
	v_max_f32_e32 v86, v80, v80
	v_max_f32_e32 v85, v86, v85
	v_max3_f32 v85, v37, v84, v85
	v_max3_f32 v82, v82, v83, v85
	v_mov_b32_e32 v83, v82
	s_nop 1
	v_permlane16_swap_b32_e32 v83, v82
	v_mov_b32_e32 v149, v1
	v_mov_b32_e32 v145, v1
	v_mov_b32_e32 v143, v1
	v_mov_b32_e32 v147, v1
	s_waitcnt lgkmcnt(0)
	v_max_f32_e32 v83, v83, v83
	v_max_f32_e32 v82, v82, v83
	v_mov_b32_e32 v83, v82
	s_nop 1
	v_permlane32_swap_b32_e32 v83, v82
	s_waitcnt vmcnt(13)
	v_mfma_f32_16x16x32_bf16 v[124:127], v[124:127], v[6:9], 0
	s_waitcnt lgkmcnt(0)
	v_max3_f32 v208, v158, v82, v83
	v_sub_f32_e32 v0, v0, v208
	v_mul_f32_e32 v0, 0x3fb8aa3b, v0
	v_exp_f32_e32 v202, v0
	v_sub_f32_e32 v0, v54, v208
	v_mul_f32_e32 v0, 0x3fb8aa3b, v0
	v_exp_f32_e32 v203, v0
	v_sub_f32_e32 v0, v37, v208
	v_mul_f32_e32 v0, 0x3fb8aa3b, v0
	v_exp_f32_e32 v204, v0
	v_sub_f32_e32 v0, v84, v208
	v_sub_f32_e32 v55, v55, v208
	v_sub_f32_e32 v36, v36, v208
	v_mul_f32_e32 v0, 0x3fb8aa3b, v0
	v_mul_f32_e32 v55, 0x3fb8aa3b, v55
	v_mul_f32_e32 v36, 0x3fb8aa3b, v36
	v_exp_f32_e32 v205, v0
	v_sub_f32_e32 v0, v80, v208
	v_exp_f32_e32 v200, v55
	v_exp_f32_e32 v201, v36
	v_mul_f32_e32 v0, 0x3fb8aa3b, v0
	v_exp_f32_e32 v206, v0
	v_sub_f32_e32 v0, v81, v208
	v_sub_f32_e32 v82, v158, v208
	v_mul_f32_e32 v0, 0x3fb8aa3b, v0
	v_mul_f32_e32 v82, 0x3fb8aa3b, v82
	v_exp_f32_e32 v207, v0
	v_exp_f32_e32 v158, v82
	v_add_u32_e32 v0, 0x8000, v201
	v_add_u32_e32 v36, 0x8000, v200
	v_perm_b32 v88, v0, v36, s87
	v_add_u32_e32 v0, 0x8000, v203
	v_add_u32_e32 v36, 0x8000, v202
	v_perm_b32 v89, v0, v36, s87
	v_add_u32_e32 v0, 0x8000, v205
	v_add_u32_e32 v36, 0x8000, v204
	v_perm_b32 v90, v0, v36, s87
	v_add_u32_e32 v0, 0x8000, v207
	v_add_u32_e32 v36, 0x8000, v206
	v_perm_b32 v91, v0, v36, s87
	v_pk_mul_f32 v[44:45], v[44:45], v[158:159] op_sel_hi:[1,0]
	v_pk_mul_f32 v[42:43], v[42:43], v[158:159] op_sel_hi:[1,0]
	v_pk_mul_f32 v[52:53], v[52:53], v[158:159] op_sel_hi:[1,0]
	v_pk_mul_f32 v[50:51], v[50:51], v[158:159] op_sel_hi:[1,0]
	v_mfma_f32_16x16x32_bf16 v[80:83], v[60:63], v[88:91], v[42:45]
	s_nop 2
	v_mul_f32_e64 v44, v94, v158
	v_mul_f32_e64 v45, v95, v158
	v_pk_mul_f32 v[42:43], v[92:93], v[158:159] op_sel_hi:[1,0]
	v_mfma_f32_16x16x32_bf16 v[84:87], v[68:71], v[88:91], v[50:53]
	s_nop 0
	v_mfma_f32_16x16x32_bf16 v[68:71], v[46:49], v[88:91], v[42:45]
	s_nop 2
	v_mul_f32_e64 v44, v102, v158
	v_mul_f32_e64 v45, v103, v158
	v_pk_mul_f32 v[42:43], v[100:101], v[158:159] op_sel_hi:[1,0]
	s_nop 1
	v_mfma_f32_16x16x32_bf16 v[36:39], v[38:41], v[88:91], v[42:45]
	v_add_u32_e32 v40, 0x1c0, v150
	v_lshlrev_b32_e32 v0, 7, v40
	s_nop 0
	v_lshl_add_u64 v[44:45], s[30:31], 0, v[0:1]
	v_mul_lo_u32 v0, v40, s33
	v_lshl_add_u64 v[40:41], s[28:29], 0, v[0:1]
	v_lshl_add_u64 v[40:41], v[40:41], 0, v[148:149]
	v_lshl_add_u64 v[40:41], v[40:41], 0, v[144:145]
	global_load_dwordx4 v[108:111], v[40:41], off
	global_load_dwordx4 v[96:99], v[40:41], off offset:16
	global_load_dwordx4 v[100:103], v[40:41], off offset:3072
	global_load_dwordx4 v[92:95], v[40:41], off offset:3088
	v_lshl_add_u64 v[44:45], v[44:45], 0, v[142:143]
	v_lshl_add_u64 v[44:45], v[44:45], 0, v[146:147]
	global_load_dwordx4 v[60:63], v[44:45], off
	global_load_dwordx4 v[52:55], v[44:45], off offset:256
	global_load_dwordx4 v[48:51], v[44:45], off offset:512
	s_nop 0
	global_load_dwordx4 v[44:47], v[44:45], off offset:768
	v_mfma_f32_16x16x32_bf16 v[40:43], v[128:131], v[6:9], 0
	v_mfma_f32_16x16x32_bf16 v[88:91], v[120:123], v[2:5], v[40:43]
	s_waitcnt vmcnt(20)
	v_mfma_f32_16x16x32_bf16 v[40:43], v[116:119], v[2:5], v[124:127]
	s_and_saveexec_b64 s[28:29], s[12:13]
	s_cbranch_execz .LBB0_1147
	ds_read_b32 v0, v179 offset:1548
	s_waitcnt lgkmcnt(0)
	s_nop 1
	v_add_f32_e32 v151, v88, v0

.LBB0_1161:
	s_or_b64 exec, exec, s[28:29]
	v_max_f32_e32 v42, v88, v88
	v_max_f32_e32 v43, v151, v151
	v_max_f32_e32 v42, v43, v42
	v_max_f32_e32 v43, v90, v90
	v_max_f32_e32 v117, v0, v0
	v_max_f32_e32 v43, v117, v43
	v_max_f32_e32 v117, v41, v41
	v_max_f32_e32 v118, v40, v40
	v_max_f32_e32 v117, v118, v117
	v_max3_f32 v117, v89, v91, v117
	v_max3_f32 v42, v42, v43, v117
	v_mov_b32_e32 v43, v42
	s_nop 1
	v_permlane16_swap_b32_e32 v43, v42
	s_lshl_b32 s1, s0, 6
	s_and_b64 s[2:3], s[26:27], exec
	s_cselect_b32 s2, 2, 0
	v_readlane_b32 s3, v255, 21
	s_waitcnt lgkmcnt(0)
	v_max_f32_e32 v43, v43, v43
	v_max_f32_e32 v42, v42, v43
	v_mov_b32_e32 v43, v42
	s_nop 1
	v_permlane32_swap_b32_e32 v43, v42
	s_or_b32 s26, s2, s3
	s_mul_i32 s44, s26, 0x18000
	s_lshl_b64 s[2:3], s[44:45], 1
	s_add_u32 s2, s42, s2
	s_waitcnt lgkmcnt(0)
	v_max3_f32 v117, v208, v42, v43
	v_sub_f32_e32 v0, v0, v117
	v_mul_f32_e32 v0, 0x3fb8aa3b, v0
	v_exp_f32_e32 v127, v0
	v_sub_f32_e32 v0, v90, v117
	v_mul_f32_e32 v0, 0x3fb8aa3b, v0
	v_exp_f32_e32 v128, v0
	v_sub_f32_e32 v0, v89, v117
	v_sub_f32_e32 v43, v151, v117
	v_mul_f32_e32 v0, 0x3fb8aa3b, v0
	v_mul_f32_e32 v43, 0x3fb8aa3b, v43
	v_exp_f32_e32 v129, v0
	v_sub_f32_e32 v0, v91, v117
	v_exp_f32_e32 v125, v43
	v_sub_f32_e32 v43, v88, v117
	v_mul_f32_e32 v0, 0x3fb8aa3b, v0
	v_sub_f32_e32 v42, v208, v117
	v_mul_f32_e32 v43, 0x3fb8aa3b, v43
	v_exp_f32_e32 v208, v0
	v_sub_f32_e32 v0, v40, v117
	v_exp_f32_e32 v126, v43
	v_mul_f32_e32 v0, 0x3fb8aa3b, v0
	v_exp_f32_e32 v209, v0
	v_sub_f32_e32 v0, v41, v117
	v_mul_f32_e32 v0, 0x3fb8aa3b, v0
	v_mul_f32_e32 v42, 0x3fb8aa3b, v42
	v_exp_f32_e32 v210, v0
	s_addc_u32 s3, s43, s3
	s_lshl_b32 s30, s1, 1
	v_exp_f32_e32 v0, v42
	v_add_u32_e32 v40, 0x8000, v126
	v_add_u32_e32 v41, 0x8000, v125
	s_add_u32 s28, s2, s30
	s_mul_i32 s1, s26, 6
	v_perm_b32 v40, v40, v41, s87
	v_add_u32_e32 v41, 0x8000, v128
	v_add_u32_e32 v42, 0x8000, v127
	s_addc_u32 s29, s3, 0
	s_add_i32 s44, s1, s0
	v_perm_b32 v41, v41, v42, s87
	v_add_u32_e32 v42, 0x8000, v208
	v_add_u32_e32 v43, 0x8000, v129
	s_lshl_b64 s[0:1], s[44:45], 15
	v_perm_b32 v42, v42, v43, s87
	v_add_u32_e32 v43, 0x8000, v210
	v_add_u32_e32 v88, 0x8000, v209
	s_add_u32 s26, s46, s0
	v_mov_b32_e32 v149, v1
	v_perm_b32 v43, v43, v88, s87
	v_pk_mul_f32 v[86:87], v[86:87], v[0:1] op_sel_hi:[1,0]
	v_pk_mul_f32 v[84:85], v[84:85], v[0:1] op_sel_hi:[1,0]
	s_addc_u32 s27, s47, s1
	v_mov_b32_e32 v145, v1
	s_waitcnt vmcnt(19)
	v_mfma_f32_16x16x32_bf16 v[56:59], v[56:59], v[40:43], v[84:87]
	v_mul_f32_e64 v38, v38, v0
	v_mul_f32_e64 v39, v39, v0
	v_pk_mul_f32 v[36:37], v[36:37], v[0:1] op_sel_hi:[1,0]
	v_mov_b32_e32 v143, v1
	v_lshl_add_u64 v[84:85], s[28:29], 0, v[148:149]
	s_waitcnt vmcnt(15)
	v_mfma_f32_16x16x32_bf16 v[112:115], v[112:115], v[6:9], 0
	v_mul_f32_e64 v82, v82, v0
	v_mul_f32_e64 v83, v83, v0
	v_pk_mul_f32 v[80:81], v[80:81], v[0:1] op_sel_hi:[1,0]
	v_pk_mul_f32 v[70:71], v[70:71], v[0:1] op_sel_hi:[1,0]
	v_pk_mul_f32 v[68:69], v[68:69], v[0:1] op_sel_hi:[1,0]
	v_lshl_add_u64 v[130:131], v[84:85], 0, v[144:145]
	v_mfma_f32_16x16x32_bf16 v[12:15], v[12:15], v[40:43], v[36:39]
	v_mov_b32_e32 v147, v1
	s_nop 1
	v_lshl_add_u64 v[36:37], s[26:27], 0, v[142:143]
	v_mfma_f32_16x16x32_bf16 v[20:23], v[20:23], v[40:43], v[80:83]
	v_lshl_add_u64 v[150:151], v[36:37], 0, v[146:147]
	global_load_dwordx4 v[88:91], v[130:131], off
	s_nop 0
	global_load_dwordx4 v[80:83], v[130:131], off offset:16
	v_mfma_f32_16x16x32_bf16 v[16:19], v[16:19], v[40:43], v[68:71]
	global_load_dwordx4 v[84:87], v[130:131], off offset:3072
	s_nop 1
	global_load_dwordx4 v[68:71], v[130:131], off offset:3088
	global_load_dwordx4 v[40:43], v[150:151], off
	global_load_dwordx4 v[36:39], v[150:151], off offset:256
	s_waitcnt vmcnt(19)
	v_mfma_f32_16x16x32_bf16 v[118:121], v[32:35], v[6:9], 0
	v_mfma_f32_16x16x32_bf16 v[112:115], v[28:31], v[2:5], v[112:115]
	global_load_dwordx4 v[32:35], v[150:151], off offset:512
	global_load_dwordx4 v[28:31], v[150:151], off offset:768
	s_waitcnt vmcnt(20)
	v_mfma_f32_16x16x32_bf16 v[104:107], v[104:107], v[2:5], v[118:121]
	s_and_saveexec_b64 s[34:35], s[12:13]
	s_cbranch_execz .LBB0_1163
	ds_read_b32 v116, v179 offset:1672
	s_waitcnt lgkmcnt(0)
	v_add_f32_e32 v116, v112, v116

.LBB0_1177:
	s_or_b64 exec, exec, s[34:35]
	v_max_f32_e32 v106, v118, v118
	v_max_f32_e32 v107, v116, v116
	v_max_f32_e32 v106, v107, v106
	v_max_f32_e32 v107, v114, v114
	v_max_f32_e32 v119, v112, v112
	v_max_f32_e32 v107, v119, v107
	v_max_f32_e32 v119, v105, v105
	v_max_f32_e32 v120, v104, v104
	v_max_f32_e32 v119, v120, v119
	v_max3_f32 v119, v113, v115, v119
	v_max3_f32 v106, v106, v107, v119
	v_mov_b32_e32 v107, v106
	s_nop 1
	v_permlane16_swap_b32_e32 v107, v106
	v_mov_b32_e32 v149, v1
	v_mov_b32_e32 v145, v1
	s_mov_b64 s[0:1], 0x6000
	v_mov_b32_e32 v143, v1
	s_waitcnt lgkmcnt(0)
	v_max_f32_e32 v107, v107, v107
	v_max_f32_e32 v106, v106, v107
	v_mov_b32_e32 v107, v106
	s_nop 1
	v_permlane32_swap_b32_e32 v107, v106
	v_mov_b32_e32 v147, v1
	s_waitcnt vmcnt(13)
	v_mfma_f32_16x16x32_bf16 v[100:103], v[100:103], v[6:9], 0
	s_waitcnt lgkmcnt(0)
	v_max3_f32 v212, v117, v106, v107
	v_sub_f32_e32 v107, v116, v212
	v_mul_f32_e32 v107, 0x3fb8aa3b, v107
	v_exp_f32_e32 v213, v107
	v_sub_f32_e32 v107, v118, v212
	v_mul_f32_e32 v107, 0x3fb8aa3b, v107
	v_exp_f32_e32 v214, v107
	v_sub_f32_e32 v107, v112, v212
	v_mul_f32_e32 v107, 0x3fb8aa3b, v107
	v_exp_f32_e32 v215, v107
	v_sub_f32_e32 v107, v114, v212
	v_mul_f32_e32 v107, 0x3fb8aa3b, v107
	v_exp_f32_e32 v216, v107
	v_sub_f32_e32 v107, v113, v212
	v_mul_f32_e32 v107, 0x3fb8aa3b, v107
	v_sub_f32_e32 v104, v104, v212
	v_exp_f32_e32 v217, v107
	v_sub_f32_e32 v107, v115, v212
	v_mul_f32_e32 v104, 0x3fb8aa3b, v104
	v_mul_f32_e32 v107, 0x3fb8aa3b, v107
	v_exp_f32_e32 v219, v104
	v_sub_f32_e32 v104, v105, v212
	v_sub_f32_e32 v106, v117, v212
	v_exp_f32_e32 v218, v107
	v_mul_f32_e32 v104, 0x3fb8aa3b, v104
	v_mul_f32_e32 v106, 0x3fb8aa3b, v106
	v_exp_f32_e32 v220, v104
	v_exp_f32_e32 v124, v106
	v_add_u32_e32 v104, 0x8000, v214
	v_add_u32_e32 v105, 0x8000, v213
	v_perm_b32 v104, v104, v105, s87
	v_add_u32_e32 v105, 0x8000, v216
	v_add_u32_e32 v106, 0x8000, v215
	v_perm_b32 v105, v105, v106, s87
	v_add_u32_e32 v106, 0x8000, v218
	v_add_u32_e32 v107, 0x8000, v217
	v_perm_b32 v106, v106, v107, s87
	v_add_u32_e32 v107, 0x8000, v220
	v_add_u32_e32 v112, 0x8000, v219
	v_perm_b32 v107, v107, v112, s87
	v_pk_mul_f32 v[58:59], v[58:59], v[124:125] op_sel_hi:[1,0]
	v_pk_mul_f32 v[56:57], v[56:57], v[124:125] op_sel_hi:[1,0]
	v_pk_mul_f32 v[22:23], v[22:23], v[124:125] op_sel_hi:[1,0]
	v_pk_mul_f32 v[20:21], v[20:21], v[124:125] op_sel_hi:[1,0]
	v_pk_mul_f32 v[18:19], v[18:19], v[124:125] op_sel_hi:[1,0]
	v_pk_mul_f32 v[16:17], v[16:17], v[124:125] op_sel_hi:[1,0]
	v_pk_mul_f32 v[14:15], v[14:15], v[124:125] op_sel_hi:[1,0]
	v_pk_mul_f32 v[12:13], v[12:13], v[124:125] op_sel_hi:[1,0]
	v_mfma_f32_16x16x32_bf16 v[120:123], v[76:79], v[104:107], v[56:59]
	v_mfma_f32_16x16x32_bf16 v[116:119], v[72:75], v[104:107], v[20:23]
	v_mfma_f32_16x16x32_bf16 v[112:115], v[64:67], v[104:107], v[16:19]
	v_mfma_f32_16x16x32_bf16 v[104:107], v[24:27], v[104:107], v[12:15]
	s_nop 2
	v_lshl_add_u64 v[12:13], s[28:29], 0, v[148:149]
	v_lshl_add_u64 v[12:13], v[12:13], 0, v[144:145]
	v_lshl_add_u64 v[14:15], v[12:13], 0, s[0:1]
	s_movk_i32 s0, 0x6000
	v_add_co_u32_e32 v12, vcc, s0, v12
	s_mov_b64 s[0:1], 0x1000
	s_nop 0
	v_addc_co_u32_e32 v13, vcc, 0, v13, vcc
	global_load_dwordx4 v[64:67], v[14:15], off offset:16
	global_load_dwordx4 v[72:75], v[14:15], off offset:3072
	global_load_dwordx4 v[76:79], v[12:13], off
	global_load_dwordx4 v[56:59], v[14:15], off offset:3088
	v_lshl_add_u64 v[12:13], s[26:27], 0, v[142:143]
	v_lshl_add_u64 v[16:17], v[12:13], 0, v[146:147]
	v_mfma_f32_16x16x32_bf16 v[12:15], v[108:111], v[6:9], 0
	v_lshl_add_u64 v[108:109], v[16:17], 0, s[0:1]
	s_movk_i32 s0, 0x1000
	v_add_co_u32_e32 v24, vcc, s0, v16
	v_mfma_f32_16x16x32_bf16 v[96:99], v[96:99], v[2:5], v[12:15]
	s_nop 0
	v_addc_co_u32_e32 v25, vcc, 0, v17, vcc
	global_load_dwordx4 v[20:23], v[108:109], off offset:256
	global_load_dwordx4 v[16:19], v[108:109], off offset:512
	s_nop 0
	global_load_dwordx4 v[24:27], v[24:25], off
	s_nop 0
	global_load_dwordx4 v[12:15], v[108:109], off offset:768
	s_waitcnt vmcnt(20)
	v_mfma_f32_16x16x32_bf16 v[92:95], v[92:95], v[2:5], v[100:103]
	s_and_saveexec_b64 s[34:35], s[12:13]
	s_cbranch_execz .LBB0_1179
	s_nop 0
	ds_read_b32 v100, v179 offset:1796
	s_waitcnt lgkmcnt(0)
	v_add_f32_e32 v211, v96, v100

.LBB0_1197:
	s_bitcmp0_b32 s17, 0
	s_cselect_b32 s0, s11, s16
	s_add_i32 s0, s0, s10
	s_add_i32 s1, s0, 0xfffff900
	s_cmp_lt_u32 s1, 0xfffffd00
	s_cbranch_scc1 .LBB0_1196
	s_add_i32 s0, s0, 0xfc00
	s_and_b32 s1, s0, 0xffff
	s_mul_i32 s1, s1, 0xaaab
	s_lshr_b32 s2, s1, 21
	s_mul_i32 s1, s2, 48
	s_sub_i32 s0, s0, s1
	s_bfe_u32 s3, s0, 0xd0003
	s_lshl_b32 s0, s0, 5
	s_lshl_b32 s1, s2, 8
	s_and_b32 s0, s0, 0xe0
	s_or_b32 s0, s0, s1
	v_or_b32_e32 v0, s0, v149
	v_mov_b64_e32 v[6:7], s[8:9]
	v_mad_u64_u32 v[8:9], s[0:1], v0, s33, v[6:7]
	s_lshl_b32 s44, s3, 7
	s_mul_i32 s2, s2, 0x30000
	s_add_u32 s0, s12, s2
	s_addc_u32 s1, s13, 0
	s_add_u32 s0, s0, s44
	s_addc_u32 s1, s1, 0
	v_mov_b32_e32 v83, v1
	v_mov_b32_e32 v81, v1
	v_lshl_add_u64 v[2:3], s[0:1], 0, v[82:83]
	v_lshl_add_u64 v[204:205], v[2:3], 0, v[80:81]
	global_load_dwordx4 v[2:5], v[204:205], off
	v_lshl_add_u64 v[8:9], v[8:9], 0, s[44:45]
	v_lshl_add_u64 v[8:9], v[8:9], 0, v[80:81]
	global_load_dwordx4 v[48:51], v[8:9], off
	global_load_dwordx4 v[16:19], v[204:205], off offset:3072
	v_or_b32_e32 v89, 16, v0
	v_mad_u64_u32 v[6:7], s[0:1], v89, s33, v[6:7]
	v_lshl_add_u64 v[6:7], v[6:7], 0, s[44:45]
	v_lshl_add_u64 v[6:7], v[6:7], 0, v[80:81]
	global_load_dwordx4 v[12:15], v[6:7], off
	global_load_dwordx4 v[20:23], v[204:205], off offset:16
	global_load_dwordx4 v[64:67], v[8:9], off offset:16
	global_load_dwordx4 v[24:27], v[204:205], off offset:3088
	s_nop 0
	global_load_dwordx4 v[8:11], v[6:7], off offset:16
	s_add_u32 s0, s14, s2
	s_addc_u32 s1, s15, 0
	s_lshl_b32 s2, s3, 15
	s_add_u32 s0, s0, s2
	v_mov_b32_e32 v85, v1
	s_addc_u32 s1, s1, 0
	v_mov_b32_e32 v87, v1
	v_lshl_add_u64 v[6:7], s[0:1], 0, v[84:85]
	v_lshl_add_u64 v[202:203], v[6:7], 0, v[86:87]
	global_load_dwordx4 v[28:31], v[202:203], off
	global_load_dwordx4 v[44:47], v[202:203], off offset:256
	v_cmp_lt_i32_e32 vcc, v231, v226
	global_load_dwordx4 v[52:55], v[202:203], off offset:768
	global_load_dwordx4 v[40:43], v[202:203], off offset:512
	v_cndmask_b32_e32 v6, v225, v231, vcc
	v_lshlrev_b32_e32 v81, 2, v6
	v_cmp_lt_i32_e32 vcc, v232, v226
	s_movk_i32 s1, 0x6000
	s_mov_b32 s0, 0xf149f2ca
	v_lshlrev_b32_e32 v0, 11, v0
	s_mov_b64 s[18:19], 0xd800200
	s_mov_b32 s2, 0xd800000
	s_waitcnt vmcnt(9)
	v_mfma_f32_16x16x32_bf16 v[36:39], v[16:19], v[48:51], 0
	v_mfma_f32_16x16x32_bf16 v[32:35], v[2:5], v[48:51], 0
	s_waitcnt vmcnt(6)
	v_mfma_f32_16x16x32_bf16 v[56:59], v[20:23], v[64:67], v[32:35]
	s_waitcnt vmcnt(5)
	v_mfma_f32_16x16x32_bf16 v[36:39], v[24:27], v[64:67], v[36:39]
	v_mfma_f32_16x16x32_bf16 v[2:5], v[2:5], v[12:15], 0
	s_nop 4
	v_max_f32_e32 v6, v57, v57
	v_max_f32_e32 v7, v56, v56
	v_max_f32_e32 v32, v59, v59
	v_max_f32_e32 v33, v58, v58
	v_max_f32_e32 v34, v39, v39
	v_max_f32_e32 v35, v38, v38
	v_max_f32_e32 v6, v7, v6
	v_max_f32_e32 v7, v33, v32
	v_max_f32_e32 v32, v35, v34
	v_max3_f32 v32, v36, v37, v32
	v_max3_f32 v6, v6, v7, v32
	ds_bpermute_b32 v7, v81, v6
	v_cndmask_b32_e32 v32, v225, v232, vcc
	v_lshlrev_b32_e32 v83, 2, v32
	s_waitcnt vmcnt(4)
	v_mfma_f32_16x16x32_bf16 v[32:35], v[20:23], v[8:11], v[2:5]
	v_add_co_u32_e32 v72, vcc, s1, v204
	s_waitcnt lgkmcnt(0)
	s_nop 0
	v_max_f32_e32 v2, v7, v7
	v_max_f32_e32 v2, v6, v2
	v_mov_b32_e32 v3, v2
	s_nop 1
	v_permlane32_swap_b32_e32 v3, v2
	v_mfma_f32_16x16x32_bf16 v[16:19], v[16:19], v[12:15], 0
	v_addc_co_u32_e32 v73, vcc, 0, v205, vcc
	global_load_dwordx4 v[68:71], v[72:73], off offset:16
	s_waitcnt lgkmcnt(0)
	v_max3_f32 v91, v2, v3, s0
	v_mfma_f32_16x16x32_bf16 v[60:63], v[24:27], v[8:11], v[16:19]
	v_sub_f32_e32 v20, v39, v91
	v_max_f32_e32 v6, v33, v33
	v_max_f32_e32 v7, v32, v32
	v_sub_f32_e32 v17, v36, v91
	v_sub_f32_e32 v18, v37, v91
	v_sub_f32_e32 v19, v38, v91
	global_load_dwordx4 v[36:39], v[72:73], off
	v_max_f32_e32 v24, v35, v35
	v_max_f32_e32 v25, v34, v34
	v_max_f32_e32 v6, v7, v6
	v_max_f32_e32 v7, v25, v24
	v_max_f32_e32 v24, v63, v63
	v_max_f32_e32 v25, v62, v62
	v_max_f32_e32 v24, v25, v24
	v_max3_f32 v24, v60, v61, v24
	v_max3_f32 v6, v6, v7, v24
	v_mov_b32_e32 v7, v6
	s_nop 1
	v_permlane16_swap_b32_e32 v7, v6
	v_sub_f32_e32 v2, 0xf149f2ca, v91
	v_sub_f32_e32 v3, v56, v91
	v_sub_f32_e32 v4, v57, v91
	v_sub_f32_e32 v5, v58, v91
	v_sub_f32_e32 v16, v59, v91
	s_waitcnt lgkmcnt(0)
	v_max_f32_e32 v7, v7, v7
	v_mul_f32_e32 v2, 0x3fb8aa3b, v2
	v_mul_f32_e32 v3, 0x3fb8aa3b, v3
	v_mul_f32_e32 v4, 0x3fb8aa3b, v4
	v_mul_f32_e32 v5, 0x3fb8aa3b, v5
	v_mul_f32_e32 v16, 0x3fb8aa3b, v16
	v_mul_f32_e32 v17, 0x3fb8aa3b, v17
	v_mul_f32_e32 v18, 0x3fb8aa3b, v18
	v_mul_f32_e32 v19, 0x3fb8aa3b, v19
	v_mul_f32_e32 v20, 0x3fb8aa3b, v20
	v_max_f32_e32 v6, v6, v7
	v_exp_f32_e32 v85, v3
	v_exp_f32_e32 v87, v4
	v_exp_f32_e32 v100, v5
	v_exp_f32_e32 v98, v16
	v_exp_f32_e32 v96, v17
	v_exp_f32_e32 v94, v18
	v_exp_f32_e32 v92, v19
	v_exp_f32_e32 v90, v20
	v_exp_f32_e32 v2, v2
	v_mov_b32_e32 v7, v6
	s_nop 1
	v_permlane32_swap_b32_e32 v7, v6
	v_add_u32_e32 v3, 0x8000, v87
	v_add_u32_e32 v4, 0x8000, v85
	v_add_u32_e32 v5, 0x8000, v98
	v_add_u32_e32 v16, 0x8000, v100
	v_add_u32_e32 v17, 0x8000, v94
	v_add_u32_e32 v18, 0x8000, v96
	v_add_u32_e32 v19, 0x8000, v90
	v_add_u32_e32 v23, 0x8000, v92
	v_mul_f32_e32 v2, 0, v2
	v_perm_b32 v20, v3, v4, s87
	v_perm_b32 v21, v5, v16, s87
	v_perm_b32 v22, v17, v18, s87
	v_perm_b32 v23, v19, v23, s87
	v_mov_b32_e32 v3, v2
	v_mov_b32_e32 v4, v2
	v_mov_b32_e32 v5, v2
	s_waitcnt lgkmcnt(0)
	v_max3_f32 v103, v6, v7, s0
	s_movk_i32 s0, 0x2000
	s_waitcnt vmcnt(5)
	v_mfma_f32_16x16x32_bf16 v[56:59], v[28:31], v[20:23], v[2:5]
	v_add_co_u32_e32 v120, vcc, s0, v202
	s_movk_i32 s0, 0x1000
	s_waitcnt vmcnt(4)
	v_mfma_f32_16x16x32_bf16 v[16:19], v[44:47], v[20:23], v[2:5]
	v_addc_co_u32_e32 v121, vcc, 0, v203, vcc
	global_load_dwordx4 v[136:139], v[120:121], off
	s_waitcnt vmcnt(3)
	v_mfma_f32_16x16x32_bf16 v[24:27], v[40:43], v[20:23], v[2:5]
	global_load_dwordx4 v[144:147], v[120:121], off offset:512
	global_load_dwordx4 v[154:157], v[120:121], off offset:768
	v_mfma_f32_16x16x32_bf16 v[20:23], v[52:55], v[20:23], v[2:5]
	s_nop 2
	v_sub_f32_e32 v4, v32, v103
	v_mul_f32_e32 v4, 0x3fb8aa3b, v4
	v_exp_f32_e32 v151, v4
	v_sub_f32_e32 v4, v33, v103
	v_mul_f32_e32 v4, 0x3fb8aa3b, v4
	v_exp_f32_e32 v153, v4
	v_sub_f32_e32 v4, v34, v103
	v_mul_f32_e32 v4, 0x3fb8aa3b, v4
	v_exp_f32_e32 v112, v4
	v_sub_f32_e32 v4, v35, v103
	v_mul_f32_e32 v4, 0x3fb8aa3b, v4
	v_exp_f32_e32 v110, v4
	v_sub_f32_e32 v4, v60, v103
	v_mul_f32_e32 v4, 0x3fb8aa3b, v4
	v_exp_f32_e32 v108, v4
	v_sub_f32_e32 v4, v61, v103
	v_mul_f32_e32 v4, 0x3fb8aa3b, v4
	v_exp_f32_e32 v106, v4
	v_sub_f32_e32 v4, v62, v103
	v_mul_f32_e32 v4, 0x3fb8aa3b, v4
	v_exp_f32_e32 v104, v4
	v_sub_f32_e32 v4, v63, v103
	v_sub_f32_e32 v3, 0xf149f2ca, v103
	v_mul_f32_e32 v4, 0x3fb8aa3b, v4
	v_mul_f32_e32 v3, 0x3fb8aa3b, v3
	v_exp_f32_e32 v102, v4
	v_exp_f32_e32 v3, v3
	v_add_u32_e32 v4, 0x8000, v153
	v_add_u32_e32 v5, 0x8000, v151
	v_perm_b32 v76, v4, v5, s87
	v_add_u32_e32 v4, 0x8000, v110
	v_add_u32_e32 v5, 0x8000, v112
	v_perm_b32 v77, v4, v5, s87
	v_add_u32_e32 v4, 0x8000, v106
	v_add_u32_e32 v5, 0x8000, v108
	v_perm_b32 v78, v4, v5, s87
	v_add_u32_e32 v4, 0x8000, v102
	v_add_u32_e32 v5, 0x8000, v104
	v_perm_b32 v79, v4, v5, s87
	v_mul_f32_e32 v4, 0, v3
	v_mov_b32_e32 v5, v4
	v_mov_b32_e32 v6, v4
	v_mov_b32_e32 v7, v4
	global_load_dwordx4 v[60:63], v[72:73], off offset:3072
	s_nop 0
	v_mfma_f32_16x16x32_bf16 v[32:35], v[28:31], v[76:79], v[4:7]
	v_mfma_f32_16x16x32_bf16 v[28:31], v[44:47], v[76:79], v[4:7]
	s_waitcnt vmcnt(4)
	v_mfma_f32_16x16x32_bf16 v[44:47], v[36:39], v[48:51], 0
	v_mfma_f32_16x16x32_bf16 v[122:125], v[68:71], v[64:67], v[44:47]
	v_mfma_f32_16x16x32_bf16 v[40:43], v[40:43], v[76:79], v[4:7]
	s_nop 5
	global_load_dwordx4 v[44:47], v[120:121], off offset:-4096
	v_max_f32_e32 v3, v123, v123
	global_load_dwordx4 v[72:75], v[72:73], off offset:3088
	s_waitcnt vmcnt(2)
	v_mfma_f32_16x16x32_bf16 v[114:117], v[60:63], v[48:51], 0
	v_max_f32_e32 v93, v122, v122
	v_max_f32_e32 v3, v93, v3
	v_max_f32_e32 v93, v125, v125
	s_waitcnt vmcnt(0)
	v_mfma_f32_16x16x32_bf16 v[126:129], v[72:75], v[64:67], v[114:117]
	v_max_f32_e32 v95, v124, v124
	v_max_f32_e32 v93, v95, v93
	s_nop 0
	v_add_co_u32_e32 v116, vcc, s0, v202
	s_nop 3
	v_max_f32_e32 v95, v129, v129
	v_max_f32_e32 v97, v128, v128
	v_max_f32_e32 v95, v97, v95
	v_max3_f32 v95, v126, v127, v95
	v_max3_f32 v3, v3, v93, v95
	v_mov_b32_e32 v93, v3
	s_nop 1
	v_permlane16_swap_b32_e32 v93, v3
	v_mfma_f32_16x16x32_bf16 v[52:55], v[52:55], v[76:79], v[4:7]
	v_addc_co_u32_e32 v117, vcc, 0, v203, vcc
	s_mov_b32 s0, 0xc000
	s_waitcnt lgkmcnt(0)
	v_max_f32_e32 v93, v93, v93
	v_max_f32_e32 v3, v3, v93
	v_mov_b32_e32 v93, v3
	s_nop 1
	v_permlane32_swap_b32_e32 v93, v3
	v_mfma_f32_16x16x32_bf16 v[36:39], v[36:39], v[12:15], 0
	s_waitcnt lgkmcnt(0)
	v_max3_f32 v6, v91, v3, v93
	v_sub_f32_e32 v3, v91, v6
	v_mul_f32_e32 v5, 0x3fb8aa3b, v3
	v_sub_f32_e32 v3, v122, v6
	v_mul_f32_e32 v3, 0x3fb8aa3b, v3
	v_exp_f32_e32 v101, v3
	v_sub_f32_e32 v3, v123, v6
	v_mul_f32_e32 v3, 0x3fb8aa3b, v3
	v_exp_f32_e32 v99, v3
	v_sub_f32_e32 v3, v124, v6
	v_mul_f32_e32 v3, 0x3fb8aa3b, v3
	v_exp_f32_e32 v97, v3
	v_sub_f32_e32 v3, v125, v6
	global_load_dwordx4 v[122:125], v[116:117], off offset:256
	v_mul_f32_e32 v3, 0x3fb8aa3b, v3
	v_exp_f32_e32 v95, v3
	v_sub_f32_e32 v3, v126, v6
	v_mul_f32_e32 v3, 0x3fb8aa3b, v3
	v_exp_f32_e32 v93, v3
	v_sub_f32_e32 v3, v127, v6
	v_mul_f32_e32 v3, 0x3fb8aa3b, v3
	v_exp_f32_e32 v91, v3
	v_sub_f32_e32 v3, v128, v6
	v_sub_f32_e32 v7, v129, v6
	v_mul_f32_e32 v3, 0x3fb8aa3b, v3
	v_mul_f32_e32 v7, 0x3fb8aa3b, v7
	v_mfma_f32_16x16x32_bf16 v[60:63], v[60:63], v[12:15], 0
	v_exp_f32_e32 v3, v3
	v_exp_f32_e32 v167, v7
	v_exp_f32_e32 v114, v5
	v_add_u32_e32 v5, 0x8000, v99
	v_add_u32_e32 v7, 0x8000, v101
	v_mfma_f32_16x16x32_bf16 v[36:39], v[68:71], v[8:11], v[36:39]
	v_perm_b32 v76, v5, v7, s87
	v_add_u32_e32 v5, 0x8000, v95
	v_add_u32_e32 v7, 0x8000, v97
	v_perm_b32 v77, v5, v7, s87
	v_add_u32_e32 v5, 0x8000, v91
	v_add_u32_e32 v7, 0x8000, v93
	v_mfma_f32_16x16x32_bf16 v[60:63], v[72:75], v[8:11], v[60:63]
	v_perm_b32 v78, v5, v7, s87
	v_add_u32_e32 v5, 0x8000, v167
	v_add_u32_e32 v7, 0x8000, v3
	v_perm_b32 v79, v5, v7, s87
	v_max_f32_e32 v5, v37, v37
	v_max_f32_e32 v7, v36, v36
	v_max_f32_e32 v5, v7, v5
	v_max_f32_e32 v7, v39, v39
	v_max_f32_e32 v72, v38, v38
	v_max_f32_e32 v7, v72, v7
	v_max_f32_e32 v72, v63, v63
	v_max_f32_e32 v73, v62, v62
	v_max_f32_e32 v72, v73, v72
	v_max3_f32 v72, v60, v61, v72
	v_max3_f32 v5, v5, v7, v72
	v_mov_b32_e32 v7, v5
	s_nop 1
	v_permlane16_swap_b32_e32 v7, v5
	v_pk_mul_f32 v[58:59], v[58:59], v[114:115] op_sel_hi:[1,0]
	v_pk_mul_f32 v[56:57], v[56:57], v[114:115] op_sel_hi:[1,0]
	v_pk_mul_f32 v[18:19], v[18:19], v[114:115] op_sel_hi:[1,0]
	v_pk_mul_f32 v[16:17], v[16:17], v[114:115] op_sel_hi:[1,0]
	s_waitcnt lgkmcnt(0)
	v_max_f32_e32 v7, v7, v7
	v_max_f32_e32 v5, v5, v7
	v_mov_b32_e32 v7, v5
	s_nop 1
	v_permlane32_swap_b32_e32 v7, v5
	v_pk_mul_f32 v[26:27], v[26:27], v[114:115] op_sel_hi:[1,0]
	v_pk_mul_f32 v[24:25], v[24:25], v[114:115] op_sel_hi:[1,0]
	v_pk_mul_f32 v[22:23], v[22:23], v[114:115] op_sel_hi:[1,0]
	v_pk_mul_f32 v[20:21], v[20:21], v[114:115] op_sel_hi:[1,0]
	s_waitcnt lgkmcnt(0)
	v_max3_f32 v115, v103, v5, v7
	v_sub_f32_e32 v5, v103, v115
	v_mul_f32_e32 v7, 0x3fb8aa3b, v5
	v_sub_f32_e32 v5, v36, v115
	v_mul_f32_e32 v5, 0x3fb8aa3b, v5
	v_exp_f32_e32 v113, v5
	v_sub_f32_e32 v5, v37, v115
	v_mul_f32_e32 v5, 0x3fb8aa3b, v5
	v_exp_f32_e32 v111, v5
	v_sub_f32_e32 v5, v38, v115
	v_mul_f32_e32 v5, 0x3fb8aa3b, v5
	v_exp_f32_e32 v109, v5
	v_sub_f32_e32 v5, v39, v115
	v_mul_f32_e32 v5, 0x3fb8aa3b, v5
	v_exp_f32_e32 v107, v5
	v_sub_f32_e32 v5, v60, v115
	v_mul_f32_e32 v5, 0x3fb8aa3b, v5
	v_exp_f32_e32 v105, v5
	v_sub_f32_e32 v5, v61, v115
	v_mul_f32_e32 v5, 0x3fb8aa3b, v5
	v_exp_f32_e32 v103, v5
	v_sub_f32_e32 v5, v62, v115
	v_sub_f32_e32 v36, v63, v115
	v_mul_f32_e32 v5, 0x3fb8aa3b, v5
	v_mul_f32_e32 v36, 0x3fb8aa3b, v36
	v_exp_f32_e32 v5, v5
	v_exp_f32_e32 v206, v36
	v_exp_f32_e32 v118, v7
	v_add_u32_e32 v7, 0x8000, v111
	v_add_u32_e32 v36, 0x8000, v113
	v_perm_b32 v36, v7, v36, s87
	v_add_u32_e32 v7, 0x8000, v107
	v_add_u32_e32 v37, 0x8000, v109
	v_perm_b32 v37, v7, v37, s87
	v_add_u32_e32 v7, 0x8000, v103
	v_add_u32_e32 v38, 0x8000, v105
	global_load_dwordx4 v[126:129], v[116:117], off offset:512
	global_load_dwordx4 v[68:71], v[116:117], off offset:768
	v_add_co_u32_e32 v116, vcc, s0, v204
	v_perm_b32 v38, v7, v38, s87
	v_add_u32_e32 v7, 0x8000, v206
	v_add_u32_e32 v39, 0x8000, v5
	v_addc_co_u32_e32 v117, vcc, 0, v205, vcc
	v_perm_b32 v39, v7, v39, s87
	v_pk_mul_f32 v[34:35], v[34:35], v[118:119] op_sel_hi:[1,0]
	v_pk_mul_f32 v[32:33], v[32:33], v[118:119] op_sel_hi:[1,0]
	v_mfma_f32_16x16x32_bf16 v[56:59], v[44:47], v[76:79], v[56:59]
	global_load_dwordx4 v[60:63], v[116:117], off offset:3072
	global_load_dwordx4 v[130:133], v[116:117], off offset:3088
	v_pk_mul_f32 v[30:31], v[30:31], v[118:119] op_sel_hi:[1,0]
	v_mfma_f32_16x16x32_bf16 v[32:35], v[44:47], v[36:39], v[32:35]
	global_load_dwordx4 v[44:47], v[116:117], off
	v_pk_mul_f32 v[28:29], v[28:29], v[118:119] op_sel_hi:[1,0]
	v_pk_mul_f32 v[42:43], v[42:43], v[118:119] op_sel_hi:[1,0]
	s_waitcnt vmcnt(5)
	v_mfma_f32_16x16x32_bf16 v[16:19], v[122:125], v[76:79], v[16:19]
	v_mul_f32_e64 v40, v40, v118
	v_mul_f32_e64 v41, v41, v118
	v_pk_mul_f32 v[54:55], v[54:55], v[118:119] op_sel_hi:[1,0]
	v_pk_mul_f32 v[52:53], v[52:53], v[118:119] op_sel_hi:[1,0]
	v_mfma_f32_16x16x32_bf16 v[28:31], v[122:125], v[36:39], v[28:31]
	global_load_dwordx4 v[122:125], v[116:117], off offset:16
	s_mov_b32 s0, 0x12000
	s_waitcnt vmcnt(1)
	v_mfma_f32_16x16x32_bf16 v[72:75], v[44:47], v[48:51], 0
	v_mfma_f32_16x16x32_bf16 v[24:27], v[126:129], v[76:79], v[24:27]
	v_mfma_f32_16x16x32_bf16 v[20:23], v[68:71], v[76:79], v[20:23]
	v_mfma_f32_16x16x32_bf16 v[76:79], v[60:63], v[48:51], 0
	s_waitcnt vmcnt(0)
	v_mfma_f32_16x16x32_bf16 v[72:75], v[122:125], v[64:67], v[72:75]
	v_mfma_f32_16x16x32_bf16 v[140:143], v[130:133], v[64:67], v[76:79]
	v_mfma_f32_16x16x32_bf16 v[40:43], v[126:129], v[36:39], v[40:43]
	s_nop 5
	v_max_f32_e32 v7, v73, v73
	v_max_f32_e32 v76, v72, v72
	v_max_f32_e32 v7, v76, v7
	v_max_f32_e32 v76, v75, v75
	v_max_f32_e32 v77, v74, v74
	v_max_f32_e32 v76, v77, v76
	v_max_f32_e32 v77, v143, v143
	v_max_f32_e32 v78, v142, v142
	v_max_f32_e32 v77, v78, v77
	v_max3_f32 v77, v140, v141, v77
	v_max3_f32 v7, v7, v76, v77
	v_mov_b32_e32 v76, v7
	s_nop 1
	v_permlane16_swap_b32_e32 v76, v7
	v_mfma_f32_16x16x32_bf16 v[36:39], v[68:71], v[36:39], v[52:55]
	s_waitcnt lgkmcnt(0)
	v_max_f32_e32 v76, v76, v76
	v_max_f32_e32 v7, v7, v76
	v_mov_b32_e32 v76, v7
	s_nop 1
	v_permlane32_swap_b32_e32 v76, v7
	v_mfma_f32_16x16x32_bf16 v[44:47], v[44:47], v[12:15], 0
	s_waitcnt lgkmcnt(0)
	v_max3_f32 v69, v6, v7, v76
	v_sub_f32_e32 v7, v72, v69
	v_mul_f32_e32 v7, 0x3fb8aa3b, v7
	v_exp_f32_e32 v181, v7
	v_sub_f32_e32 v7, v73, v69
	v_mul_f32_e32 v7, 0x3fb8aa3b, v7
	v_exp_f32_e32 v193, v7
	v_sub_f32_e32 v7, v74, v69
	v_mul_f32_e32 v7, 0x3fb8aa3b, v7
	v_exp_f32_e32 v78, v7
	v_sub_f32_e32 v7, v75, v69
	v_mul_f32_e32 v7, 0x3fb8aa3b, v7
	v_exp_f32_e32 v76, v7
	v_sub_f32_e32 v7, v140, v69
	v_mul_f32_e32 v7, 0x3fb8aa3b, v7
	v_exp_f32_e32 v74, v7
	v_sub_f32_e32 v7, v141, v69
	v_mul_f32_e32 v7, 0x3fb8aa3b, v7
	v_exp_f32_e32 v72, v7
	v_sub_f32_e32 v7, v142, v69
	v_mul_f32_e32 v7, 0x3fb8aa3b, v7
	v_exp_f32_e32 v70, v7
	v_sub_f32_e32 v7, v143, v69
	global_load_dwordx4 v[140:143], v[120:121], off offset:256
	v_mfma_f32_16x16x32_bf16 v[60:63], v[60:63], v[12:15], 0
	v_sub_f32_e32 v6, v6, v69
	v_mul_f32_e32 v6, 0x3fb8aa3b, v6
	v_exp_f32_e32 v116, v6
	v_mfma_f32_16x16x32_bf16 v[44:47], v[122:125], v[8:11], v[44:47]
	v_mul_f32_e32 v7, 0x3fb8aa3b, v7
	v_exp_f32_e32 v68, v7
	v_pk_mul_f32 v[58:59], v[58:59], v[116:117] op_sel_hi:[1,0]
	v_mfma_f32_16x16x32_bf16 v[60:63], v[130:133], v[8:11], v[60:63]
	v_mul_f32_e64 v56, v56, v116
	v_mul_f32_e64 v57, v57, v116
	s_nop 1
	v_max_f32_e32 v71, v45, v45
	v_max_f32_e32 v73, v44, v44
	v_max_f32_e32 v71, v73, v71
	v_max_f32_e32 v73, v47, v47
	v_max_f32_e32 v75, v46, v46
	v_max_f32_e32 v73, v75, v73
	v_max_f32_e32 v75, v63, v63
	v_max_f32_e32 v77, v62, v62
	v_max_f32_e32 v75, v77, v75
	v_max3_f32 v75, v60, v61, v75
	v_max3_f32 v71, v71, v73, v75
	v_mov_b32_e32 v73, v71
	s_nop 1
	v_permlane16_swap_b32_e32 v73, v71
	v_pk_mul_f32 v[18:19], v[18:19], v[116:117] op_sel_hi:[1,0]
	v_pk_mul_f32 v[16:17], v[16:17], v[116:117] op_sel_hi:[1,0]
	v_pk_mul_f32 v[26:27], v[26:27], v[116:117] op_sel_hi:[1,0]
	v_pk_mul_f32 v[24:25], v[24:25], v[116:117] op_sel_hi:[1,0]
	s_waitcnt lgkmcnt(0)
	v_max_f32_e32 v73, v73, v73
	v_max_f32_e32 v71, v71, v73
	v_mov_b32_e32 v73, v71
	s_nop 1
	v_permlane32_swap_b32_e32 v73, v71
	v_pk_mul_f32 v[22:23], v[22:23], v[116:117] op_sel_hi:[1,0]
	v_pk_mul_f32 v[20:21], v[20:21], v[116:117] op_sel_hi:[1,0]
	v_add_u32_e32 v6, 0x8000, v193
	v_add_u32_e32 v7, 0x8000, v181
	s_waitcnt lgkmcnt(0)
	v_max3_f32 v117, v115, v71, v73
	v_sub_f32_e32 v44, v44, v117
	v_mul_f32_e32 v44, 0x3fb8aa3b, v44
	v_exp_f32_e32 v207, v44
	v_sub_f32_e32 v44, v45, v117
	v_mul_f32_e32 v44, 0x3fb8aa3b, v44
	v_exp_f32_e32 v208, v44
	v_sub_f32_e32 v44, v46, v117
	v_mul_f32_e32 v44, 0x3fb8aa3b, v44
	v_exp_f32_e32 v132, v44
	v_sub_f32_e32 v44, v47, v117
	v_mul_f32_e32 v44, 0x3fb8aa3b, v44
	v_exp_f32_e32 v130, v44
	v_sub_f32_e32 v44, v60, v117
	v_mul_f32_e32 v44, 0x3fb8aa3b, v44
	v_exp_f32_e32 v128, v44
	v_sub_f32_e32 v44, v61, v117
	v_mul_f32_e32 v44, 0x3fb8aa3b, v44
	v_exp_f32_e32 v126, v44
	v_sub_f32_e32 v44, v62, v117
	v_mul_f32_e32 v44, 0x3fb8aa3b, v44
	v_perm_b32 v52, v6, v7, s87
	v_add_u32_e32 v6, 0x8000, v76
	v_add_u32_e32 v7, 0x8000, v78
	v_exp_f32_e32 v124, v44
	v_sub_f32_e32 v44, v63, v117
	v_perm_b32 v53, v6, v7, s87
	v_add_u32_e32 v6, 0x8000, v72
	v_add_u32_e32 v7, 0x8000, v74
	v_mul_f32_e32 v44, 0x3fb8aa3b, v44
	v_perm_b32 v54, v6, v7, s87
	v_add_u32_e32 v6, 0x8000, v68
	v_add_u32_e32 v7, 0x8000, v70
	v_exp_f32_e32 v122, v44
	v_perm_b32 v55, v6, v7, s87
	v_add_co_u32_e32 v6, vcc, s0, v204
	v_add_u32_e32 v44, 0x8000, v208
	v_add_u32_e32 v45, 0x8000, v207
	v_mfma_f32_16x16x32_bf16 v[56:59], v[136:139], v[52:55], v[56:59]
	v_addc_co_u32_e32 v7, vcc, 0, v205, vcc
	v_perm_b32 v44, v44, v45, s87
	s_waitcnt vmcnt(0)
	v_mfma_f32_16x16x32_bf16 v[16:19], v[140:143], v[52:55], v[16:19]
	v_add_u32_e32 v45, 0x8000, v130
	v_add_u32_e32 v46, 0x8000, v132
	global_load_dwordx4 v[158:161], v[6:7], off
	global_load_dwordx4 v[60:63], v[6:7], off offset:16
	v_mfma_f32_16x16x32_bf16 v[24:27], v[144:147], v[52:55], v[24:27]
	v_perm_b32 v45, v45, v46, s87
	v_add_u32_e32 v46, 0x8000, v126
	v_add_u32_e32 v47, 0x8000, v128
	v_mfma_f32_16x16x32_bf16 v[20:23], v[154:157], v[52:55], v[20:23]
	v_sub_f32_e32 v52, v115, v117
	v_mul_f32_e32 v52, 0x3fb8aa3b, v52
	v_exp_f32_e32 v134, v52
	v_perm_b32 v46, v46, v47, s87
	v_add_u32_e32 v47, 0x8000, v122
	v_add_u32_e32 v52, 0x8000, v124
	v_perm_b32 v47, v47, v52, s87
	global_load_dwordx4 v[52:55], v[6:7], off offset:3072
	v_pk_mul_f32 v[30:31], v[30:31], v[134:135] op_sel_hi:[1,0]
	v_pk_mul_f32 v[28:29], v[28:29], v[134:135] op_sel_hi:[1,0]
	v_pk_mul_f32 v[34:35], v[34:35], v[134:135] op_sel_hi:[1,0]
	v_pk_mul_f32 v[32:33], v[32:33], v[134:135] op_sel_hi:[1,0]
	v_mfma_f32_16x16x32_bf16 v[28:31], v[140:143], v[44:47], v[28:31]
	global_load_dwordx4 v[140:143], v[6:7], off offset:3088
	v_pk_mul_f32 v[42:43], v[42:43], v[134:135] op_sel_hi:[1,0]
	v_pk_mul_f32 v[40:41], v[40:41], v[134:135] op_sel_hi:[1,0]
	v_mfma_f32_16x16x32_bf16 v[32:35], v[136:139], v[44:47], v[32:35]
	v_mul_f32_e64 v38, v38, v134
	v_mul_f32_e64 v39, v39, v134
	v_pk_mul_f32 v[36:37], v[36:37], v[134:135] op_sel_hi:[1,0]
	s_movk_i32 s0, 0x4000
	s_waitcnt vmcnt(3)
	v_mfma_f32_16x16x32_bf16 v[136:139], v[158:161], v[48:51], 0
	v_add_co_u32_e32 v6, vcc, s0, v202
	s_movk_i32 s0, 0x3000
	s_waitcnt vmcnt(1)
	v_mfma_f32_16x16x32_bf16 v[162:165], v[52:55], v[48:51], 0
	v_addc_co_u32_e32 v7, vcc, 0, v203, vcc
	v_add_co_u32_e32 v172, vcc, s0, v202
	v_mfma_f32_16x16x32_bf16 v[136:139], v[60:63], v[64:67], v[136:139]
	s_nop 0
	v_addc_co_u32_e32 v173, vcc, 0, v203, vcc
	global_load_dwordx4 v[168:171], v[6:7], off offset:-4096
	global_load_dwordx4 v[176:179], v[6:7], off offset:512
	s_waitcnt vmcnt(2)
	v_mfma_f32_16x16x32_bf16 v[162:165], v[140:143], v[64:67], v[162:165]
	s_nop 1
	v_max_f32_e32 v71, v137, v137
	v_max_f32_e32 v73, v136, v136
	v_max_f32_e32 v71, v73, v71
	v_max_f32_e32 v73, v139, v139
	v_max_f32_e32 v75, v138, v138
	v_max_f32_e32 v73, v75, v73
	v_max_f32_e32 v75, v165, v165
	v_max_f32_e32 v77, v164, v164
	v_max_f32_e32 v75, v77, v75
	v_max3_f32 v75, v162, v163, v75
	v_max3_f32 v71, v71, v73, v75
	v_mov_b32_e32 v73, v71
	s_nop 1
	v_permlane16_swap_b32_e32 v73, v71
	v_mfma_f32_16x16x32_bf16 v[40:43], v[144:147], v[44:47], v[40:43]
	s_mov_b32 s0, 0x18000
	global_load_dwordx4 v[188:191], v[6:7], off offset:768
	s_waitcnt lgkmcnt(0)
	v_max_f32_e32 v73, v73, v73
	v_max_f32_e32 v71, v71, v73
	v_mov_b32_e32 v73, v71
	s_nop 1
	v_permlane32_swap_b32_e32 v73, v71
	v_mfma_f32_16x16x32_bf16 v[36:39], v[154:157], v[44:47], v[36:39]
	global_load_dwordx4 v[154:157], v[172:173], off offset:512
	s_waitcnt lgkmcnt(0)
	v_max3_f32 v135, v69, v71, v73
	v_sub_f32_e32 v45, v136, v135
	v_mul_f32_e32 v45, 0x3fb8aa3b, v45
	v_exp_f32_e32 v79, v45
	v_sub_f32_e32 v45, v137, v135
	v_mfma_f32_16x16x32_bf16 v[144:147], v[158:161], v[12:15], 0
	v_mul_f32_e32 v45, 0x3fb8aa3b, v45
	v_exp_f32_e32 v77, v45
	v_sub_f32_e32 v45, v138, v135
	v_mul_f32_e32 v45, 0x3fb8aa3b, v45
	v_exp_f32_e32 v75, v45
	v_sub_f32_e32 v45, v139, v135
	global_load_dwordx4 v[136:139], v[172:173], off offset:256
	v_mfma_f32_16x16x32_bf16 v[60:63], v[60:63], v[8:11], v[144:147]
	v_mul_f32_e32 v45, 0x3fb8aa3b, v45
	v_exp_f32_e32 v73, v45
	v_sub_f32_e32 v45, v162, v135
	global_load_dwordx4 v[144:147], v[172:173], off offset:768
	v_mul_f32_e32 v45, 0x3fb8aa3b, v45
	v_exp_f32_e32 v71, v45
	v_sub_f32_e32 v45, v163, v135
	v_mul_f32_e32 v45, 0x3fb8aa3b, v45
	v_sub_f32_e32 v44, v69, v135
	v_exp_f32_e32 v69, v45
	v_sub_f32_e32 v45, v164, v135
	v_mul_f32_e32 v45, 0x3fb8aa3b, v45
	v_exp_f32_e32 v115, v45
	v_sub_f32_e32 v45, v165, v135
	v_mul_f32_e32 v45, 0x3fb8aa3b, v45
	v_mfma_f32_16x16x32_bf16 v[52:55], v[52:55], v[12:15], 0
	v_mul_f32_e32 v44, 0x3fb8aa3b, v44
	v_exp_f32_e32 v121, v45
	v_exp_f32_e32 v120, v44
	v_add_u32_e32 v44, 0x8000, v77
	v_add_u32_e32 v45, 0x8000, v79
	v_perm_b32 v44, v44, v45, s87
	v_add_u32_e32 v45, 0x8000, v73
	v_add_u32_e32 v46, 0x8000, v75
	v_perm_b32 v45, v45, v46, s87
	v_add_u32_e32 v46, 0x8000, v69
	v_add_u32_e32 v47, 0x8000, v71
	v_mfma_f32_16x16x32_bf16 v[52:55], v[140:143], v[8:11], v[52:55]
	v_perm_b32 v46, v46, v47, s87
	v_add_u32_e32 v47, 0x8000, v121
	v_add_u32_e32 v119, 0x8000, v115
	v_perm_b32 v47, v47, v119, s87
	v_max_f32_e32 v119, v61, v61
	v_max_f32_e32 v123, v60, v60
	v_max_f32_e32 v119, v123, v119
	v_max_f32_e32 v123, v63, v63
	v_max_f32_e32 v125, v62, v62
	v_max_f32_e32 v123, v125, v123
	v_max_f32_e32 v125, v55, v55
	v_max_f32_e32 v127, v54, v54
	v_max_f32_e32 v125, v127, v125
	v_max3_f32 v125, v52, v53, v125
	v_max3_f32 v119, v119, v123, v125
	v_mov_b32_e32 v123, v119
	s_nop 1
	v_permlane16_swap_b32_e32 v123, v119
	v_pk_mul_f32 v[58:59], v[58:59], v[120:121] op_sel_hi:[1,0]
	v_pk_mul_f32 v[56:57], v[56:57], v[120:121] op_sel_hi:[1,0]
	v_pk_mul_f32 v[18:19], v[18:19], v[120:121] op_sel_hi:[1,0]
	v_pk_mul_f32 v[16:17], v[16:17], v[120:121] op_sel_hi:[1,0]
	s_waitcnt lgkmcnt(0)
	v_max_f32_e32 v123, v123, v123
	v_max_f32_e32 v119, v119, v123
	v_mov_b32_e32 v123, v119
	s_nop 1
	v_permlane32_swap_b32_e32 v123, v119
	v_pk_mul_f32 v[26:27], v[26:27], v[120:121] op_sel_hi:[1,0]
	v_pk_mul_f32 v[24:25], v[24:25], v[120:121] op_sel_hi:[1,0]
	v_pk_mul_f32 v[22:23], v[22:23], v[120:121] op_sel_hi:[1,0]
	v_pk_mul_f32 v[20:21], v[20:21], v[120:121] op_sel_hi:[1,0]
	s_waitcnt lgkmcnt(0)
	v_max3_f32 v152, v117, v119, v123
	s_waitcnt vmcnt(5)
	v_mfma_f32_16x16x32_bf16 v[56:59], v[168:171], v[44:47], v[56:59]
	v_add_co_u32_e32 v162, vcc, s0, v204
	s_mov_b32 s0, 0x1e000
	s_waitcnt vmcnt(1)
	v_mfma_f32_16x16x32_bf16 v[16:19], v[136:139], v[44:47], v[16:19]
	v_addc_co_u32_e32 v163, vcc, 0, v205, vcc
	global_load_dwordx4 v[158:161], v[162:163], off offset:16
	v_mfma_f32_16x16x32_bf16 v[24:27], v[154:157], v[44:47], v[24:27]
	s_waitcnt vmcnt(1)
	v_mfma_f32_16x16x32_bf16 v[20:23], v[144:147], v[44:47], v[20:23]
	v_sub_f32_e32 v45, v60, v152
	v_mul_f32_e32 v45, 0x3fb8aa3b, v45
	v_exp_f32_e32 v133, v45
	v_sub_f32_e32 v45, v61, v152
	v_mul_f32_e32 v45, 0x3fb8aa3b, v45
	v_exp_f32_e32 v131, v45
	v_sub_f32_e32 v45, v62, v152
	v_mul_f32_e32 v45, 0x3fb8aa3b, v45
	v_exp_f32_e32 v129, v45
	v_sub_f32_e32 v45, v63, v152
	v_mul_f32_e32 v45, 0x3fb8aa3b, v45
	v_exp_f32_e32 v127, v45
	v_sub_f32_e32 v45, v52, v152
	v_mul_f32_e32 v45, 0x3fb8aa3b, v45
	v_exp_f32_e32 v125, v45
	v_sub_f32_e32 v45, v53, v152
	v_mul_f32_e32 v45, 0x3fb8aa3b, v45
	v_exp_f32_e32 v123, v45
	v_sub_f32_e32 v45, v54, v152
	v_mul_f32_e32 v45, 0x3fb8aa3b, v45
	v_exp_f32_e32 v119, v45
	v_sub_f32_e32 v45, v55, v152
	v_sub_f32_e32 v44, v117, v152
	v_mul_f32_e32 v45, 0x3fb8aa3b, v45
	v_mul_f32_e32 v44, 0x3fb8aa3b, v44
	v_exp_f32_e32 v211, v45
	v_exp_f32_e32 v150, v44
	v_add_u32_e32 v44, 0x8000, v131
	v_add_u32_e32 v45, 0x8000, v133
	v_perm_b32 v44, v44, v45, s87
	v_add_u32_e32 v45, 0x8000, v127
	v_add_u32_e32 v46, 0x8000, v129
	v_perm_b32 v45, v45, v46, s87
	v_add_u32_e32 v46, 0x8000, v123
	v_add_u32_e32 v47, 0x8000, v125
	v_perm_b32 v46, v46, v47, s87
	v_add_u32_e32 v47, 0x8000, v211
	v_add_u32_e32 v52, 0x8000, v119
	v_perm_b32 v47, v47, v52, s87
	global_load_dwordx4 v[52:55], v[162:163], off
	global_load_dwordx4 v[60:63], v[162:163], off offset:3072
	v_pk_mul_f32 v[30:31], v[30:31], v[150:151] op_sel_hi:[1,0]
	global_load_dwordx4 v[162:165], v[162:163], off offset:3088
	v_pk_mul_f32 v[28:29], v[28:29], v[150:151] op_sel_hi:[1,0]
	s_waitcnt vmcnt(1)
	v_mfma_f32_16x16x32_bf16 v[140:143], v[60:63], v[48:51], 0
	v_mul_f32_e64 v34, v34, v150
	v_mul_f32_e64 v35, v35, v150
	v_pk_mul_f32 v[32:33], v[32:33], v[150:151] op_sel_hi:[1,0]
	v_pk_mul_f32 v[42:43], v[42:43], v[150:151] op_sel_hi:[1,0]
	v_mfma_f32_16x16x32_bf16 v[28:31], v[136:139], v[44:47], v[28:31]
	v_mul_f32_e64 v40, v40, v150
	v_mul_f32_e64 v41, v41, v150
	v_pk_mul_f32 v[38:39], v[38:39], v[150:151] op_sel_hi:[1,0]
	v_pk_mul_f32 v[36:37], v[36:37], v[150:151] op_sel_hi:[1,0]
	v_mfma_f32_16x16x32_bf16 v[136:139], v[52:55], v[48:51], 0
	v_mfma_f32_16x16x32_bf16 v[136:139], v[158:161], v[64:67], v[136:139]
	s_waitcnt vmcnt(0)
	v_mfma_f32_16x16x32_bf16 v[172:175], v[162:165], v[64:67], v[140:143]
	v_mfma_f32_16x16x32_bf16 v[32:35], v[168:171], v[44:47], v[32:35]
	s_nop 4
	v_max_f32_e32 v117, v137, v137
	v_max_f32_e32 v140, v136, v136
	v_max_f32_e32 v117, v140, v117
	v_max_f32_e32 v140, v139, v139
	v_max_f32_e32 v141, v138, v138
	v_max_f32_e32 v140, v141, v140
	v_max_f32_e32 v141, v175, v175
	v_max_f32_e32 v142, v174, v174
	v_max_f32_e32 v141, v142, v141
	v_max3_f32 v141, v172, v173, v141
	v_max3_f32 v117, v117, v140, v141
	v_mov_b32_e32 v140, v117
	s_nop 1
	v_permlane16_swap_b32_e32 v140, v117
	v_mfma_f32_16x16x32_bf16 v[40:43], v[154:157], v[44:47], v[40:43]
	global_load_dwordx4 v[168:171], v[6:7], off
	s_waitcnt lgkmcnt(0)
	v_max_f32_e32 v140, v140, v140
	v_max_f32_e32 v117, v117, v140
	v_mov_b32_e32 v140, v117
	s_nop 1
	v_permlane32_swap_b32_e32 v140, v117
	v_mfma_f32_16x16x32_bf16 v[36:39], v[144:147], v[44:47], v[36:39]
	s_waitcnt lgkmcnt(0)
	v_max3_f32 v117, v135, v117, v140
	v_sub_f32_e32 v45, v136, v117
	v_mul_f32_e32 v45, 0x3fb8aa3b, v45
	v_exp_f32_e32 v209, v45
	v_sub_f32_e32 v45, v137, v117
	v_mul_f32_e32 v45, 0x3fb8aa3b, v45
	v_exp_f32_e32 v210, v45
	v_sub_f32_e32 v45, v138, v117
	v_mul_f32_e32 v45, 0x3fb8aa3b, v45
	v_exp_f32_e32 v146, v45
	v_sub_f32_e32 v45, v139, v117
	v_mul_f32_e32 v45, 0x3fb8aa3b, v45
	v_exp_f32_e32 v144, v45
	v_sub_f32_e32 v45, v172, v117
	v_mul_f32_e32 v45, 0x3fb8aa3b, v45
	v_exp_f32_e32 v142, v45
	v_sub_f32_e32 v45, v173, v117
	v_mul_f32_e32 v45, 0x3fb8aa3b, v45
	v_exp_f32_e32 v140, v45
	v_sub_f32_e32 v45, v174, v117
	v_mul_f32_e32 v45, 0x3fb8aa3b, v45
	v_exp_f32_e32 v138, v45
	v_sub_f32_e32 v45, v175, v117
	global_load_dwordx4 v[172:175], v[6:7], off offset:256
	v_mfma_f32_16x16x32_bf16 v[52:55], v[52:55], v[12:15], 0
	v_sub_f32_e32 v44, v135, v117
	v_mul_f32_e32 v45, 0x3fb8aa3b, v45
	v_mul_f32_e32 v44, 0x3fb8aa3b, v44
	v_mfma_f32_16x16x32_bf16 v[60:63], v[60:63], v[12:15], 0
	v_exp_f32_e32 v136, v45
	v_exp_f32_e32 v148, v44
	v_add_u32_e32 v44, 0x8000, v210
	v_add_u32_e32 v45, 0x8000, v209
	v_mfma_f32_16x16x32_bf16 v[52:55], v[158:161], v[8:11], v[52:55]
	v_perm_b32 v44, v44, v45, s87
	v_add_u32_e32 v45, 0x8000, v144
	v_add_u32_e32 v46, 0x8000, v146
	v_perm_b32 v45, v45, v46, s87
	v_add_u32_e32 v46, 0x8000, v140
	v_add_u32_e32 v47, 0x8000, v142
	v_mfma_f32_16x16x32_bf16 v[60:63], v[162:165], v[8:11], v[60:63]
	v_perm_b32 v46, v46, v47, s87
	v_add_u32_e32 v47, 0x8000, v136
	v_add_u32_e32 v135, 0x8000, v138
	v_perm_b32 v47, v47, v135, s87
	v_max_f32_e32 v135, v53, v53
	v_max_f32_e32 v137, v52, v52
	v_max_f32_e32 v135, v137, v135
	v_max_f32_e32 v137, v55, v55
	v_max_f32_e32 v139, v54, v54
	v_max_f32_e32 v137, v139, v137
	v_max_f32_e32 v139, v63, v63
	v_max_f32_e32 v141, v62, v62
	v_max_f32_e32 v139, v141, v139
	v_max3_f32 v139, v60, v61, v139
	v_max3_f32 v135, v135, v137, v139
	v_mov_b32_e32 v137, v135
	s_nop 1
	v_permlane16_swap_b32_e32 v137, v135
	v_pk_mul_f32 v[58:59], v[58:59], v[148:149] op_sel_hi:[1,0]
	v_pk_mul_f32 v[56:57], v[56:57], v[148:149] op_sel_hi:[1,0]
	v_pk_mul_f32 v[18:19], v[18:19], v[148:149] op_sel_hi:[1,0]
	v_pk_mul_f32 v[16:17], v[16:17], v[148:149] op_sel_hi:[1,0]
	s_waitcnt lgkmcnt(0)
	v_max_f32_e32 v137, v137, v137
	v_max_f32_e32 v135, v135, v137
	v_mov_b32_e32 v137, v135
	s_nop 1
	v_permlane32_swap_b32_e32 v137, v135
	v_pk_mul_f32 v[26:27], v[26:27], v[148:149] op_sel_hi:[1,0]
	v_pk_mul_f32 v[24:25], v[24:25], v[148:149] op_sel_hi:[1,0]
	v_pk_mul_f32 v[22:23], v[22:23], v[148:149] op_sel_hi:[1,0]
	v_pk_mul_f32 v[20:21], v[20:21], v[148:149] op_sel_hi:[1,0]
	s_waitcnt lgkmcnt(0)
	v_max3_f32 v135, v152, v135, v137
	s_waitcnt vmcnt(1)
	v_mfma_f32_16x16x32_bf16 v[56:59], v[168:171], v[44:47], v[56:59]
	v_add_co_u32_e32 v6, vcc, s0, v204
	s_movk_i32 s0, 0x5000
	s_waitcnt vmcnt(0)
	v_mfma_f32_16x16x32_bf16 v[16:19], v[172:175], v[44:47], v[16:19]
	v_addc_co_u32_e32 v7, vcc, 0, v205, vcc
	global_load_dwordx4 v[194:197], v[6:7], off
	v_mfma_f32_16x16x32_bf16 v[24:27], v[176:179], v[44:47], v[24:27]
	v_add_co_u32_e32 v184, vcc, s1, v202
	v_mfma_f32_16x16x32_bf16 v[20:23], v[188:191], v[44:47], v[20:23]
	v_sub_f32_e32 v45, v52, v135
	v_mul_f32_e32 v45, 0x3fb8aa3b, v45
	v_exp_f32_e32 v213, v45
	v_sub_f32_e32 v45, v53, v135
	v_mul_f32_e32 v45, 0x3fb8aa3b, v45
	v_exp_f32_e32 v214, v45
	v_sub_f32_e32 v45, v54, v135
	v_mul_f32_e32 v45, 0x3fb8aa3b, v45
	v_exp_f32_e32 v164, v45
	v_sub_f32_e32 v45, v55, v135
	v_mul_f32_e32 v45, 0x3fb8aa3b, v45
	v_exp_f32_e32 v162, v45
	v_sub_f32_e32 v45, v60, v135
	v_mul_f32_e32 v45, 0x3fb8aa3b, v45
	v_exp_f32_e32 v160, v45
	v_sub_f32_e32 v45, v61, v135
	v_mul_f32_e32 v45, 0x3fb8aa3b, v45
	v_exp_f32_e32 v158, v45
	v_sub_f32_e32 v45, v62, v135
	v_mul_f32_e32 v45, 0x3fb8aa3b, v45
	v_exp_f32_e32 v156, v45
	v_sub_f32_e32 v45, v63, v135
	v_sub_f32_e32 v44, v152, v135
	v_mul_f32_e32 v45, 0x3fb8aa3b, v45
	v_mul_f32_e32 v44, 0x3fb8aa3b, v44
	v_exp_f32_e32 v154, v45
	v_exp_f32_e32 v166, v44
	v_add_u32_e32 v44, 0x8000, v214
	v_add_u32_e32 v45, 0x8000, v213
	v_perm_b32 v44, v44, v45, s87
	v_add_u32_e32 v45, 0x8000, v162
	v_add_u32_e32 v46, 0x8000, v164
	v_perm_b32 v45, v45, v46, s87
	v_add_u32_e32 v46, 0x8000, v158
	v_add_u32_e32 v47, 0x8000, v160
	v_perm_b32 v46, v46, v47, s87
	v_add_u32_e32 v47, 0x8000, v154
	v_add_u32_e32 v52, 0x8000, v156
	v_perm_b32 v47, v47, v52, s87
	global_load_dwordx4 v[52:55], v[6:7], off offset:3072
	global_load_dwordx4 v[60:63], v[6:7], off offset:16
	v_pk_mul_f32 v[30:31], v[30:31], v[166:167] op_sel_hi:[1,0]
	v_pk_mul_f32 v[28:29], v[28:29], v[166:167] op_sel_hi:[1,0]
	v_pk_mul_f32 v[34:35], v[34:35], v[166:167] op_sel_hi:[1,0]
	v_pk_mul_f32 v[32:33], v[32:33], v[166:167] op_sel_hi:[1,0]
	v_mfma_f32_16x16x32_bf16 v[28:31], v[172:175], v[44:47], v[28:31]
	global_load_dwordx4 v[172:175], v[6:7], off offset:3088
	v_pk_mul_f32 v[42:43], v[42:43], v[166:167] op_sel_hi:[1,0]
	v_pk_mul_f32 v[40:41], v[40:41], v[166:167] op_sel_hi:[1,0]
	v_mfma_f32_16x16x32_bf16 v[32:35], v[168:171], v[44:47], v[32:35]
	v_mul_f32_e64 v38, v38, v166
	v_mul_f32_e64 v39, v39, v166
	v_pk_mul_f32 v[36:37], v[36:37], v[166:167] op_sel_hi:[1,0]
	v_addc_co_u32_e32 v185, vcc, 0, v203, vcc
	s_waitcnt vmcnt(3)
	v_mfma_f32_16x16x32_bf16 v[168:171], v[194:197], v[48:51], 0
	global_load_dwordx4 v[216:219], v[184:185], off offset:-4096
	s_waitcnt vmcnt(3)
	v_mfma_f32_16x16x32_bf16 v[198:201], v[52:55], v[48:51], 0
	s_waitcnt vmcnt(2)
	v_mfma_f32_16x16x32_bf16 v[168:171], v[60:63], v[64:67], v[168:171]
	s_waitcnt vmcnt(1)
	v_mfma_f32_16x16x32_bf16 v[198:201], v[172:175], v[64:67], v[198:201]
	v_mfma_f32_16x16x32_bf16 v[40:43], v[176:179], v[44:47], v[40:43]
	s_nop 4
	v_max_f32_e32 v6, v169, v169
	v_max_f32_e32 v7, v168, v168
	v_max_f32_e32 v6, v7, v6
	v_max_f32_e32 v7, v171, v171
	v_max_f32_e32 v137, v170, v170
	v_max_f32_e32 v7, v137, v7
	v_max_f32_e32 v137, v201, v201
	v_max_f32_e32 v139, v200, v200
	v_max_f32_e32 v137, v139, v137
	v_max3_f32 v137, v198, v199, v137
	v_max3_f32 v7, v6, v7, v137
	v_mov_b32_e32 v137, v7
	s_nop 1
	v_permlane16_swap_b32_e32 v137, v7
	v_mfma_f32_16x16x32_bf16 v[36:39], v[188:191], v[44:47], v[36:39]
	v_add_co_u32_e32 v6, vcc, s0, v202
	s_mov_b32 s0, 0x24000
	s_waitcnt lgkmcnt(0)
	v_max_f32_e32 v137, v137, v137
	v_max_f32_e32 v137, v7, v137
	v_mov_b32_e32 v139, v137
	s_nop 1
	v_permlane32_swap_b32_e32 v139, v137
	v_mfma_f32_16x16x32_bf16 v[176:179], v[194:197], v[12:15], 0
	v_addc_co_u32_e32 v7, vcc, 0, v203, vcc
	global_load_dwordx4 v[188:191], v[6:7], off offset:512
	s_waitcnt lgkmcnt(0)
	v_max3_f32 v180, v117, v137, v139
	v_sub_f32_e32 v45, v168, v180
	v_mul_f32_e32 v45, 0x3fb8aa3b, v45
	v_exp_f32_e32 v147, v45
	v_sub_f32_e32 v45, v169, v180
	v_mul_f32_e32 v45, 0x3fb8aa3b, v45
	v_exp_f32_e32 v145, v45
	v_sub_f32_e32 v45, v170, v180
	v_mul_f32_e32 v45, 0x3fb8aa3b, v45
	v_exp_f32_e32 v143, v45
	v_sub_f32_e32 v45, v171, v180
	global_load_dwordx4 v[168:171], v[6:7], off offset:256
	v_mfma_f32_16x16x32_bf16 v[60:63], v[60:63], v[8:11], v[176:179]
	v_mul_f32_e32 v45, 0x3fb8aa3b, v45
	v_exp_f32_e32 v141, v45
	v_sub_f32_e32 v45, v198, v180
	global_load_dwordx4 v[176:179], v[6:7], off offset:768
	v_mul_f32_e32 v45, 0x3fb8aa3b, v45
	v_exp_f32_e32 v139, v45
	v_sub_f32_e32 v45, v199, v180
	v_mul_f32_e32 v45, 0x3fb8aa3b, v45
	v_exp_f32_e32 v137, v45
	v_sub_f32_e32 v45, v200, v180
	v_mul_f32_e32 v45, 0x3fb8aa3b, v45
	v_sub_f32_e32 v44, v117, v180
	v_exp_f32_e32 v117, v45
	v_sub_f32_e32 v45, v201, v180
	v_mfma_f32_16x16x32_bf16 v[52:55], v[52:55], v[12:15], 0
	v_mul_f32_e32 v45, 0x3fb8aa3b, v45
	v_mul_f32_e32 v44, 0x3fb8aa3b, v44
	v_exp_f32_e32 v212, v45
	v_exp_f32_e32 v152, v44
	v_add_u32_e32 v44, 0x8000, v145
	v_add_u32_e32 v45, 0x8000, v147
	v_perm_b32 v44, v44, v45, s87
	v_add_u32_e32 v45, 0x8000, v141
	v_add_u32_e32 v46, 0x8000, v143
	v_mfma_f32_16x16x32_bf16 v[52:55], v[172:175], v[8:11], v[52:55]
	v_perm_b32 v45, v45, v46, s87
	v_add_u32_e32 v46, 0x8000, v137
	v_add_u32_e32 v47, 0x8000, v139
	v_perm_b32 v46, v46, v47, s87
	v_add_u32_e32 v47, 0x8000, v212
	v_add_u32_e32 v155, 0x8000, v117
	v_max_f32_e32 v6, v61, v61
	v_max_f32_e32 v7, v60, v60
	v_perm_b32 v47, v47, v155, s87
	v_max_f32_e32 v6, v7, v6
	v_max_f32_e32 v7, v63, v63
	v_max_f32_e32 v155, v62, v62
	v_max_f32_e32 v7, v155, v7
	v_max_f32_e32 v155, v55, v55
	v_max_f32_e32 v157, v54, v54
	v_max_f32_e32 v155, v157, v155
	v_max3_f32 v155, v52, v53, v155
	v_max3_f32 v7, v6, v7, v155
	v_mov_b32_e32 v155, v7
	s_nop 1
	v_permlane16_swap_b32_e32 v155, v7
	v_pk_mul_f32 v[58:59], v[58:59], v[152:153] op_sel_hi:[1,0]
	v_pk_mul_f32 v[56:57], v[56:57], v[152:153] op_sel_hi:[1,0]
	v_pk_mul_f32 v[18:19], v[18:19], v[152:153] op_sel_hi:[1,0]
	v_pk_mul_f32 v[16:17], v[16:17], v[152:153] op_sel_hi:[1,0]
	s_waitcnt lgkmcnt(0)
	v_max_f32_e32 v155, v155, v155
	v_max_f32_e32 v155, v7, v155
	v_mov_b32_e32 v157, v155
	s_nop 1
	v_permlane32_swap_b32_e32 v157, v155
	v_pk_mul_f32 v[26:27], v[26:27], v[152:153] op_sel_hi:[1,0]
	v_pk_mul_f32 v[24:25], v[24:25], v[152:153] op_sel_hi:[1,0]
	v_pk_mul_f32 v[22:23], v[22:23], v[152:153] op_sel_hi:[1,0]
	v_pk_mul_f32 v[20:21], v[20:21], v[152:153] op_sel_hi:[1,0]
	s_waitcnt lgkmcnt(0)
	v_max3_f32 v173, v135, v155, v157
	s_waitcnt vmcnt(3)
	v_mfma_f32_16x16x32_bf16 v[56:59], v[216:219], v[44:47], v[56:59]
	v_add_co_u32_e32 v6, vcc, s0, v204
	s_mov_b32 s0, 0x2a000
	s_waitcnt vmcnt(1)
	v_mfma_f32_16x16x32_bf16 v[16:19], v[168:171], v[44:47], v[16:19]
	v_addc_co_u32_e32 v7, vcc, 0, v205, vcc
	global_load_dwordx4 v[194:197], v[6:7], off offset:16
	v_mfma_f32_16x16x32_bf16 v[24:27], v[188:191], v[44:47], v[24:27]
	global_load_dwordx4 v[198:201], v[6:7], off offset:3088
	v_add_co_u32_e32 v204, vcc, s0, v204
	s_waitcnt vmcnt(2)
	v_mfma_f32_16x16x32_bf16 v[20:23], v[176:179], v[44:47], v[20:23]
	v_sub_f32_e32 v45, v60, v173
	v_mul_f32_e32 v45, 0x3fb8aa3b, v45
	v_exp_f32_e32 v165, v45
	v_sub_f32_e32 v45, v61, v173
	v_mul_f32_e32 v45, 0x3fb8aa3b, v45
	v_exp_f32_e32 v163, v45
	v_sub_f32_e32 v45, v62, v173
	v_mul_f32_e32 v45, 0x3fb8aa3b, v45
	v_exp_f32_e32 v161, v45
	v_sub_f32_e32 v45, v63, v173
	v_mul_f32_e32 v45, 0x3fb8aa3b, v45
	v_exp_f32_e32 v159, v45
	v_sub_f32_e32 v45, v52, v173
	v_mul_f32_e32 v45, 0x3fb8aa3b, v45
	v_exp_f32_e32 v157, v45
	v_sub_f32_e32 v45, v53, v173
	v_mul_f32_e32 v45, 0x3fb8aa3b, v45
	v_exp_f32_e32 v155, v45
	v_sub_f32_e32 v45, v54, v173
	v_mul_f32_e32 v45, 0x3fb8aa3b, v45
	v_sub_f32_e32 v44, v135, v173
	v_exp_f32_e32 v135, v45
	v_sub_f32_e32 v45, v55, v173
	v_mul_f32_e32 v45, 0x3fb8aa3b, v45
	v_mul_f32_e32 v44, 0x3fb8aa3b, v44
	v_exp_f32_e32 v215, v45
	v_exp_f32_e32 v192, v44
	v_add_u32_e32 v44, 0x8000, v163
	v_add_u32_e32 v45, 0x8000, v165
	v_perm_b32 v44, v44, v45, s87
	v_add_u32_e32 v45, 0x8000, v159
	v_add_u32_e32 v46, 0x8000, v161
	v_perm_b32 v45, v45, v46, s87
	v_add_u32_e32 v46, 0x8000, v155
	v_add_u32_e32 v47, 0x8000, v157
	v_perm_b32 v46, v46, v47, s87
	v_add_u32_e32 v47, 0x8000, v215
	v_add_u32_e32 v52, 0x8000, v135
	v_perm_b32 v47, v47, v52, s87
	v_pk_mul_f32 v[30:31], v[30:31], v[192:193] op_sel_hi:[1,0]
	v_pk_mul_f32 v[28:29], v[28:29], v[192:193] op_sel_hi:[1,0]
	global_load_dwordx4 v[60:63], v[6:7], off
	v_pk_mul_f32 v[34:35], v[34:35], v[192:193] op_sel_hi:[1,0]
	v_mfma_f32_16x16x32_bf16 v[220:223], v[168:171], v[44:47], v[28:31]
	v_mul_f32_e64 v32, v32, v192
	v_mul_f32_e64 v33, v33, v192
	v_pk_mul_f32 v[38:39], v[38:39], v[192:193] op_sel_hi:[1,0]
	v_pk_mul_f32 v[36:37], v[36:37], v[192:193] op_sel_hi:[1,0]
	global_load_dwordx4 v[28:31], v[6:7], off offset:3072
	v_mfma_f32_16x16x32_bf16 v[52:55], v[216:219], v[44:47], v[32:35]
	v_mul_f32_e64 v42, v42, v192
	v_mul_f32_e64 v43, v43, v192
	v_pk_mul_f32 v[40:41], v[40:41], v[192:193] op_sel_hi:[1,0]
	v_addc_co_u32_e32 v205, vcc, 0, v205, vcc
	s_waitcnt vmcnt(1)
	v_mfma_f32_16x16x32_bf16 v[32:35], v[60:63], v[48:51], 0
	s_movk_i32 s0, 0x7000
	s_waitcnt vmcnt(0)
	v_mfma_f32_16x16x32_bf16 v[168:171], v[28:31], v[48:51], 0
	v_mfma_f32_16x16x32_bf16 v[32:35], v[194:197], v[64:67], v[32:35]
	v_mfma_f32_16x16x32_bf16 v[238:241], v[198:201], v[64:67], v[168:171]
	v_mfma_f32_16x16x32_bf16 v[250:253], v[176:179], v[44:47], v[36:39]
	s_nop 5
	v_max_f32_e32 v6, v33, v33
	v_max_f32_e32 v7, v32, v32
	v_max_f32_e32 v168, v241, v241
	v_max_f32_e32 v169, v240, v240
	v_max_f32_e32 v6, v7, v6
	v_max_f32_e32 v7, v35, v35
	v_max_f32_e32 v172, v34, v34
	v_max_f32_e32 v168, v169, v168
	v_max_f32_e32 v7, v172, v7
	v_max3_f32 v168, v238, v239, v168
	v_max3_f32 v6, v6, v7, v168
	v_mov_b32_e32 v7, v6
	s_nop 1
	v_permlane16_swap_b32_e32 v7, v6
	v_mfma_f32_16x16x32_bf16 v[246:249], v[188:191], v[44:47], v[40:43]
	s_waitcnt lgkmcnt(0)
	v_max_f32_e32 v7, v7, v7
	v_max_f32_e32 v6, v6, v7
	v_mov_b32_e32 v7, v6
	s_nop 1
	v_permlane32_swap_b32_e32 v7, v6
	s_waitcnt lgkmcnt(0)
	v_max3_f32 v6, v180, v6, v7
	v_sub_f32_e32 v32, v32, v6
	v_mul_f32_e32 v32, 0x3fb8aa3b, v32
	v_exp_f32_e32 v216, v32
	v_sub_f32_e32 v32, v33, v6
	v_mul_f32_e32 v32, 0x3fb8aa3b, v32
	v_exp_f32_e32 v217, v32
	v_sub_f32_e32 v32, v34, v6
	v_mul_f32_e32 v32, 0x3fb8aa3b, v32
	v_exp_f32_e32 v176, v32
	v_sub_f32_e32 v32, v35, v6
	v_mul_f32_e32 v32, 0x3fb8aa3b, v32
	v_exp_f32_e32 v174, v32
	v_sub_f32_e32 v32, v238, v6
	v_mul_f32_e32 v32, 0x3fb8aa3b, v32
	v_sub_f32_e32 v7, v180, v6
	v_exp_f32_e32 v172, v32
	v_sub_f32_e32 v32, v239, v6
	v_mul_f32_e32 v7, 0x3fb8aa3b, v7
	v_mul_f32_e32 v32, 0x3fb8aa3b, v32
	v_exp_f32_e32 v170, v32
	v_sub_f32_e32 v32, v240, v6
	v_exp_f32_e32 v180, v7
	v_mul_f32_e32 v32, 0x3fb8aa3b, v32
	v_exp_f32_e32 v168, v32
	v_sub_f32_e32 v32, v241, v6
	v_mul_f32_e32 v32, 0x3fb8aa3b, v32
	v_exp_f32_e32 v178, v32
	v_pk_mul_f32 v[34:35], v[58:59], v[180:181] op_sel_hi:[1,0]
	v_pk_mul_f32 v[32:33], v[56:57], v[180:181] op_sel_hi:[1,0]
	global_load_dwordx4 v[56:59], v[184:185], off
	global_load_dwordx4 v[238:241], v[184:185], off offset:256
	v_add_u32_e32 v7, 0x8000, v217
	v_add_u32_e32 v36, 0x8000, v216
	v_perm_b32 v44, v7, v36, s87
	v_add_u32_e32 v7, 0x8000, v174
	v_add_u32_e32 v36, 0x8000, v176
	v_perm_b32 v45, v7, v36, s87
	v_add_u32_e32 v7, 0x8000, v170
	v_add_u32_e32 v36, 0x8000, v172
	v_perm_b32 v46, v7, v36, s87
	v_add_u32_e32 v7, 0x8000, v178
	v_add_u32_e32 v36, 0x8000, v168
	v_pk_mul_f32 v[18:19], v[18:19], v[180:181] op_sel_hi:[1,0]
	v_pk_mul_f32 v[16:17], v[16:17], v[180:181] op_sel_hi:[1,0]
	v_perm_b32 v47, v7, v36, s87
	v_pk_mul_f32 v[26:27], v[26:27], v[180:181] op_sel_hi:[1,0]
	v_pk_mul_f32 v[24:25], v[24:25], v[180:181] op_sel_hi:[1,0]
	s_waitcnt vmcnt(0)
	v_mfma_f32_16x16x32_bf16 v[36:39], v[238:241], v[44:47], v[16:19]
	s_nop 2
	global_load_dwordx4 v[16:19], v[184:185], off offset:512
	v_pk_mul_f32 v[22:23], v[22:23], v[180:181] op_sel_hi:[1,0]
	global_load_dwordx4 v[184:187], v[184:185], off offset:768
	v_pk_mul_f32 v[20:21], v[20:21], v[180:181] op_sel_hi:[1,0]
	v_mfma_f32_16x16x32_bf16 v[32:35], v[56:59], v[44:47], v[32:35]
	s_waitcnt vmcnt(1)
	v_mfma_f32_16x16x32_bf16 v[40:43], v[16:19], v[44:47], v[24:27]
	s_waitcnt vmcnt(0)
	v_mfma_f32_16x16x32_bf16 v[44:47], v[184:187], v[44:47], v[20:23]
	v_mfma_f32_16x16x32_bf16 v[20:23], v[60:63], v[12:15], 0
	global_load_dwordx4 v[60:63], v[204:205], off
	v_mfma_f32_16x16x32_bf16 v[24:27], v[28:31], v[12:15], 0
	v_mfma_f32_16x16x32_bf16 v[20:23], v[194:197], v[8:11], v[20:23]
	v_mfma_f32_16x16x32_bf16 v[24:27], v[198:201], v[8:11], v[24:27]
	s_nop 6
	v_max_f32_e32 v7, v21, v21
	v_max_f32_e32 v28, v20, v20
	v_max_f32_e32 v7, v28, v7
	v_max_f32_e32 v28, v23, v23
	v_max_f32_e32 v29, v22, v22
	v_max_f32_e32 v28, v29, v28
	v_max_f32_e32 v29, v27, v27
	v_max_f32_e32 v30, v26, v26
	v_max_f32_e32 v29, v30, v29
	v_max3_f32 v29, v24, v25, v29
	v_max3_f32 v7, v7, v28, v29
	v_mov_b32_e32 v28, v7
	s_nop 1
	v_permlane16_swap_b32_e32 v28, v7
	s_waitcnt lgkmcnt(0)
	v_max_f32_e32 v28, v28, v28
	v_max_f32_e32 v7, v7, v28
	v_mov_b32_e32 v28, v7
	s_nop 1
	v_permlane32_swap_b32_e32 v28, v7
	s_waitcnt lgkmcnt(0)
	v_max3_f32 v189, v173, v7, v28
	v_sub_f32_e32 v7, v173, v189
	v_mul_f32_e32 v7, 0x3fb8aa3b, v7
	v_exp_f32_e32 v182, v7
	v_sub_f32_e32 v7, v20, v189
	v_sub_f32_e32 v20, v21, v189
	v_mul_f32_e32 v7, 0x3fb8aa3b, v7
	v_exp_f32_e32 v218, v7
	v_mul_f32_e32 v7, 0x3fb8aa3b, v20
	v_exp_f32_e32 v219, v7
	v_sub_f32_e32 v21, v22, v189
	v_sub_f32_e32 v22, v23, v189
	v_mul_f32_e32 v7, 0x3fb8aa3b, v21
	v_mul_f32_e32 v20, 0x3fb8aa3b, v22
	v_sub_f32_e32 v23, v24, v189
	v_sub_f32_e32 v24, v25, v189
	v_exp_f32_e32 v188, v20
	v_exp_f32_e32 v190, v7
	v_add_u32_e32 v7, 0x8000, v219
	v_add_u32_e32 v20, 0x8000, v218
	v_pk_mul_f32 v[28:29], v[52:53], v[182:183] op_sel_hi:[1,0]
	v_perm_b32 v52, v7, v20, s87
	v_mul_f32_e32 v7, 0x3fb8aa3b, v23
	v_mul_f32_e32 v20, 0x3fb8aa3b, v24
	v_exp_f32_e32 v194, v20
	v_exp_f32_e32 v196, v7
	v_sub_f32_e32 v25, v26, v189
	v_sub_f32_e32 v26, v27, v189
	v_add_u32_e32 v7, 0x8000, v194
	v_add_u32_e32 v20, 0x8000, v196
	v_pk_mul_f32 v[30:31], v[54:55], v[182:183] op_sel_hi:[1,0]
	v_perm_b32 v54, v7, v20, s87
	v_mul_f32_e32 v7, 0x3fb8aa3b, v25
	v_mul_f32_e32 v20, 0x3fb8aa3b, v26
	v_exp_f32_e32 v198, v20
	v_exp_f32_e32 v200, v7
	v_add_u32_e32 v21, 0x8000, v188
	v_add_u32_e32 v22, 0x8000, v190
	v_add_u32_e32 v7, 0x8000, v198
	v_add_u32_e32 v20, 0x8000, v200
	v_perm_b32 v53, v21, v22, s87
	v_perm_b32 v55, v7, v20, s87
	v_pk_mul_f32 v[22:23], v[222:223], v[182:183] op_sel_hi:[1,0]
	v_pk_mul_f32 v[20:21], v[220:221], v[182:183] op_sel_hi:[1,0]
	v_mfma_f32_16x16x32_bf16 v[28:31], v[56:59], v[52:55], v[28:31]
	global_load_dwordx4 v[56:59], v[204:205], off offset:3072
	v_mfma_f32_16x16x32_bf16 v[24:27], v[238:241], v[52:55], v[20:23]
	s_nop 2
	v_mul_f32_e64 v22, v248, v182
	v_mul_f32_e64 v23, v249, v182
	v_pk_mul_f32 v[20:21], v[246:247], v[182:183] op_sel_hi:[1,0]
	s_waitcnt vmcnt(0)
	v_mfma_f32_16x16x32_bf16 v[220:223], v[56:59], v[48:51], 0
	v_mfma_f32_16x16x32_bf16 v[20:23], v[16:19], v[52:55], v[20:23]
	v_mul_f32_e64 v18, v252, v182
	v_mul_f32_e64 v19, v253, v182
	v_pk_mul_f32 v[16:17], v[250:251], v[182:183] op_sel_hi:[1,0]
	s_nop 1
	v_mfma_f32_16x16x32_bf16 v[16:19], v[184:187], v[52:55], v[16:19]
	global_load_dwordx4 v[52:55], v[204:205], off offset:16
	v_mfma_f32_16x16x32_bf16 v[184:187], v[60:63], v[48:51], 0
	global_load_dwordx4 v[48:51], v[204:205], off offset:3088
	s_waitcnt vmcnt(1)
	v_mfma_f32_16x16x32_bf16 v[184:187], v[52:55], v[64:67], v[184:187]
	s_nop 7
	v_max_f32_e32 v7, v185, v185
	s_waitcnt vmcnt(0)
	v_mfma_f32_16x16x32_bf16 v[220:223], v[48:51], v[64:67], v[220:223]
	v_max_f32_e32 v64, v184, v184
	v_max_f32_e32 v7, v64, v7
	v_max_f32_e32 v64, v187, v187
	v_max_f32_e32 v65, v186, v186
	v_max_f32_e32 v64, v65, v64
	s_nop 2
	v_max_f32_e32 v65, v223, v223
	v_max_f32_e32 v66, v222, v222
	v_max_f32_e32 v65, v66, v65
	v_max3_f32 v65, v220, v221, v65
	v_max3_f32 v7, v7, v64, v65
	v_mov_b32_e32 v64, v7
	s_nop 1
	v_permlane16_swap_b32_e32 v64, v7
	v_mfma_f32_16x16x32_bf16 v[60:63], v[60:63], v[12:15], 0
	s_waitcnt lgkmcnt(0)
	v_max_f32_e32 v64, v64, v64
	v_max_f32_e32 v7, v7, v64
	v_mov_b32_e32 v64, v7
	s_nop 1
	v_permlane32_swap_b32_e32 v64, v7
	v_mfma_f32_16x16x32_bf16 v[12:15], v[56:59], v[12:15], 0
	s_waitcnt lgkmcnt(0)
	v_max3_f32 v173, v6, v7, v64
	v_sub_f32_e32 v66, v220, v173
	v_add_co_u32_e32 v220, vcc, s0, v202
	v_sub_f32_e32 v65, v221, v173
	s_nop 0
	v_addc_co_u32_e32 v221, vcc, 0, v203, vcc
	global_load_dwordx4 v[56:59], v[220:221], off
	v_sub_f32_e32 v175, v184, v173
	v_sub_f32_e32 v171, v185, v173
	v_sub_f32_e32 v169, v186, v173
	v_sub_f32_e32 v67, v187, v173
	v_sub_f32_e32 v64, v222, v173
	v_sub_f32_e32 v7, v223, v173
	v_sub_f32_e32 v6, v6, v173
	v_mul_f32_e32 v173, 0x3fb8aa3b, v175
	v_mul_f32_e32 v171, 0x3fb8aa3b, v171
	v_exp_f32_e32 v177, v173
	v_exp_f32_e32 v175, v171
	v_mul_f32_e32 v169, 0x3fb8aa3b, v169
	v_mul_f32_e32 v67, 0x3fb8aa3b, v67
	v_exp_f32_e32 v173, v169
	v_exp_f32_e32 v171, v67
	v_mul_f32_e32 v66, 0x3fb8aa3b, v66
	v_mul_f32_e32 v65, 0x3fb8aa3b, v65
	v_exp_f32_e32 v169, v66
	v_exp_f32_e32 v179, v65
	v_mul_f32_e32 v64, 0x3fb8aa3b, v64
	v_mul_f32_e32 v7, 0x3fb8aa3b, v7
	v_mul_f32_e32 v6, 0x3fb8aa3b, v6
	v_exp_f32_e32 v67, v64
	v_exp_f32_e32 v65, v7
	v_exp_f32_e32 v64, v6
	v_add_u32_e32 v6, 0x8000, v175
	v_add_u32_e32 v7, 0x8000, v177
	v_perm_b32 v184, v6, v7, s87
	v_add_u32_e32 v6, 0x8000, v171
	v_add_u32_e32 v7, 0x8000, v173
	v_perm_b32 v185, v6, v7, s87
	v_add_u32_e32 v6, 0x8000, v179
	v_add_u32_e32 v7, 0x8000, v169
	v_perm_b32 v186, v6, v7, s87
	v_add_u32_e32 v6, 0x8000, v65
	v_add_u32_e32 v7, 0x8000, v67
	v_mfma_f32_16x16x32_bf16 v[52:55], v[52:55], v[8:11], v[60:63]
	v_perm_b32 v187, v6, v7, s87
	v_pk_mul_f32 v[6:7], v[32:33], v[64:65] op_sel_hi:[1,0]
	v_pk_mul_f32 v[204:205], v[46:47], v[64:65] op_sel_hi:[1,0]
	v_mfma_f32_16x16x32_bf16 v[48:51], v[48:51], v[8:11], v[12:15]
	v_mul_f32_e64 v8, v34, v64
	v_mul_f32_e64 v9, v35, v64
	v_pk_mul_f32 v[202:203], v[44:45], v[64:65] op_sel_hi:[1,0]
	global_load_dwordx4 v[44:47], v[220:221], off offset:256
	s_waitcnt vmcnt(1)
	v_mfma_f32_16x16x32_bf16 v[32:35], v[56:59], v[184:187], v[6:9]
	s_nop 2
	v_mul_f32_e64 v8, v38, v64
	v_mul_f32_e64 v9, v39, v64
	v_pk_mul_f32 v[6:7], v[36:37], v[64:65] op_sel_hi:[1,0]
	v_pk_mul_f32 v[38:39], v[42:43], v[64:65] op_sel_hi:[1,0]
	v_pk_mul_f32 v[36:37], v[40:41], v[64:65] op_sel_hi:[1,0]
	global_load_dwordx4 v[40:43], v[220:221], off offset:512
	global_load_dwordx4 v[60:63], v[220:221], off offset:768
	v_max_f32_e32 v14, v53, v53
	v_max_f32_e32 v15, v52, v52
	v_max_f32_e32 v14, v15, v14
	v_max_f32_e32 v15, v55, v55
	v_max_f32_e32 v66, v54, v54
	s_waitcnt vmcnt(2)
	v_mfma_f32_16x16x32_bf16 v[10:13], v[44:47], v[184:187], v[6:9]
	v_max_f32_e32 v15, v66, v15
	v_max_f32_e32 v66, v51, v51
	s_waitcnt vmcnt(1)
	v_mfma_f32_16x16x32_bf16 v[6:9], v[40:43], v[184:187], v[36:39]
	s_waitcnt vmcnt(0)
	v_mfma_f32_16x16x32_bf16 v[36:39], v[60:63], v[184:187], v[202:205]
	v_max_f32_e32 v184, v50, v50
	v_max_f32_e32 v66, v184, v66
	v_max3_f32 v66, v48, v49, v66
	v_max3_f32 v14, v14, v15, v66
	v_mov_b32_e32 v15, v14
	s_nop 1
	v_permlane16_swap_b32_e32 v15, v14
	s_waitcnt lgkmcnt(0)
	v_max_f32_e32 v15, v15, v15
	v_max_f32_e32 v14, v14, v15
	v_mov_b32_e32 v15, v14
	s_nop 1
	v_permlane32_swap_b32_e32 v15, v14
	s_waitcnt lgkmcnt(0)
	v_max3_f32 v14, v189, v14, v15
	v_sub_f32_e32 v52, v52, v14
	v_mul_f32_e32 v52, 0x3fb8aa3b, v52
	v_exp_f32_e32 v191, v52
	v_sub_f32_e32 v52, v53, v14
	v_mul_f32_e32 v52, 0x3fb8aa3b, v52
	v_sub_f32_e32 v15, v189, v14
	v_exp_f32_e32 v189, v52
	v_sub_f32_e32 v52, v54, v14
	v_sub_f32_e32 v48, v48, v14
	v_mul_f32_e32 v52, 0x3fb8aa3b, v52
	v_mul_f32_e32 v48, 0x3fb8aa3b, v48
	v_exp_f32_e32 v197, v52
	v_sub_f32_e32 v52, v55, v14
	v_exp_f32_e32 v201, v48
	v_sub_f32_e32 v48, v49, v14
	v_mul_f32_e32 v52, 0x3fb8aa3b, v52
	v_mul_f32_e32 v48, 0x3fb8aa3b, v48
	v_exp_f32_e32 v195, v52
	v_exp_f32_e32 v199, v48
	v_sub_f32_e32 v48, v50, v14
	v_sub_f32_e32 v14, v51, v14
	v_mul_f32_e32 v48, 0x3fb8aa3b, v48
	v_mul_f32_e32 v14, 0x3fb8aa3b, v14
	v_mul_f32_e32 v15, 0x3fb8aa3b, v15
	v_exp_f32_e32 v53, v48
	v_exp_f32_e32 v51, v14
	v_exp_f32_e32 v50, v15
	v_add_u32_e32 v14, 0x8000, v189
	v_add_u32_e32 v15, 0x8000, v191
	v_perm_b32 v184, v14, v15, s87
	v_add_u32_e32 v14, 0x8000, v195
	v_add_u32_e32 v15, 0x8000, v197
	v_perm_b32 v185, v14, v15, s87
	v_add_u32_e32 v14, 0x8000, v199
	v_add_u32_e32 v15, 0x8000, v201
	v_perm_b32 v186, v14, v15, s87
	v_add_u32_e32 v14, 0x8000, v51
	v_add_u32_e32 v15, 0x8000, v53
	v_perm_b32 v187, v14, v15, s87
	v_lshl_add_u64 v[14:15], s[6:7], 0, v[0:1]
	v_lshlrev_b32_e32 v0, 11, v89
	v_lshl_add_u64 v[48:49], v[14:15], 0, s[44:45]
	v_lshl_add_u64 v[14:15], s[6:7], 0, v[0:1]
	v_pk_mul_f32 v[22:23], v[22:23], v[50:51] op_sel_hi:[1,0]
	v_pk_mul_f32 v[20:21], v[20:21], v[50:51] op_sel_hi:[1,0]
	v_pk_mul_f32 v[18:19], v[18:19], v[50:51] op_sel_hi:[1,0]
	v_pk_mul_f32 v[16:17], v[16:17], v[50:51] op_sel_hi:[1,0]
	v_add_f32_e32 v0, 0, v218
	v_mfma_f32_16x16x32_bf16 v[20:23], v[40:43], v[184:187], v[20:23]
	v_lshl_add_u64 v[40:41], v[14:15], 0, s[44:45]
	v_pk_mul_f32 v[26:27], v[26:27], v[50:51] op_sel_hi:[1,0]
	v_pk_mul_f32 v[24:25], v[24:25], v[50:51] op_sel_hi:[1,0]
	v_mfma_f32_16x16x32_bf16 v[14:17], v[60:63], v[184:187], v[16:19]
	v_mov_b32_e32 v43, v1
	v_mov_b32_e32 v89, v1
	v_pk_mul_f32 v[30:31], v[30:31], v[50:51] op_sel_hi:[1,0]
	v_add_f32_e32 v18, v219, v0
	v_add_f32_e32 v0, 0, v213
	v_add_f32_e32 v42, v214, v0
	v_add_f32_e32 v0, 0, v207
	v_mfma_f32_16x16x32_bf16 v[24:27], v[44:47], v[184:187], v[24:27]
	v_add_f32_e32 v44, v208, v0
	v_add_f32_e32 v0, 0, v151
	v_add_f32_e32 v0, v153, v0
	v_pk_add_f32 v[46:47], v[112:113], v[0:1]
	v_mov_b32_e32 v45, v1
	v_pk_add_f32 v[46:47], v[110:111], v[46:47]
	v_pk_mul_f32 v[28:29], v[28:29], v[50:51] op_sel_hi:[1,0]
	v_pk_add_f32 v[46:47], v[108:109], v[46:47]
	s_nop 0
	v_pk_add_f32 v[46:47], v[106:107], v[46:47]
	v_mfma_f32_16x16x32_bf16 v[28:31], v[56:59], v[184:187], v[28:31]
	v_add_f32_e64 v46, v104, v46
	v_add_f32_e64 v47, v105, v47
	v_pk_add_f32 v[46:47], v[102:103], v[46:47]
	s_nop 0
	v_pk_add_f32 v[4:5], v[4:5], v[46:47]
	s_nop 0
	v_add_f32_e32 v0, v5, v206
	v_fmac_f32_e32 v0, v4, v118
	v_pk_add_f32 v[4:5], v[132:133], v[44:45]
	v_mul_f32_e32 v118, v0, v134
	v_pk_add_f32 v[4:5], v[130:131], v[4:5]
	s_nop 0
	v_pk_add_f32 v[4:5], v[128:129], v[4:5]
	s_nop 0
	v_pk_add_f32 v[4:5], v[126:127], v[4:5]
	s_nop 0
	v_pk_add_f32 v[4:5], v[124:125], v[4:5]
	s_nop 0
	v_pk_add_f32 v[4:5], v[122:123], v[4:5]
	s_nop 0
	v_pk_add_f32 v[4:5], v[118:119], v[4:5]
	s_nop 0
	v_add_f32_e32 v0, v5, v211
	v_fmac_f32_e32 v0, v4, v150
	v_pk_add_f32 v[4:5], v[164:165], v[42:43]
	v_mul_f32_e32 v134, v0, v166
	v_pk_add_f32 v[4:5], v[162:163], v[4:5]
	v_add_f32_e32 v0, 0, v216
	v_pk_add_f32 v[4:5], v[160:161], v[4:5]
	s_nop 0
	v_pk_add_f32 v[4:5], v[158:159], v[4:5]
	s_nop 0
	v_pk_add_f32 v[4:5], v[156:157], v[4:5]
	s_nop 0
	v_pk_add_f32 v[4:5], v[154:155], v[4:5]
	s_nop 0
	v_pk_add_f32 v[4:5], v[134:135], v[4:5]
	s_nop 0
	v_add_f32_e32 v19, v5, v215
	v_fmac_f32_e32 v19, v4, v192
	v_add_f32_e32 v4, v217, v0
	v_add_f32_e32 v0, 0, v209
	v_add_f32_e32 v42, v210, v0
	v_add_f32_e32 v0, 0, v181
	v_add_f32_e32 v44, v193, v0
	v_add_f32_e32 v0, 0, v85
	v_add_f32_e32 v0, v87, v0
	v_pk_add_f32 v[46:47], v[100:101], v[0:1]
	v_mov_b32_e32 v5, v1
	v_pk_add_f32 v[46:47], v[98:99], v[46:47]
	v_mul_f32_e32 v52, v19, v182
	v_pk_add_f32 v[46:47], v[96:97], v[46:47]
	v_mov_b32_e32 v19, v1
	v_pk_add_f32 v[46:47], v[94:95], v[46:47]
	s_nop 0
	v_pk_add_f32 v[46:47], v[92:93], v[46:47]
	s_nop 0
	v_pk_add_f32 v[46:47], v[90:91], v[46:47]
	s_nop 0
	v_pk_add_f32 v[2:3], v[2:3], v[46:47]
	s_nop 0
	v_add_f32_e32 v0, v3, v167
	v_fmac_f32_e32 v0, v2, v114
	v_pk_add_f32 v[2:3], v[78:79], v[44:45]
	v_mul_f32_e32 v114, v0, v116
	v_pk_add_f32 v[2:3], v[76:77], v[2:3]
	s_nop 0
	v_pk_add_f32 v[2:3], v[74:75], v[2:3]
	s_nop 0
	v_pk_add_f32 v[2:3], v[72:73], v[2:3]
	s_nop 0
	v_pk_add_f32 v[2:3], v[70:71], v[2:3]
	s_nop 0
	v_pk_add_f32 v[2:3], v[68:69], v[2:3]
	s_nop 0
	v_pk_add_f32 v[2:3], v[114:115], v[2:3]
	s_nop 0
	v_add_f32_e32 v0, v3, v121
	v_fmac_f32_e32 v0, v2, v120
	v_pk_add_f32 v[2:3], v[146:147], v[42:43]
	v_mul_f32_e32 v116, v0, v148
	v_pk_add_f32 v[2:3], v[144:145], v[2:3]
	s_nop 0
	v_pk_add_f32 v[2:3], v[142:143], v[2:3]
	s_nop 0
	v_pk_add_f32 v[2:3], v[140:141], v[2:3]
	s_nop 0
	v_pk_add_f32 v[2:3], v[138:139], v[2:3]
	s_nop 0
	v_pk_add_f32 v[2:3], v[136:137], v[2:3]
	s_nop 0
	v_pk_add_f32 v[2:3], v[116:117], v[2:3]
	s_nop 0
	v_add_f32_e32 v0, v3, v212
	v_fmac_f32_e32 v0, v2, v152
	v_pk_add_f32 v[2:3], v[176:177], v[4:5]
	v_mul_f32_e32 v66, v0, v180
	v_pk_add_f32 v[2:3], v[174:175], v[2:3]
	s_nop 0
	v_pk_add_f32 v[2:3], v[172:173], v[2:3]
	s_nop 0
	v_pk_add_f32 v[2:3], v[170:171], v[2:3]
	s_nop 0
	v_pk_add_f32 v[2:3], v[168:169], v[2:3]
	s_nop 0
	v_pk_add_f32 v[2:3], v[178:179], v[2:3]
	s_nop 0
	v_pk_add_f32 v[2:3], v[66:67], v[2:3]
	s_nop 0
	v_add_f32_e32 v0, v3, v65
	v_fmac_f32_e32 v0, v2, v64
	v_mov_b32_e32 v4, v0
	s_nop 1
	v_permlane16_swap_b32_e32 v4, v0
	v_pk_add_f32 v[2:3], v[190:191], v[18:19]
	s_waitcnt lgkmcnt(0)
	v_add_f32_e32 v0, v0, v4
	v_mov_b32_e32 v4, v0
	s_nop 1
	v_permlane32_swap_b32_e32 v4, v0
	v_pk_add_f32 v[2:3], v[188:189], v[2:3]
	s_waitcnt lgkmcnt(0)
	v_add_f32_e32 v0, v0, v4
	v_pk_add_f32 v[2:3], v[196:197], v[2:3]
	v_div_scale_f32 v4, s[0:1], v0, v0, 1.0
	v_pk_add_f32 v[2:3], v[194:195], v[2:3]
	v_rcp_f32_e32 v5, v4
	v_pk_add_f32 v[2:3], v[200:201], v[2:3]
	s_nop 0
	v_pk_add_f32 v[2:3], v[198:199], v[2:3]
	s_nop 0
	v_pk_add_f32 v[2:3], v[52:53], v[2:3]
	s_nop 0
	v_add_f32_e32 v42, v3, v51
	v_fmac_f32_e32 v42, v2, v50
	v_fma_f32 v2, -v4, v5, 1.0
	v_fmac_f32_e32 v5, v2, v5
	v_div_scale_f32 v2, vcc, 1.0, v0, 1.0
	v_mul_f32_e32 v3, v2, v5
	v_fma_f32 v18, -v4, v3, v2
	v_fmac_f32_e32 v3, v18, v5
	v_fma_f32 v2, -v4, v3, v2
	v_div_fmas_f32 v2, v2, v5, v3
	v_div_fixup_f32 v0, v2, v0, 1.0
	v_mov_b32_e32 v2, v32
	v_mov_b32_e32 v3, v34
	v_pk_mul_f32 v[2:3], v[2:3], v[0:1] op_sel_hi:[1,0]
	v_mov_b32_e32 v34, v33
	v_pk_mul_f32 v[4:5], v[34:35], v[0:1] op_sel_hi:[1,0]
	v_and_b32_sdwa v18, v3, v236 dst_sel:DWORD dst_unused:UNUSED_PAD src0_sel:WORD_1 src1_sel:DWORD
	v_and_b32_sdwa v19, v2, v236 dst_sel:DWORD dst_unused:UNUSED_PAD src0_sel:WORD_1 src1_sel:DWORD
	v_add3_u32 v2, v2, v19, s60
	v_add3_u32 v3, v3, v18, s60
	v_and_b32_sdwa v18, v5, v236 dst_sel:DWORD dst_unused:UNUSED_PAD src0_sel:WORD_1 src1_sel:DWORD
	v_and_b32_sdwa v19, v4, v236 dst_sel:DWORD dst_unused:UNUSED_PAD src0_sel:WORD_1 src1_sel:DWORD
	v_add3_u32 v5, v5, v18, s60
	v_add3_u32 v4, v4, v19, s60
	v_and_b32_e32 v5, 0xffff0000, v5
	v_and_b32_e32 v4, 0xffff0000, v4
	v_or_b32_sdwa v3, v5, v3 dst_sel:DWORD dst_unused:UNUSED_PAD src0_sel:DWORD src1_sel:WORD_1
	v_or_b32_sdwa v2, v4, v2 dst_sel:DWORD dst_unused:UNUSED_PAD src0_sel:DWORD src1_sel:WORD_1
	v_lshl_add_u64 v[4:5], v[48:49], 0, v[88:89]
	v_lshl_add_u64 v[18:19], v[4:5], 0, s[18:19]
	v_add_co_u32_e32 v4, vcc, s2, v4
	s_nop 1
	v_addc_co_u32_e32 v5, vcc, 0, v5, vcc
	global_store_dwordx2 v[4:5], v[2:3], off offset:512
	v_mov_b32_e32 v2, v10
	v_mov_b32_e32 v3, v12
	v_pk_mul_f32 v[2:3], v[2:3], v[0:1] op_sel_hi:[1,0]
	v_mov_b32_e32 v12, v11
	v_pk_mul_f32 v[4:5], v[12:13], v[0:1] op_sel_hi:[1,0]
	v_and_b32_sdwa v10, v3, v236 dst_sel:DWORD dst_unused:UNUSED_PAD src0_sel:WORD_1 src1_sel:DWORD
	v_and_b32_sdwa v11, v2, v236 dst_sel:DWORD dst_unused:UNUSED_PAD src0_sel:WORD_1 src1_sel:DWORD
	v_add3_u32 v2, v2, v11, s60
	v_add3_u32 v3, v3, v10, s60
	v_and_b32_sdwa v10, v5, v236 dst_sel:DWORD dst_unused:UNUSED_PAD src0_sel:WORD_1 src1_sel:DWORD
	v_and_b32_sdwa v11, v4, v236 dst_sel:DWORD dst_unused:UNUSED_PAD src0_sel:WORD_1 src1_sel:DWORD
	v_add3_u32 v5, v5, v10, s60
	v_add3_u32 v4, v4, v11, s60
	v_and_b32_e32 v5, 0xffff0000, v5
	v_and_b32_e32 v4, 0xffff0000, v4
	v_or_b32_sdwa v3, v5, v3 dst_sel:DWORD dst_unused:UNUSED_PAD src0_sel:DWORD src1_sel:WORD_1
	v_or_b32_sdwa v2, v4, v2 dst_sel:DWORD dst_unused:UNUSED_PAD src0_sel:DWORD src1_sel:WORD_1
	global_store_dwordx2 v[18:19], v[2:3], off offset:32
	v_mov_b32_e32 v2, v6
	v_mov_b32_e32 v3, v8
	v_pk_mul_f32 v[2:3], v[2:3], v[0:1] op_sel_hi:[1,0]
	v_mov_b32_e32 v8, v7
	v_pk_mul_f32 v[4:5], v[8:9], v[0:1] op_sel_hi:[1,0]
	v_and_b32_sdwa v7, v2, v236 dst_sel:DWORD dst_unused:UNUSED_PAD src0_sel:WORD_1 src1_sel:DWORD
	v_add3_u32 v2, v2, v7, s60
	v_and_b32_sdwa v7, v4, v236 dst_sel:DWORD dst_unused:UNUSED_PAD src0_sel:WORD_1 src1_sel:DWORD
	v_add3_u32 v4, v4, v7, s60
	v_mov_b32_e32 v7, v42
	s_nop 1
	v_permlane16_swap_b32_e32 v7, v42
	v_and_b32_sdwa v6, v3, v236 dst_sel:DWORD dst_unused:UNUSED_PAD src0_sel:WORD_1 src1_sel:DWORD
	v_add3_u32 v3, v3, v6, s60
	v_and_b32_sdwa v6, v5, v236 dst_sel:DWORD dst_unused:UNUSED_PAD src0_sel:WORD_1 src1_sel:DWORD
	v_add3_u32 v5, v5, v6, s60
	v_and_b32_e32 v5, 0xffff0000, v5
	v_and_b32_e32 v4, 0xffff0000, v4
	s_waitcnt lgkmcnt(0)
	v_add_f32_e32 v7, v42, v7
	v_or_b32_sdwa v3, v5, v3 dst_sel:DWORD dst_unused:UNUSED_PAD src0_sel:DWORD src1_sel:WORD_1
	v_or_b32_sdwa v2, v4, v2 dst_sel:DWORD dst_unused:UNUSED_PAD src0_sel:DWORD src1_sel:WORD_1
	v_mov_b32_e32 v8, v7
	s_nop 1
	v_permlane32_swap_b32_e32 v8, v7
	global_store_dwordx2 v[18:19], v[2:3], off offset:64
	v_mov_b32_e32 v2, v36
	v_mov_b32_e32 v3, v38
	v_pk_mul_f32 v[2:3], v[2:3], v[0:1] op_sel_hi:[1,0]
	v_mov_b32_e32 v38, v37
	v_pk_mul_f32 v[4:5], v[38:39], v[0:1] op_sel_hi:[1,0]
	v_and_b32_sdwa v0, v3, v236 dst_sel:DWORD dst_unused:UNUSED_PAD src0_sel:WORD_1 src1_sel:DWORD
	v_and_b32_sdwa v6, v2, v236 dst_sel:DWORD dst_unused:UNUSED_PAD src0_sel:WORD_1 src1_sel:DWORD
	v_add3_u32 v0, v3, v0, s60
	v_and_b32_sdwa v3, v5, v236 dst_sel:DWORD dst_unused:UNUSED_PAD src0_sel:WORD_1 src1_sel:DWORD
	v_add3_u32 v2, v2, v6, s60
	v_and_b32_sdwa v6, v4, v236 dst_sel:DWORD dst_unused:UNUSED_PAD src0_sel:WORD_1 src1_sel:DWORD
	v_add3_u32 v3, v5, v3, s60
	s_waitcnt lgkmcnt(0)
	v_add_f32_e32 v5, v7, v8
	v_add3_u32 v4, v4, v6, s60
	v_div_scale_f32 v6, s[0:1], v5, v5, 1.0
	v_rcp_f32_e32 v7, v6
	v_and_b32_e32 v3, 0xffff0000, v3
	v_and_b32_e32 v4, 0xffff0000, v4
	v_or_b32_sdwa v3, v3, v0 dst_sel:DWORD dst_unused:UNUSED_PAD src0_sel:DWORD src1_sel:WORD_1
	v_fma_f32 v0, -v6, v7, 1.0
	v_or_b32_sdwa v2, v4, v2 dst_sel:DWORD dst_unused:UNUSED_PAD src0_sel:DWORD src1_sel:WORD_1
	v_fmac_f32_e32 v7, v0, v7
	v_div_scale_f32 v0, vcc, 1.0, v5, 1.0
	global_store_dwordx2 v[18:19], v[2:3], off offset:96
	v_mul_f32_e32 v2, v0, v7
	v_fma_f32 v3, -v6, v2, v0
	v_fmac_f32_e32 v2, v3, v7
	v_fma_f32 v0, -v6, v2, v0
	v_div_fmas_f32 v0, v0, v7, v2
	v_div_fixup_f32 v0, v0, v5, 1.0
	v_mov_b32_e32 v2, v28
	v_mov_b32_e32 v3, v30
	v_pk_mul_f32 v[2:3], v[2:3], v[0:1] op_sel_hi:[1,0]
	v_mov_b32_e32 v30, v29
	v_pk_mul_f32 v[4:5], v[30:31], v[0:1] op_sel_hi:[1,0]
	v_and_b32_sdwa v6, v3, v236 dst_sel:DWORD dst_unused:UNUSED_PAD src0_sel:WORD_1 src1_sel:DWORD
	v_and_b32_sdwa v7, v2, v236 dst_sel:DWORD dst_unused:UNUSED_PAD src0_sel:WORD_1 src1_sel:DWORD
	v_add3_u32 v2, v2, v7, s60
	v_add3_u32 v3, v3, v6, s60
	v_and_b32_sdwa v6, v5, v236 dst_sel:DWORD dst_unused:UNUSED_PAD src0_sel:WORD_1 src1_sel:DWORD
	v_and_b32_sdwa v7, v4, v236 dst_sel:DWORD dst_unused:UNUSED_PAD src0_sel:WORD_1 src1_sel:DWORD
	v_add3_u32 v5, v5, v6, s60
	v_add3_u32 v4, v4, v7, s60
	v_and_b32_e32 v5, 0xffff0000, v5
	v_and_b32_e32 v4, 0xffff0000, v4
	v_or_b32_sdwa v3, v5, v3 dst_sel:DWORD dst_unused:UNUSED_PAD src0_sel:DWORD src1_sel:WORD_1
	v_or_b32_sdwa v2, v4, v2 dst_sel:DWORD dst_unused:UNUSED_PAD src0_sel:DWORD src1_sel:WORD_1
	v_lshl_add_u64 v[4:5], v[40:41], 0, v[88:89]
	v_lshl_add_u64 v[6:7], v[4:5], 0, s[18:19]
	v_add_co_u32_e32 v4, vcc, s2, v4
	s_nop 1
	v_addc_co_u32_e32 v5, vcc, 0, v5, vcc
	global_store_dwordx2 v[4:5], v[2:3], off offset:512
	v_mov_b32_e32 v2, v24
	v_mov_b32_e32 v3, v26
	v_pk_mul_f32 v[2:3], v[2:3], v[0:1] op_sel_hi:[1,0]
	v_mov_b32_e32 v26, v25
	v_pk_mul_f32 v[4:5], v[26:27], v[0:1] op_sel_hi:[1,0]
	v_and_b32_sdwa v8, v3, v236 dst_sel:DWORD dst_unused:UNUSED_PAD src0_sel:WORD_1 src1_sel:DWORD
	v_and_b32_sdwa v9, v2, v236 dst_sel:DWORD dst_unused:UNUSED_PAD src0_sel:WORD_1 src1_sel:DWORD
	v_add3_u32 v2, v2, v9, s60
	v_add3_u32 v3, v3, v8, s60
	v_and_b32_sdwa v8, v5, v236 dst_sel:DWORD dst_unused:UNUSED_PAD src0_sel:WORD_1 src1_sel:DWORD
	v_and_b32_sdwa v9, v4, v236 dst_sel:DWORD dst_unused:UNUSED_PAD src0_sel:WORD_1 src1_sel:DWORD
	v_add3_u32 v5, v5, v8, s60
	v_add3_u32 v4, v4, v9, s60
	v_and_b32_e32 v5, 0xffff0000, v5
	v_and_b32_e32 v4, 0xffff0000, v4
	v_or_b32_sdwa v3, v5, v3 dst_sel:DWORD dst_unused:UNUSED_PAD src0_sel:DWORD src1_sel:WORD_1
	v_or_b32_sdwa v2, v4, v2 dst_sel:DWORD dst_unused:UNUSED_PAD src0_sel:DWORD src1_sel:WORD_1
	global_store_dwordx2 v[6:7], v[2:3], off offset:32
	v_mov_b32_e32 v2, v20
	v_mov_b32_e32 v3, v22
	v_pk_mul_f32 v[2:3], v[2:3], v[0:1] op_sel_hi:[1,0]
	v_mov_b32_e32 v22, v21
	v_pk_mul_f32 v[4:5], v[22:23], v[0:1] op_sel_hi:[1,0]
	v_and_b32_sdwa v8, v3, v236 dst_sel:DWORD dst_unused:UNUSED_PAD src0_sel:WORD_1 src1_sel:DWORD
	v_and_b32_sdwa v9, v2, v236 dst_sel:DWORD dst_unused:UNUSED_PAD src0_sel:WORD_1 src1_sel:DWORD
	v_add3_u32 v2, v2, v9, s60
	v_add3_u32 v3, v3, v8, s60
	v_and_b32_sdwa v8, v5, v236 dst_sel:DWORD dst_unused:UNUSED_PAD src0_sel:WORD_1 src1_sel:DWORD
	v_and_b32_sdwa v9, v4, v236 dst_sel:DWORD dst_unused:UNUSED_PAD src0_sel:WORD_1 src1_sel:DWORD
	v_add3_u32 v5, v5, v8, s60
	v_add3_u32 v4, v4, v9, s60
	v_and_b32_e32 v5, 0xffff0000, v5
	v_and_b32_e32 v4, 0xffff0000, v4
	v_or_b32_sdwa v3, v5, v3 dst_sel:DWORD dst_unused:UNUSED_PAD src0_sel:DWORD src1_sel:WORD_1
	v_or_b32_sdwa v2, v4, v2 dst_sel:DWORD dst_unused:UNUSED_PAD src0_sel:DWORD src1_sel:WORD_1
	global_store_dwordx2 v[6:7], v[2:3], off offset:64
	v_mov_b32_e32 v2, v14
	v_mov_b32_e32 v3, v16
	v_pk_mul_f32 v[2:3], v[2:3], v[0:1] op_sel_hi:[1,0]
	v_mov_b32_e32 v16, v15
	v_pk_mul_f32 v[4:5], v[16:17], v[0:1] op_sel_hi:[1,0]
	v_and_b32_sdwa v0, v3, v236 dst_sel:DWORD dst_unused:UNUSED_PAD src0_sel:WORD_1 src1_sel:DWORD
	v_and_b32_sdwa v8, v2, v236 dst_sel:DWORD dst_unused:UNUSED_PAD src0_sel:WORD_1 src1_sel:DWORD
	v_add3_u32 v2, v2, v8, s60
	v_add3_u32 v0, v3, v0, s60
	v_and_b32_sdwa v3, v5, v236 dst_sel:DWORD dst_unused:UNUSED_PAD src0_sel:WORD_1 src1_sel:DWORD
	v_and_b32_sdwa v8, v4, v236 dst_sel:DWORD dst_unused:UNUSED_PAD src0_sel:WORD_1 src1_sel:DWORD
	v_add3_u32 v3, v5, v3, s60
	v_add3_u32 v4, v4, v8, s60
	v_and_b32_e32 v3, 0xffff0000, v3
	v_and_b32_e32 v4, 0xffff0000, v4
	v_or_b32_sdwa v3, v3, v0 dst_sel:DWORD dst_unused:UNUSED_PAD src0_sel:DWORD src1_sel:WORD_1
	v_or_b32_sdwa v2, v4, v2 dst_sel:DWORD dst_unused:UNUSED_PAD src0_sel:DWORD src1_sel:WORD_1
	global_store_dwordx2 v[6:7], v[2:3], off offset:96
	s_branch .LBB0_1196
